# v19 with the 268 v_mov_b64 in the in-proj GEMM epilogues split into two v_mov_b32 each (64-bit moves issue slower)
# speedup vs baseline: 1.0078x; 1.0078x over previous
; #define PG8_STAGE(bufoff, gbase, voff) do { _Pragma("unroll") for (int _i = 0; _i < 2; ++_i) \
;     __builtin_amdgcn_global_load_lds((const unsigned*)((const char*)(gbase) + (voff)[_i]), (PG8_LAS unsigned*)(lds + (bufoff) + ldsw + _i * 8192), 16, 0, 0); } while (0)
; #define PG8_LDA(dst, b, h) do { _Pragma("unroll") for (int m = 0; m < 4; ++m) _Pragma("unroll") for (int k = 0; k < 2; ++k) dst[m][k] = *(const PG8_LAS bf16x8*)(lds + PG8_SA(b, h) + aoff + m * 2048 + k * 1024); } while (0)
; #define PG8_LDB(dst, b, h) do { _Pragma("unroll") for (int n = 0; n < 2; ++n) _Pragma("unroll") for (int k = 0; k < 2; ++k) dst[n][k] = *(const PG8_LAS bf16x8*)(lds + PG8_SB(b, h) + boff + n * 2048 + k * 1024); } while (0)
; #define PG8_MMA(ai, bj, At, Bt) do { __builtin_amdgcn_s_setprio(1); _Pragma("unroll") for (int m = 0; m < 4; ++m) _Pragma("unroll") for (int n = 0; n < 2; ++n) _Pragma("unroll") for (int k = 0; k < 2; ++k) \
;     acc[ai][bj][m][n] = __builtin_amdgcn_mfma_f32_16x16x32_bf16(Bt[n][k], At[m][k], acc[ai][bj][m][n], 0, 0, 0); __builtin_amdgcn_s_setprio(0); } while (0)
; #define PG8_WAIT_V(n) asm volatile("s_waitcnt vmcnt(" #n ")" ::: "memory")
; template <class Epi>
; DI void gemm_phase(PG8_LAS unsigned char* lds, const Gemm g, const StaticOrder& S, const Epi& E) {
;     ...
;     for (int t = 0; t < nt; t += 2) {
;       const bool last = (t == nt - 2);
;       const char* a1 = cA + (size_t)(t + 1) * kstep;
;       const char* a2 = last ? nA : cA + (size_t)(t + 2) * kstep; const char* b2 = last ? nB : cB + (size_t)(t + 2) * kstep;
;       const char* a3 = a2 + kstep; const char* b3 = b2 + kstep;
;       PG8_LDB(B0, 0, 0); PG8_SCHED; PG8_LDA(At, 0, 0); PG8_STAGE(PG8_SA(1, 1), a1 + hstepA, voffA);
;       PG8_WAIT_L(8); PG8_BAR; PG8_WAIT_L(0); PG8_MMA(0, 0, At, B0); PG8_BAR; PG8_SCHED;
;       PG8_LDB(B1, 0, 1); PG8_STAGE(PG8_SB(0, 0), b2, voffB);
;       PG8_BAR; PG8_WAIT_L(0); PG8_MMA(0, 1, At, B1); PG8_BAR;
;       PG8_LDA(At, 0, 1); PG8_STAGE(PG8_SA(0, 0), a2, voffA);
;       PG8_BAR; PG8_WAIT_L(0); PG8_MMA(1, 0, At, B0); PG8_BAR; PG8_SCHED;
;       PG8_STAGE(PG8_SB(0, 1), b2 + hstepB, voffB);
;       PG8_WAIT_V(6); PG8_BAR; PG8_MMA(1, 1, At, B1); PG8_BAR;
;       PG8_LDB(B0, 1, 0); PG8_SCHED; PG8_LDA(At, 1, 0); PG8_STAGE(PG8_SA(0, 1), a2 + hstepA, voffA);
;       PG8_WAIT_L(8); PG8_BAR; PG8_WAIT_L(0); PG8_MMA(0, 0, At, B0); PG8_BAR; PG8_SCHED;
.LBB0_220:
	s_add_u32 s10, s8, 0xfffc0080
	s_addc_u32 s11, s9, -1
	s_add_i32 s26, 0, 0x10000
	v_add_u32_e32 v162, s26, v160
	ds_read_b128 v[130:133], v162
	ds_read_b128 v[134:137], v162 offset:1024
	ds_read_b128 v[156:159], v162 offset:2048
	ds_read_b128 v[162:165], v162 offset:3072
	s_cmp_eq_u32 s25, 12
	s_cselect_b32 s19, s13, s11
	s_cselect_b32 s18, s21, s10
	s_cselect_b32 s11, s1, s24
	s_cselect_b32 s10, s22, s23
	v_lshl_add_u64 v[198:199], s[8:9], 0, v[152:153]
	s_add_i32 m0, s35, 0xc000
	ds_read_b128 v[166:169], v161
	ds_read_b128 v[170:173], v161 offset:1024
	ds_read_b128 v[174:177], v161 offset:2048
	ds_read_b128 v[178:181], v161 offset:3072
	ds_read_b128 v[182:185], v161 offset:4096
	ds_read_b128 v[186:189], v161 offset:5120
	ds_read_b128 v[190:193], v161 offset:6144
	ds_read_b128 v[194:197], v161 offset:7168
	global_load_lds_dwordx4 v[198:199], off
	v_lshl_add_u64 v[198:199], s[8:9], 0, v[154:155]
	s_add_i32 m0, s35, 0xe000
	s_nop 0
	global_load_lds_dwordx4 v[198:199], off
	s_waitcnt lgkmcnt(8)
	s_barrier
	s_waitcnt lgkmcnt(0)
	s_setprio 1
	s_waitcnt lgkmcnt(0)
	v_mfma_f32_16x16x32_bf16 v[126:129], v[130:133], v[166:169], v[126:129]
	v_mfma_f32_16x16x32_bf16 v[122:125], v[156:159], v[166:169], v[122:125]
	v_mfma_f32_16x16x32_bf16 v[110:113], v[130:133], v[174:177], v[110:113]
	v_mfma_f32_16x16x32_bf16 v[106:109], v[156:159], v[174:177], v[106:109]
	v_mfma_f32_16x16x32_bf16 v[94:97], v[130:133], v[182:185], v[94:97]
	v_mfma_f32_16x16x32_bf16 v[90:93], v[156:159], v[182:185], v[90:93]
	v_mfma_f32_16x16x32_bf16 v[78:81], v[130:133], v[190:193], v[78:81]
	v_mfma_f32_16x16x32_bf16 v[74:77], v[156:159], v[190:193], v[74:77]
	v_mfma_f32_16x16x32_bf16 v[126:129], v[134:137], v[170:173], v[126:129]
	v_mfma_f32_16x16x32_bf16 v[122:125], v[162:165], v[170:173], v[122:125]
	v_mfma_f32_16x16x32_bf16 v[110:113], v[134:137], v[178:181], v[110:113]
	v_mfma_f32_16x16x32_bf16 v[106:109], v[162:165], v[178:181], v[106:109]
	v_mfma_f32_16x16x32_bf16 v[94:97], v[134:137], v[186:189], v[94:97]
	v_mfma_f32_16x16x32_bf16 v[90:93], v[162:165], v[186:189], v[90:93]
	v_mfma_f32_16x16x32_bf16 v[78:81], v[134:137], v[194:197], v[78:81]
	v_mfma_f32_16x16x32_bf16 v[74:77], v[162:165], v[194:197], v[74:77]
	s_setprio 0
	s_barrier
	s_add_i32 s33, 0, 0x14000
	v_add_u32_e32 v206, s33, v160
	s_add_i32 s26, s26, s34
	ds_read_b128 v[198:201], v206
	ds_read_b128 v[202:205], v206 offset:1024
	ds_read_b128 v[226:229], v206 offset:2048
	ds_read_b128 v[230:233], v206 offset:3072
	v_lshl_add_u64 v[206:207], s[10:11], 0, v[0:1]
	s_mov_b32 m0, s26
	v_lshl_add_u64 v[234:235], s[10:11], 0, v[138:139]
	global_load_lds_dwordx4 v[206:207], off
	s_add_i32 m0, s26, 0x2000
	s_nop 0
	global_load_lds_dwordx4 v[234:235], off
	s_barrier
	s_waitcnt lgkmcnt(0)
	s_setprio 1
	s_waitcnt lgkmcnt(0)
	v_mfma_f32_16x16x32_bf16 v[118:121], v[198:201], v[166:169], v[118:121]
	v_mfma_f32_16x16x32_bf16 v[114:117], v[226:229], v[166:169], v[114:117]
	v_mfma_f32_16x16x32_bf16 v[102:105], v[198:201], v[174:177], v[102:105]
	v_mfma_f32_16x16x32_bf16 v[98:101], v[226:229], v[174:177], v[98:101]
	v_mfma_f32_16x16x32_bf16 v[86:89], v[198:201], v[182:185], v[86:89]
	v_mfma_f32_16x16x32_bf16 v[82:85], v[226:229], v[182:185], v[82:85]
	v_mfma_f32_16x16x32_bf16 v[70:73], v[198:201], v[190:193], v[70:73]
	v_mfma_f32_16x16x32_bf16 v[66:69], v[226:229], v[190:193], v[66:69]
	v_mfma_f32_16x16x32_bf16 v[118:121], v[202:205], v[170:173], v[118:121]
	v_mfma_f32_16x16x32_bf16 v[114:117], v[230:233], v[170:173], v[114:117]
	v_mfma_f32_16x16x32_bf16 v[102:105], v[202:205], v[178:181], v[102:105]
	v_mfma_f32_16x16x32_bf16 v[98:101], v[230:233], v[178:181], v[98:101]
	v_mfma_f32_16x16x32_bf16 v[86:89], v[202:205], v[186:189], v[86:89]
	v_mfma_f32_16x16x32_bf16 v[82:85], v[230:233], v[186:189], v[82:85]
	v_mfma_f32_16x16x32_bf16 v[70:73], v[202:205], v[194:197], v[70:73]
	v_mfma_f32_16x16x32_bf16 v[66:69], v[230:233], v[194:197], v[66:69]
	s_setprio 0
	s_mov_b32 m0, s35
	v_lshl_add_u64 v[236:237], s[18:19], 0, v[148:149]
	s_barrier
	ds_read_b128 v[166:169], v161 offset:16384
	ds_read_b128 v[170:173], v161 offset:17408
	ds_read_b128 v[174:177], v161 offset:18432
	ds_read_b128 v[178:181], v161 offset:19456
	ds_read_b128 v[182:185], v161 offset:20480
	ds_read_b128 v[186:189], v161 offset:21504
	ds_read_b128 v[190:193], v161 offset:22528
	ds_read_b128 v[194:197], v161 offset:23552
	global_load_lds_dwordx4 v[236:237], off
	v_lshl_add_u64 v[238:239], s[18:19], 0, v[140:141]
	s_mov_b32 m0, s75
	s_nop 0
	global_load_lds_dwordx4 v[238:239], off
	s_barrier
	s_waitcnt lgkmcnt(0)
	s_setprio 1
	s_waitcnt lgkmcnt(0)
	v_mfma_f32_16x16x32_bf16 v[62:65], v[130:133], v[166:169], v[62:65]
	v_mfma_f32_16x16x32_bf16 v[58:61], v[156:159], v[166:169], v[58:61]
	v_mfma_f32_16x16x32_bf16 v[46:49], v[130:133], v[174:177], v[46:49]
	v_mfma_f32_16x16x32_bf16 v[42:45], v[156:159], v[174:177], v[42:45]
	v_mfma_f32_16x16x32_bf16 v[30:33], v[130:133], v[182:185], v[30:33]
	v_mfma_f32_16x16x32_bf16 v[26:29], v[156:159], v[182:185], v[26:29]
	v_mfma_f32_16x16x32_bf16 v[14:17], v[130:133], v[190:193], v[14:17]
	v_mfma_f32_16x16x32_bf16 v[10:13], v[156:159], v[190:193], v[10:13]
	v_mfma_f32_16x16x32_bf16 v[62:65], v[134:137], v[170:173], v[62:65]
	v_mfma_f32_16x16x32_bf16 v[58:61], v[162:165], v[170:173], v[58:61]
	v_mfma_f32_16x16x32_bf16 v[46:49], v[134:137], v[178:181], v[46:49]
	v_mfma_f32_16x16x32_bf16 v[42:45], v[162:165], v[178:181], v[42:45]
	v_mfma_f32_16x16x32_bf16 v[30:33], v[134:137], v[186:189], v[30:33]
	v_mfma_f32_16x16x32_bf16 v[26:29], v[162:165], v[186:189], v[26:29]
	v_mfma_f32_16x16x32_bf16 v[14:17], v[134:137], v[194:197], v[14:17]
	v_mfma_f32_16x16x32_bf16 v[10:13], v[162:165], v[194:197], v[10:13]
	s_setprio 0
	s_barrier
; #define PG8_STAGE(bufoff, gbase, voff) do { _Pragma("unroll") for (int _i = 0; _i < 2; ++_i) \
;     __builtin_amdgcn_global_load_lds((const unsigned*)((const char*)(gbase) + (voff)[_i]), (PG8_LAS unsigned*)(lds + (bufoff) + ldsw + _i * 8192), 16, 0, 0); } while (0)
; #define PG8_LDA(dst, b, h) do { _Pragma("unroll") for (int m = 0; m < 4; ++m) _Pragma("unroll") for (int k = 0; k < 2; ++k) dst[m][k] = *(const PG8_LAS bf16x8*)(lds + PG8_SA(b, h) + aoff + m * 2048 + k * 1024); } while (0)
; #define PG8_LDB(dst, b, h) do { _Pragma("unroll") for (int n = 0; n < 2; ++n) _Pragma("unroll") for (int k = 0; k < 2; ++k) dst[n][k] = *(const PG8_LAS bf16x8*)(lds + PG8_SB(b, h) + boff + n * 2048 + k * 1024); } while (0)
; #define PG8_MMA(ai, bj, At, Bt) do { __builtin_amdgcn_s_setprio(1); _Pragma("unroll") for (int m = 0; m < 4; ++m) _Pragma("unroll") for (int n = 0; n < 2; ++n) _Pragma("unroll") for (int k = 0; k < 2; ++k) \
;     acc[ai][bj][m][n] = __builtin_amdgcn_mfma_f32_16x16x32_bf16(Bt[n][k], At[m][k], acc[ai][bj][m][n], 0, 0, 0); __builtin_amdgcn_s_setprio(0); } while (0)
; #define PG8_WAIT_V(n) asm volatile("s_waitcnt vmcnt(" #n ")" ::: "memory")
; #define PG8_WAIT_L(n) asm volatile("s_waitcnt lgkmcnt(" #n ")" ::: "memory")
; #define PG8_BAR __builtin_amdgcn_s_barrier()
; #define PG8_SCHED __builtin_amdgcn_sched_barrier(0)
; template <class Epi>
; DI void gemm_phase(PG8_LAS unsigned char* lds, const Gemm g, const StaticOrder& S, const Epi& E) {
;     ...
;       PG8_BAR; PG8_WAIT_L(0); PG8_MMA(1, 0, At, B0); PG8_BAR; PG8_SCHED;
;       PG8_STAGE(PG8_SB(0, 1), b2 + hstepB, voffB);
;       PG8_WAIT_V(6); PG8_BAR; PG8_MMA(1, 1, At, B1); PG8_BAR;
;       PG8_LDB(B0, 1, 0); PG8_SCHED; PG8_LDA(At, 1, 0); PG8_STAGE(PG8_SA(0, 1), a2 + hstepA, voffA);
;       PG8_WAIT_L(8); PG8_BAR; PG8_WAIT_L(0); PG8_MMA(0, 0, At, B0); PG8_BAR; PG8_SCHED;
;       PG8_LDB(B1, 1, 1); PG8_STAGE(PG8_SB(1, 0), b3, voffB);
;       PG8_BAR; PG8_WAIT_L(0); PG8_MMA(0, 1, At, B1); PG8_BAR;
	s_add_u32 s26, s10, 0x40000
	s_addc_u32 s27, s11, 0
	s_add_i32 s33, s33, s34
	v_lshl_add_u64 v[130:131], s[26:27], 0, v[0:1]
	s_mov_b32 m0, s33
	s_nop 0
	global_load_lds_dwordx4 v[130:131], off
	v_lshl_add_u64 v[130:131], s[26:27], 0, v[138:139]
	s_add_i32 m0, s33, 0x2000
	s_nop 0
	global_load_lds_dwordx4 v[130:131], off
	s_waitcnt vmcnt(6)
	s_barrier
	s_setprio 1
	v_mfma_f32_16x16x32_bf16 v[54:57], v[198:201], v[166:169], v[54:57]
	v_mfma_f32_16x16x32_bf16 v[50:53], v[226:229], v[166:169], v[50:53]
	v_mfma_f32_16x16x32_bf16 v[38:41], v[198:201], v[174:177], v[38:41]
	v_mfma_f32_16x16x32_bf16 v[34:37], v[226:229], v[174:177], v[34:37]
	v_mfma_f32_16x16x32_bf16 v[22:25], v[198:201], v[182:185], v[22:25]
	v_mfma_f32_16x16x32_bf16 v[18:21], v[226:229], v[182:185], v[18:21]
	v_mfma_f32_16x16x32_bf16 v[6:9], v[198:201], v[190:193], v[6:9]
	v_mfma_f32_16x16x32_bf16 v[2:5], v[226:229], v[190:193], v[2:5]
	v_mfma_f32_16x16x32_bf16 v[54:57], v[202:205], v[170:173], v[54:57]
	v_mfma_f32_16x16x32_bf16 v[50:53], v[230:233], v[170:173], v[50:53]
	v_mfma_f32_16x16x32_bf16 v[38:41], v[202:205], v[178:181], v[38:41]
	v_mfma_f32_16x16x32_bf16 v[34:37], v[230:233], v[178:181], v[34:37]
	v_mfma_f32_16x16x32_bf16 v[22:25], v[202:205], v[186:189], v[22:25]
	v_mfma_f32_16x16x32_bf16 v[18:21], v[230:233], v[186:189], v[18:21]
	v_mfma_f32_16x16x32_bf16 v[6:9], v[202:205], v[194:197], v[6:9]
	v_mfma_f32_16x16x32_bf16 v[2:5], v[230:233], v[194:197], v[2:5]
	s_setprio 0
	s_add_i32 s26, 0, 0x18000
	v_add_u32_e32 v162, s26, v160
	s_barrier
	ds_read_b128 v[130:133], v162
	ds_read_b128 v[134:137], v162 offset:1024
	ds_read_b128 v[156:159], v162 offset:2048
	ds_read_b128 v[162:165], v162 offset:3072
	s_add_u32 s18, s18, 0x40000
	s_addc_u32 s19, s19, 0
	s_mov_b32 m0, s84
	v_lshl_add_u64 v[198:199], s[18:19], 0, v[148:149]
	ds_read_b128 v[166:169], v161 offset:32768
	ds_read_b128 v[170:173], v161 offset:33792
	ds_read_b128 v[174:177], v161 offset:34816
	ds_read_b128 v[178:181], v161 offset:35840
	ds_read_b128 v[182:185], v161 offset:36864
	ds_read_b128 v[186:189], v161 offset:37888
	ds_read_b128 v[190:193], v161 offset:38912
	ds_read_b128 v[194:197], v161 offset:39936
	global_load_lds_dwordx4 v[198:199], off
	v_lshl_add_u64 v[198:199], s[18:19], 0, v[140:141]
	s_mov_b32 m0, s85
	s_nop 0
	global_load_lds_dwordx4 v[198:199], off
	s_waitcnt lgkmcnt(8)
	s_barrier
	s_waitcnt lgkmcnt(0)
	s_setprio 1
	s_waitcnt lgkmcnt(0)
	v_mfma_f32_16x16x32_bf16 v[126:129], v[130:133], v[166:169], v[126:129]
	v_mfma_f32_16x16x32_bf16 v[122:125], v[156:159], v[166:169], v[122:125]
	v_mfma_f32_16x16x32_bf16 v[110:113], v[130:133], v[174:177], v[110:113]
	v_mfma_f32_16x16x32_bf16 v[106:109], v[156:159], v[174:177], v[106:109]
	v_mfma_f32_16x16x32_bf16 v[94:97], v[130:133], v[182:185], v[94:97]
	v_mfma_f32_16x16x32_bf16 v[90:93], v[156:159], v[182:185], v[90:93]
	v_mfma_f32_16x16x32_bf16 v[78:81], v[130:133], v[190:193], v[78:81]
	v_mfma_f32_16x16x32_bf16 v[74:77], v[156:159], v[190:193], v[74:77]
	v_mfma_f32_16x16x32_bf16 v[126:129], v[134:137], v[170:173], v[126:129]
	v_mfma_f32_16x16x32_bf16 v[122:125], v[162:165], v[170:173], v[122:125]
	v_mfma_f32_16x16x32_bf16 v[110:113], v[134:137], v[178:181], v[110:113]
	v_mfma_f32_16x16x32_bf16 v[106:109], v[162:165], v[178:181], v[106:109]
	v_mfma_f32_16x16x32_bf16 v[94:97], v[134:137], v[186:189], v[94:97]
	v_mfma_f32_16x16x32_bf16 v[90:93], v[162:165], v[186:189], v[90:93]
	v_mfma_f32_16x16x32_bf16 v[78:81], v[134:137], v[194:197], v[78:81]
	v_mfma_f32_16x16x32_bf16 v[74:77], v[162:165], v[194:197], v[74:77]
	s_setprio 0
	s_barrier
	s_add_i32 s18, 0, 0x1c000
	s_add_i32 s19, s26, s34
	v_add_u32_e32 v212, s18, v160
	v_lshl_add_u64 v[206:207], v[206:207], 0, s[82:83]
	s_mov_b32 m0, s19
	ds_read_b128 v[198:201], v212
	ds_read_b128 v[202:205], v212 offset:1024
	ds_read_b128 v[226:229], v212 offset:2048
	ds_read_b128 v[230:233], v212 offset:3072
	global_load_lds_dwordx4 v[206:207], off
	v_lshl_add_u64 v[206:207], v[234:235], 0, s[82:83]
	s_add_i32 m0, s19, 0x2000
	s_nop 0
	global_load_lds_dwordx4 v[206:207], off
	s_barrier
; #define LAS3 __attribute__((address_space(3)))
; template <class Epi>
; DI void gemm_phase(PG8_LAS unsigned char* lds, const Gemm g, const StaticOrder& S, const Epi& E) {
;     ...
;       PG8_BAR; PG8_WAIT_L(0); PG8_MMA(0, 1, At, B1); PG8_BAR;
;       PG8_LDA(At, 1, 1); PG8_STAGE(PG8_SA(1, 0), a3, voffA);
;       PG8_BAR; PG8_WAIT_L(0); PG8_MMA(1, 0, At, B0); PG8_BAR; PG8_SCHED;
;       PG8_STAGE(PG8_SB(1, 1), b3 + hstepB, voffB);
;       PG8_WAIT_V(6); PG8_BAR; PG8_MMA(1, 1, At, B1); PG8_BAR;
;     }
;   DI void operator()(const f32x4 (&acc)[2][2][4][2], const pg8::Unit& un, int wr, int wc, int fr, int fq) const {
;     ...
;           const int c128 = upn * 256 + bj * 128;
;           const int col0 = c128 + wc * 32 + fq * 8;
;           f32x4 v0 = acc[ai][bj][m][0], v1 = acc[ai][bj][m][1];
;           if (MODE == 2) {
;             u32x4 w; w[0] = pk2(v0[0], v0[1]); w[1] = pk2(v0[2], v0[3]); w[2] = pk2(v1[0], v1[1]); w[3] = pk2(v1[2], v1[3]);
;             *(u32x4*)(u + (size_t)row * 1024 + col0) = w;
;           } else {
;             if (isA && !isctx && c128 < kend) {
;               f32x4 p0, p1;
; #pragma unroll
;               for (int e = 0; e < 4; ++e) { p0[e] = __shfl_xor(v0[e], 32); p1[e] = __shfl_xor(v1[e], 32); }
;               const int sp = row & 2047;
;               const int pos = (wc & 1) ? (sp & 63) : (sp >> 6);
;               LAS3 const float* tb = rope + (pos * 16 + 8 * (fq & 1)) * 2;
;               const f32x4 t0 = *(LAS3 const f32x4*)(tb), t1 = *(LAS3 const f32x4*)(tb + 4), t2 = *(LAS3 const f32x4*)(tb + 8), t3 = *(LAS3 const f32x4*)(tb + 12);
;               const float sg = (fq < 2) ? -1.f : 1.f;
;               v0[0] = v0[0] * t0[0] + sg * p0[0] * t0[1]; v0[1] = v0[1] * t0[2] + sg * p0[1] * t0[3];
;               v0[2] = v0[2] * t1[0] + sg * p0[2] * t1[1]; v0[3] = v0[3] * t1[2] + sg * p0[3] * t1[3];
;               v1[0] = v1[0] * t2[0] + sg * p1[0] * t2[1]; v1[1] = v1[1] * t2[2] + sg * p1[1] * t2[3];
;               v1[2] = v1[2] * t3[0] + sg * p1[2] * t3[1]; v1[3] = v1[3] * t3[2] + sg * p1[3] * t3[3];
;             }
;             if (c128 >= vend) {
; #pragma unroll
;               for (int e = 0; e < 4; ++e) { v0[e] = silu_f(v0[e]); v1[e] = silu_f(v1[e]); }
;             } else if (c128 < 1024) {
;               v0 = v0 * (0.125f * 1.4426950408889634f); v1 = v1 * (0.125f * 1.4426950408889634f);
;             }
	s_waitcnt lgkmcnt(0)
	s_setprio 1
	s_waitcnt lgkmcnt(0)
	v_mfma_f32_16x16x32_bf16 v[118:121], v[198:201], v[166:169], v[118:121]
	v_mfma_f32_16x16x32_bf16 v[114:117], v[226:229], v[166:169], v[114:117]
	v_mfma_f32_16x16x32_bf16 v[102:105], v[198:201], v[174:177], v[102:105]
	v_mfma_f32_16x16x32_bf16 v[98:101], v[226:229], v[174:177], v[98:101]
	v_mfma_f32_16x16x32_bf16 v[86:89], v[198:201], v[182:185], v[86:89]
	v_mfma_f32_16x16x32_bf16 v[82:85], v[226:229], v[182:185], v[82:85]
	v_mfma_f32_16x16x32_bf16 v[70:73], v[198:201], v[190:193], v[70:73]
	v_mfma_f32_16x16x32_bf16 v[66:69], v[226:229], v[190:193], v[66:69]
	v_mfma_f32_16x16x32_bf16 v[118:121], v[202:205], v[170:173], v[118:121]
	v_mfma_f32_16x16x32_bf16 v[114:117], v[230:233], v[170:173], v[114:117]
	v_mfma_f32_16x16x32_bf16 v[102:105], v[202:205], v[178:181], v[102:105]
	v_mfma_f32_16x16x32_bf16 v[98:101], v[230:233], v[178:181], v[98:101]
	v_mfma_f32_16x16x32_bf16 v[86:89], v[202:205], v[186:189], v[86:89]
	v_mfma_f32_16x16x32_bf16 v[82:85], v[230:233], v[186:189], v[82:85]
	v_mfma_f32_16x16x32_bf16 v[70:73], v[202:205], v[194:197], v[70:73]
	v_mfma_f32_16x16x32_bf16 v[66:69], v[230:233], v[194:197], v[66:69]
	s_setprio 0
	s_mov_b32 m0, s86
	v_lshl_add_u64 v[206:207], v[236:237], 0, s[82:83]
	s_barrier
	ds_read_b128 v[166:169], v161 offset:49152
	ds_read_b128 v[170:173], v161 offset:50176
	ds_read_b128 v[174:177], v161 offset:51200
	ds_read_b128 v[178:181], v161 offset:52224
	ds_read_b128 v[182:185], v161 offset:53248
	ds_read_b128 v[186:189], v161 offset:54272
	ds_read_b128 v[190:193], v161 offset:55296
	ds_read_b128 v[194:197], v161 offset:56320
	global_load_lds_dwordx4 v[206:207], off
	v_lshl_add_u64 v[206:207], v[238:239], 0, s[82:83]
	s_mov_b32 m0, s87
	s_nop 0
	global_load_lds_dwordx4 v[206:207], off
	s_barrier
	s_waitcnt lgkmcnt(0)
	s_setprio 1
	s_waitcnt lgkmcnt(0)
	v_mfma_f32_16x16x32_bf16 v[62:65], v[130:133], v[166:169], v[62:65]
	v_mfma_f32_16x16x32_bf16 v[58:61], v[156:159], v[166:169], v[58:61]
	v_mfma_f32_16x16x32_bf16 v[46:49], v[130:133], v[174:177], v[46:49]
	v_mfma_f32_16x16x32_bf16 v[42:45], v[156:159], v[174:177], v[42:45]
	v_mfma_f32_16x16x32_bf16 v[30:33], v[130:133], v[182:185], v[30:33]
	v_mfma_f32_16x16x32_bf16 v[26:29], v[156:159], v[182:185], v[26:29]
	v_mfma_f32_16x16x32_bf16 v[14:17], v[130:133], v[190:193], v[14:17]
	v_mfma_f32_16x16x32_bf16 v[10:13], v[156:159], v[190:193], v[10:13]
	v_mfma_f32_16x16x32_bf16 v[62:65], v[134:137], v[170:173], v[62:65]
	v_mfma_f32_16x16x32_bf16 v[58:61], v[162:165], v[170:173], v[58:61]
	v_mfma_f32_16x16x32_bf16 v[46:49], v[134:137], v[178:181], v[46:49]
	v_mfma_f32_16x16x32_bf16 v[42:45], v[162:165], v[178:181], v[42:45]
	v_mfma_f32_16x16x32_bf16 v[30:33], v[134:137], v[186:189], v[30:33]
	v_mfma_f32_16x16x32_bf16 v[26:29], v[162:165], v[186:189], v[26:29]
	v_mfma_f32_16x16x32_bf16 v[14:17], v[134:137], v[194:197], v[14:17]
	v_mfma_f32_16x16x32_bf16 v[10:13], v[162:165], v[194:197], v[10:13]
	s_setprio 0
	s_barrier
	s_add_u32 s10, s10, 0x40080
	s_addc_u32 s11, s11, 0
	s_add_i32 s18, s18, s34
	v_lshl_add_u64 v[130:131], s[10:11], 0, v[0:1]
	s_mov_b32 m0, s18
	s_nop 0
	global_load_lds_dwordx4 v[130:131], off
	v_lshl_add_u64 v[130:131], s[10:11], 0, v[138:139]
	s_add_i32 m0, s18, 0x2000
	s_nop 0
	global_load_lds_dwordx4 v[130:131], off
	s_waitcnt vmcnt(6)
	s_barrier
	s_setprio 1
	v_mfma_f32_16x16x32_bf16 v[54:57], v[198:201], v[166:169], v[54:57]
	v_mfma_f32_16x16x32_bf16 v[50:53], v[226:229], v[166:169], v[50:53]
	v_mfma_f32_16x16x32_bf16 v[38:41], v[198:201], v[174:177], v[38:41]
	v_mfma_f32_16x16x32_bf16 v[34:37], v[226:229], v[174:177], v[34:37]
	v_mfma_f32_16x16x32_bf16 v[22:25], v[198:201], v[182:185], v[22:25]
	v_mfma_f32_16x16x32_bf16 v[18:21], v[226:229], v[182:185], v[18:21]
	v_mfma_f32_16x16x32_bf16 v[6:9], v[198:201], v[190:193], v[6:9]
	v_mfma_f32_16x16x32_bf16 v[2:5], v[226:229], v[190:193], v[2:5]
	v_mfma_f32_16x16x32_bf16 v[54:57], v[202:205], v[170:173], v[54:57]
	v_mfma_f32_16x16x32_bf16 v[50:53], v[230:233], v[170:173], v[50:53]
	v_mfma_f32_16x16x32_bf16 v[38:41], v[202:205], v[178:181], v[38:41]
	v_mfma_f32_16x16x32_bf16 v[34:37], v[230:233], v[178:181], v[34:37]
	v_mfma_f32_16x16x32_bf16 v[22:25], v[202:205], v[186:189], v[22:25]
	v_mfma_f32_16x16x32_bf16 v[18:21], v[230:233], v[186:189], v[18:21]
	v_mfma_f32_16x16x32_bf16 v[6:9], v[202:205], v[194:197], v[6:9]
	v_mfma_f32_16x16x32_bf16 v[2:5], v[230:233], v[194:197], v[2:5]
	s_setprio 0
	s_add_i32 s25, s25, 2
	s_add_u32 s8, s8, 0x100
	s_addc_u32 s9, s9, 0
	s_add_u32 s23, s23, 0x100
	s_addc_u32 s24, s24, 0
	s_cmp_gt_u32 s25, 13
	s_barrier
	s_cbranch_scc0 .LBB0_220
	s_cmp_lt_i32 s89, 12
	s_cselect_b64 s[10:11], -1, 0
	s_mov_b64 s[8:9], -1
	s_and_b64 vcc, exec, s[10:11]
	s_cbranch_vccz .LBB0_225
	v_mov_b32_e32 v136, v124
	v_mov_b32_e32 v137, v125
	v_mov_b32_e32 v132, v128
	v_mov_b32_e32 v133, v129
	s_cmp_gt_i32 s89, 3
	v_mov_b32_e32 v134, v122
	v_mov_b32_e32 v135, v123
	v_mov_b32_e32 v130, v126
	v_mov_b32_e32 v131, v127
	s_cbranch_scc1 .LBB0_224
	v_pk_mul_f32 v[132:133], v[128:129], s[94:95] op_sel_hi:[1,0]
	v_pk_mul_f32 v[130:131], v[126:127], s[94:95] op_sel_hi:[1,0]
	v_pk_mul_f32 v[136:137], v[124:125], s[94:95] op_sel_hi:[1,0]
	v_pk_mul_f32 v[134:135], v[122:123], s[94:95] op_sel_hi:[1,0]

; #define LAS3 __attribute__((address_space(3)))
; DI unsigned pk2(float lo, float hi) { f32x2 v = {lo, hi}; return __builtin_bit_cast(unsigned, __builtin_convertvector(v, bf16x2v)); }
; DI float silu_f(float x) { return x * __builtin_amdgcn_rcpf(1.f + __expf(-x)); }
;   DI void operator()(const f32x4 (&acc)[2][2][4][2], const pg8::Unit& un, int wr, int wc, int fr, int fq) const {
;     ...
;           const int c128 = upn * 256 + bj * 128;
;           const int col0 = c128 + wc * 32 + fq * 8;
;           f32x4 v0 = acc[ai][bj][m][0], v1 = acc[ai][bj][m][1];
;           if (MODE == 2) {
;             u32x4 w; w[0] = pk2(v0[0], v0[1]); w[1] = pk2(v0[2], v0[3]); w[2] = pk2(v1[0], v1[1]); w[3] = pk2(v1[2], v1[3]);
;             *(u32x4*)(u + (size_t)row * 1024 + col0) = w;
;           } else {
;             if (isA && !isctx && c128 < kend) {
;               f32x4 p0, p1;
; #pragma unroll
;               for (int e = 0; e < 4; ++e) { p0[e] = __shfl_xor(v0[e], 32); p1[e] = __shfl_xor(v1[e], 32); }
;               const int sp = row & 2047;
;               const int pos = (wc & 1) ? (sp & 63) : (sp >> 6);
;               LAS3 const float* tb = rope + (pos * 16 + 8 * (fq & 1)) * 2;
;               const f32x4 t0 = *(LAS3 const f32x4*)(tb), t1 = *(LAS3 const f32x4*)(tb + 4), t2 = *(LAS3 const f32x4*)(tb + 8), t3 = *(LAS3 const f32x4*)(tb + 12);
;               const float sg = (fq < 2) ? -1.f : 1.f;
;               v0[0] = v0[0] * t0[0] + sg * p0[0] * t0[1]; v0[1] = v0[1] * t0[2] + sg * p0[1] * t0[3];
;               v0[2] = v0[2] * t1[0] + sg * p0[2] * t1[1]; v0[3] = v0[3] * t1[2] + sg * p0[3] * t1[3];
;               v1[0] = v1[0] * t2[0] + sg * p1[0] * t2[1]; v1[1] = v1[1] * t2[2] + sg * p1[1] * t2[3];
;               v1[2] = v1[2] * t3[0] + sg * p1[2] * t3[1]; v1[3] = v1[3] * t3[2] + sg * p1[3] * t3[3];
;             }
;             if (c128 >= vend) {
; #pragma unroll
;               for (int e = 0; e < 4; ++e) { v0[e] = silu_f(v0[e]); v1[e] = silu_f(v1[e]); }
;             } else if (c128 < 1024) {
;               v0 = v0 * (0.125f * 1.4426950408889634f); v1 = v1 * (0.125f * 1.4426950408889634f);
;             }
;             u32x4 w; w[0] = pk2(v0[0], v0[1]); w[1] = pk2(v0[2], v0[3]); w[2] = pk2(v1[0], v1[1]); w[3] = pk2(v1[2], v1[3]);
;             *(u32x4*)(qkvg + (size_t)row * NW + col0) = w;
.LBB0_227:
	v_lshl_add_u32 v158, s20, 8, v142
	s_lshl_b32 s8, s89, 8
	v_ashrrev_i32_e32 v159, 31, v158
	v_lshlrev_b64 v[126:127], 13, v[158:159]
	v_or_b32_e32 v156, s8, v150
	s_or_b32 s1, s8, 0x80
	v_cvt_pk_bf16_f32 v122, v130, v131
	v_lshl_add_u64 v[130:131], s[38:39], 0, v[126:127]
	v_ashrrev_i32_e32 v157, 31, v156
	s_cmpk_lt_i32 s1, 0xc00
	v_cvt_pk_bf16_f32 v123, v132, v133
	v_cvt_pk_bf16_f32 v124, v134, v135
	v_cvt_pk_bf16_f32 v125, v136, v137
	v_lshl_add_u64 v[126:127], v[156:157], 1, v[130:131]
	s_cselect_b64 s[18:19], -1, 0
	s_cmpk_gt_i32 s1, 0xbff
	s_mov_b64 s[70:71], -1
	global_store_dwordx4 v[126:127], v[122:125], off
	s_cbranch_scc1 .LBB0_231
	v_mov_b32_e32 v128, v116
	v_mov_b32_e32 v129, v117
	v_mov_b32_e32 v124, v120
	v_mov_b32_e32 v125, v121
	s_cmpk_gt_i32 s1, 0x3ff
	v_mov_b32_e32 v126, v114
	v_mov_b32_e32 v127, v115
	v_mov_b32_e32 v122, v118
	v_mov_b32_e32 v123, v119
	s_cbranch_scc1 .LBB0_230
	v_pk_mul_f32 v[124:125], v[120:121], s[94:95] op_sel_hi:[1,0]
	v_pk_mul_f32 v[122:123], v[118:119], s[94:95] op_sel_hi:[1,0]
	v_pk_mul_f32 v[128:129], v[116:117], s[94:95] op_sel_hi:[1,0]
	v_pk_mul_f32 v[126:127], v[114:115], s[94:95] op_sel_hi:[1,0]

; #define LAS3 __attribute__((address_space(3)))
; DI unsigned pk2(float lo, float hi) { f32x2 v = {lo, hi}; return __builtin_bit_cast(unsigned, __builtin_convertvector(v, bf16x2v)); }
; DI float silu_f(float x) { return x * __builtin_amdgcn_rcpf(1.f + __expf(-x)); }
;   DI void operator()(const f32x4 (&acc)[2][2][4][2], const pg8::Unit& un, int wr, int wc, int fr, int fq) const {
;     ...
;           const int c128 = upn * 256 + bj * 128;
;           const int col0 = c128 + wc * 32 + fq * 8;
;           f32x4 v0 = acc[ai][bj][m][0], v1 = acc[ai][bj][m][1];
;           if (MODE == 2) {
;             u32x4 w; w[0] = pk2(v0[0], v0[1]); w[1] = pk2(v0[2], v0[3]); w[2] = pk2(v1[0], v1[1]); w[3] = pk2(v1[2], v1[3]);
;             *(u32x4*)(u + (size_t)row * 1024 + col0) = w;
;           } else {
;             if (isA && !isctx && c128 < kend) {
;               f32x4 p0, p1;
; #pragma unroll
;               for (int e = 0; e < 4; ++e) { p0[e] = __shfl_xor(v0[e], 32); p1[e] = __shfl_xor(v1[e], 32); }
;               const int sp = row & 2047;
;               const int pos = (wc & 1) ? (sp & 63) : (sp >> 6);
;               LAS3 const float* tb = rope + (pos * 16 + 8 * (fq & 1)) * 2;
;               const f32x4 t0 = *(LAS3 const f32x4*)(tb), t1 = *(LAS3 const f32x4*)(tb + 4), t2 = *(LAS3 const f32x4*)(tb + 8), t3 = *(LAS3 const f32x4*)(tb + 12);
;               const float sg = (fq < 2) ? -1.f : 1.f;
;               v0[0] = v0[0] * t0[0] + sg * p0[0] * t0[1]; v0[1] = v0[1] * t0[2] + sg * p0[1] * t0[3];
;               v0[2] = v0[2] * t1[0] + sg * p0[2] * t1[1]; v0[3] = v0[3] * t1[2] + sg * p0[3] * t1[3];
;               v1[0] = v1[0] * t2[0] + sg * p1[0] * t2[1]; v1[1] = v1[1] * t2[2] + sg * p1[1] * t2[3];
;               v1[2] = v1[2] * t3[0] + sg * p1[2] * t3[1]; v1[3] = v1[3] * t3[2] + sg * p1[3] * t3[3];
;             }
;             if (c128 >= vend) {
; #pragma unroll
;               for (int e = 0; e < 4; ++e) { v0[e] = silu_f(v0[e]); v1[e] = silu_f(v1[e]); }
;             } else if (c128 < 1024) {
;               v0 = v0 * (0.125f * 1.4426950408889634f); v1 = v1 * (0.125f * 1.4426950408889634f);
;             }
;             u32x4 w; w[0] = pk2(v0[0], v0[1]); w[1] = pk2(v0[2], v0[3]); w[2] = pk2(v1[0], v1[1]); w[3] = pk2(v1[2], v1[3]);
;             *(u32x4*)(qkvg + (size_t)row * NW + col0) = w;
.LBB0_233:
	s_ashr_i32 s9, s8, 31
	v_cvt_pk_bf16_f32 v114, v122, v123
	v_lshl_add_u64 v[122:123], s[8:9], 0, v[150:151]
	v_cvt_pk_bf16_f32 v115, v124, v125
	v_cvt_pk_bf16_f32 v116, v126, v127
	v_cvt_pk_bf16_f32 v117, v128, v129
	v_lshl_add_u64 v[118:119], v[122:123], 1, v[130:131]
	global_store_dwordx4 v[118:119], v[114:117], off offset:256
	s_andn2_b64 vcc, exec, s[10:11]
	s_nop 0
	v_cndmask_b32_e64 v114, 0, 1, s[10:11]
	v_cmp_ne_u32_e64 s[8:9], 1, v114
	s_mov_b64 s[10:11], -1
	s_cbranch_vccnz .LBB0_237
	v_mov_b32_e32 v120, v108
	v_mov_b32_e32 v121, v109
	v_mov_b32_e32 v116, v112
	v_mov_b32_e32 v117, v113
	s_cmp_gt_i32 s89, 3
	v_mov_b32_e32 v118, v106
	v_mov_b32_e32 v119, v107
	v_mov_b32_e32 v114, v110
	v_mov_b32_e32 v115, v111
	s_cbranch_scc1 .LBB0_236
	v_pk_mul_f32 v[116:117], v[112:113], s[94:95] op_sel_hi:[1,0]
	v_pk_mul_f32 v[114:115], v[110:111], s[94:95] op_sel_hi:[1,0]
	v_pk_mul_f32 v[120:121], v[108:109], s[94:95] op_sel_hi:[1,0]
	v_pk_mul_f32 v[118:119], v[106:107], s[94:95] op_sel_hi:[1,0]

; #define LAS3 __attribute__((address_space(3)))
; DI unsigned pk2(float lo, float hi) { f32x2 v = {lo, hi}; return __builtin_bit_cast(unsigned, __builtin_convertvector(v, bf16x2v)); }
; DI float silu_f(float x) { return x * __builtin_amdgcn_rcpf(1.f + __expf(-x)); }
;   DI void operator()(const f32x4 (&acc)[2][2][4][2], const pg8::Unit& un, int wr, int wc, int fr, int fq) const {
;     ...
;           const int c128 = upn * 256 + bj * 128;
;           const int col0 = c128 + wc * 32 + fq * 8;
;           f32x4 v0 = acc[ai][bj][m][0], v1 = acc[ai][bj][m][1];
;           if (MODE == 2) {
;             u32x4 w; w[0] = pk2(v0[0], v0[1]); w[1] = pk2(v0[2], v0[3]); w[2] = pk2(v1[0], v1[1]); w[3] = pk2(v1[2], v1[3]);
;             *(u32x4*)(u + (size_t)row * 1024 + col0) = w;
;           } else {
;             if (isA && !isctx && c128 < kend) {
;               f32x4 p0, p1;
; #pragma unroll
;               for (int e = 0; e < 4; ++e) { p0[e] = __shfl_xor(v0[e], 32); p1[e] = __shfl_xor(v1[e], 32); }
;               const int sp = row & 2047;
;               const int pos = (wc & 1) ? (sp & 63) : (sp >> 6);
;               LAS3 const float* tb = rope + (pos * 16 + 8 * (fq & 1)) * 2;
;               const f32x4 t0 = *(LAS3 const f32x4*)(tb), t1 = *(LAS3 const f32x4*)(tb + 4), t2 = *(LAS3 const f32x4*)(tb + 8), t3 = *(LAS3 const f32x4*)(tb + 12);
;               const float sg = (fq < 2) ? -1.f : 1.f;
;               v0[0] = v0[0] * t0[0] + sg * p0[0] * t0[1]; v0[1] = v0[1] * t0[2] + sg * p0[1] * t0[3];
;               v0[2] = v0[2] * t1[0] + sg * p0[2] * t1[1]; v0[3] = v0[3] * t1[2] + sg * p0[3] * t1[3];
;               v1[0] = v1[0] * t2[0] + sg * p1[0] * t2[1]; v1[1] = v1[1] * t2[2] + sg * p1[1] * t2[3];
;               v1[2] = v1[2] * t3[0] + sg * p1[2] * t3[1]; v1[3] = v1[3] * t3[2] + sg * p1[3] * t3[3];
;             }
;             if (c128 >= vend) {
; #pragma unroll
;               for (int e = 0; e < 4; ++e) { v0[e] = silu_f(v0[e]); v1[e] = silu_f(v1[e]); }
;             } else if (c128 < 1024) {
;               v0 = v0 * (0.125f * 1.4426950408889634f); v1 = v1 * (0.125f * 1.4426950408889634f);
;             }
;             u32x4 w; w[0] = pk2(v0[0], v0[1]); w[1] = pk2(v0[2], v0[3]); w[2] = pk2(v1[0], v1[1]); w[3] = pk2(v1[2], v1[3]);
;             *(u32x4*)(qkvg + (size_t)row * NW + col0) = w;
.LBB0_239:
	v_or_b32_e32 v106, 16, v158
	v_ashrrev_i32_e32 v107, 31, v106
	v_lshlrev_b64 v[110:111], 13, v[106:107]
	v_cvt_pk_bf16_f32 v106, v114, v115
	v_lshl_add_u64 v[114:115], s[38:39], 0, v[110:111]
	v_cvt_pk_bf16_f32 v107, v116, v117
	v_cvt_pk_bf16_f32 v108, v118, v119
	v_cvt_pk_bf16_f32 v109, v120, v121
	v_lshl_add_u64 v[110:111], v[156:157], 1, v[114:115]
	global_store_dwordx4 v[110:111], v[106:109], off
	s_andn2_b64 vcc, exec, s[18:19]
	s_nop 0
	v_cndmask_b32_e64 v106, 0, 1, s[18:19]
	v_cmp_ne_u32_e64 s[10:11], 1, v106
	s_mov_b64 s[18:19], -1
	s_cbranch_vccnz .LBB0_243
	v_mov_b32_e32 v112, v100
	v_mov_b32_e32 v113, v101
	v_mov_b32_e32 v108, v104
	v_mov_b32_e32 v109, v105
	s_cmpk_gt_i32 s1, 0x3ff
	v_mov_b32_e32 v110, v98
	v_mov_b32_e32 v111, v99
	v_mov_b32_e32 v106, v102
	v_mov_b32_e32 v107, v103
	s_cbranch_scc1 .LBB0_242
	v_pk_mul_f32 v[108:109], v[104:105], s[94:95] op_sel_hi:[1,0]
	v_pk_mul_f32 v[106:107], v[102:103], s[94:95] op_sel_hi:[1,0]
	v_pk_mul_f32 v[112:113], v[100:101], s[94:95] op_sel_hi:[1,0]
	v_pk_mul_f32 v[110:111], v[98:99], s[94:95] op_sel_hi:[1,0]

; #define LAS3 __attribute__((address_space(3)))
; DI unsigned pk2(float lo, float hi) { f32x2 v = {lo, hi}; return __builtin_bit_cast(unsigned, __builtin_convertvector(v, bf16x2v)); }
; DI float silu_f(float x) { return x * __builtin_amdgcn_rcpf(1.f + __expf(-x)); }
;   DI void operator()(const f32x4 (&acc)[2][2][4][2], const pg8::Unit& un, int wr, int wc, int fr, int fq) const {
;     ...
;           const int c128 = upn * 256 + bj * 128;
;           const int col0 = c128 + wc * 32 + fq * 8;
;           f32x4 v0 = acc[ai][bj][m][0], v1 = acc[ai][bj][m][1];
;           if (MODE == 2) {
;             u32x4 w; w[0] = pk2(v0[0], v0[1]); w[1] = pk2(v0[2], v0[3]); w[2] = pk2(v1[0], v1[1]); w[3] = pk2(v1[2], v1[3]);
;             *(u32x4*)(u + (size_t)row * 1024 + col0) = w;
;           } else {
;             if (isA && !isctx && c128 < kend) {
;               f32x4 p0, p1;
; #pragma unroll
;               for (int e = 0; e < 4; ++e) { p0[e] = __shfl_xor(v0[e], 32); p1[e] = __shfl_xor(v1[e], 32); }
;               const int sp = row & 2047;
;               const int pos = (wc & 1) ? (sp & 63) : (sp >> 6);
;               LAS3 const float* tb = rope + (pos * 16 + 8 * (fq & 1)) * 2;
;               const f32x4 t0 = *(LAS3 const f32x4*)(tb), t1 = *(LAS3 const f32x4*)(tb + 4), t2 = *(LAS3 const f32x4*)(tb + 8), t3 = *(LAS3 const f32x4*)(tb + 12);
;               const float sg = (fq < 2) ? -1.f : 1.f;
;               v0[0] = v0[0] * t0[0] + sg * p0[0] * t0[1]; v0[1] = v0[1] * t0[2] + sg * p0[1] * t0[3];
;               v0[2] = v0[2] * t1[0] + sg * p0[2] * t1[1]; v0[3] = v0[3] * t1[2] + sg * p0[3] * t1[3];
;               v1[0] = v1[0] * t2[0] + sg * p1[0] * t2[1]; v1[1] = v1[1] * t2[2] + sg * p1[1] * t2[3];
;               v1[2] = v1[2] * t3[0] + sg * p1[2] * t3[1]; v1[3] = v1[3] * t3[2] + sg * p1[3] * t3[3];
;             }
;             if (c128 >= vend) {
; #pragma unroll
;               for (int e = 0; e < 4; ++e) { v0[e] = silu_f(v0[e]); v1[e] = silu_f(v1[e]); }
;             } else if (c128 < 1024) {
;               v0 = v0 * (0.125f * 1.4426950408889634f); v1 = v1 * (0.125f * 1.4426950408889634f);
;             }
;             u32x4 w; w[0] = pk2(v0[0], v0[1]); w[1] = pk2(v0[2], v0[3]); w[2] = pk2(v1[0], v1[1]); w[3] = pk2(v1[2], v1[3]);
;             *(u32x4*)(qkvg + (size_t)row * NW + col0) = w;
.LBB0_245:
	v_cvt_pk_bf16_f32 v98, v106, v107
	v_cvt_pk_bf16_f32 v99, v108, v109
	v_cvt_pk_bf16_f32 v100, v110, v111
	v_cvt_pk_bf16_f32 v101, v112, v113
	v_lshl_add_u64 v[102:103], v[122:123], 1, v[114:115]
	s_and_b64 vcc, exec, s[8:9]
	s_mov_b64 s[18:19], -1
	global_store_dwordx4 v[102:103], v[98:101], off offset:256
	s_cbranch_vccnz .LBB0_249
	v_mov_b32_e32 v104, v92
	v_mov_b32_e32 v105, v93
	v_mov_b32_e32 v100, v96
	v_mov_b32_e32 v101, v97
	s_cmp_gt_i32 s89, 3
	v_mov_b32_e32 v102, v90
	v_mov_b32_e32 v103, v91
	v_mov_b32_e32 v98, v94
	v_mov_b32_e32 v99, v95
	s_cbranch_scc1 .LBB0_248
	v_pk_mul_f32 v[100:101], v[96:97], s[94:95] op_sel_hi:[1,0]
	v_pk_mul_f32 v[98:99], v[94:95], s[94:95] op_sel_hi:[1,0]
	v_pk_mul_f32 v[104:105], v[92:93], s[94:95] op_sel_hi:[1,0]
	v_pk_mul_f32 v[102:103], v[90:91], s[94:95] op_sel_hi:[1,0]

; #define LAS3 __attribute__((address_space(3)))
; DI unsigned pk2(float lo, float hi) { f32x2 v = {lo, hi}; return __builtin_bit_cast(unsigned, __builtin_convertvector(v, bf16x2v)); }
; DI float silu_f(float x) { return x * __builtin_amdgcn_rcpf(1.f + __expf(-x)); }
;   DI void operator()(const f32x4 (&acc)[2][2][4][2], const pg8::Unit& un, int wr, int wc, int fr, int fq) const {
;     ...
;           const int c128 = upn * 256 + bj * 128;
;           const int col0 = c128 + wc * 32 + fq * 8;
;           f32x4 v0 = acc[ai][bj][m][0], v1 = acc[ai][bj][m][1];
;           if (MODE == 2) {
;             u32x4 w; w[0] = pk2(v0[0], v0[1]); w[1] = pk2(v0[2], v0[3]); w[2] = pk2(v1[0], v1[1]); w[3] = pk2(v1[2], v1[3]);
;             *(u32x4*)(u + (size_t)row * 1024 + col0) = w;
;           } else {
;             if (isA && !isctx && c128 < kend) {
;               f32x4 p0, p1;
; #pragma unroll
;               for (int e = 0; e < 4; ++e) { p0[e] = __shfl_xor(v0[e], 32); p1[e] = __shfl_xor(v1[e], 32); }
;               const int sp = row & 2047;
;               const int pos = (wc & 1) ? (sp & 63) : (sp >> 6);
;               LAS3 const float* tb = rope + (pos * 16 + 8 * (fq & 1)) * 2;
;               const f32x4 t0 = *(LAS3 const f32x4*)(tb), t1 = *(LAS3 const f32x4*)(tb + 4), t2 = *(LAS3 const f32x4*)(tb + 8), t3 = *(LAS3 const f32x4*)(tb + 12);
;               const float sg = (fq < 2) ? -1.f : 1.f;
;               v0[0] = v0[0] * t0[0] + sg * p0[0] * t0[1]; v0[1] = v0[1] * t0[2] + sg * p0[1] * t0[3];
;               v0[2] = v0[2] * t1[0] + sg * p0[2] * t1[1]; v0[3] = v0[3] * t1[2] + sg * p0[3] * t1[3];
;               v1[0] = v1[0] * t2[0] + sg * p1[0] * t2[1]; v1[1] = v1[1] * t2[2] + sg * p1[1] * t2[3];
;               v1[2] = v1[2] * t3[0] + sg * p1[2] * t3[1]; v1[3] = v1[3] * t3[2] + sg * p1[3] * t3[3];
;             }
;             if (c128 >= vend) {
; #pragma unroll
;               for (int e = 0; e < 4; ++e) { v0[e] = silu_f(v0[e]); v1[e] = silu_f(v1[e]); }
;             } else if (c128 < 1024) {
;               v0 = v0 * (0.125f * 1.4426950408889634f); v1 = v1 * (0.125f * 1.4426950408889634f);
;             }
;             u32x4 w; w[0] = pk2(v0[0], v0[1]); w[1] = pk2(v0[2], v0[3]); w[2] = pk2(v1[0], v1[1]); w[3] = pk2(v1[2], v1[3]);
;             *(u32x4*)(qkvg + (size_t)row * NW + col0) = w;
.LBB0_251:
	v_or_b32_e32 v90, 32, v158
	v_ashrrev_i32_e32 v91, 31, v90
	v_lshlrev_b64 v[94:95], 13, v[90:91]
	v_cvt_pk_bf16_f32 v90, v98, v99
	v_lshl_add_u64 v[98:99], s[38:39], 0, v[94:95]
	v_cvt_pk_bf16_f32 v91, v100, v101
	v_cvt_pk_bf16_f32 v92, v102, v103
	v_cvt_pk_bf16_f32 v93, v104, v105
	v_lshl_add_u64 v[94:95], v[156:157], 1, v[98:99]
	s_and_b64 vcc, exec, s[10:11]
	s_mov_b64 s[18:19], -1
	global_store_dwordx4 v[94:95], v[90:93], off
	s_cbranch_vccnz .LBB0_255
	v_mov_b32_e32 v96, v84
	v_mov_b32_e32 v97, v85
	v_mov_b32_e32 v92, v88
	v_mov_b32_e32 v93, v89
	s_cmpk_gt_i32 s1, 0x3ff
	v_mov_b32_e32 v94, v82
	v_mov_b32_e32 v95, v83
	v_mov_b32_e32 v90, v86
	v_mov_b32_e32 v91, v87
	s_cbranch_scc1 .LBB0_254
	v_pk_mul_f32 v[92:93], v[88:89], s[94:95] op_sel_hi:[1,0]
	v_pk_mul_f32 v[90:91], v[86:87], s[94:95] op_sel_hi:[1,0]
	v_pk_mul_f32 v[96:97], v[84:85], s[94:95] op_sel_hi:[1,0]
	v_pk_mul_f32 v[94:95], v[82:83], s[94:95] op_sel_hi:[1,0]

; #define LAS3 __attribute__((address_space(3)))
; DI unsigned pk2(float lo, float hi) { f32x2 v = {lo, hi}; return __builtin_bit_cast(unsigned, __builtin_convertvector(v, bf16x2v)); }
; DI float silu_f(float x) { return x * __builtin_amdgcn_rcpf(1.f + __expf(-x)); }
;   DI void operator()(const f32x4 (&acc)[2][2][4][2], const pg8::Unit& un, int wr, int wc, int fr, int fq) const {
;     ...
;           const int c128 = upn * 256 + bj * 128;
;           const int col0 = c128 + wc * 32 + fq * 8;
;           f32x4 v0 = acc[ai][bj][m][0], v1 = acc[ai][bj][m][1];
;           if (MODE == 2) {
;             u32x4 w; w[0] = pk2(v0[0], v0[1]); w[1] = pk2(v0[2], v0[3]); w[2] = pk2(v1[0], v1[1]); w[3] = pk2(v1[2], v1[3]);
;             *(u32x4*)(u + (size_t)row * 1024 + col0) = w;
;           } else {
;             if (isA && !isctx && c128 < kend) {
;               f32x4 p0, p1;
; #pragma unroll
;               for (int e = 0; e < 4; ++e) { p0[e] = __shfl_xor(v0[e], 32); p1[e] = __shfl_xor(v1[e], 32); }
;               const int sp = row & 2047;
;               const int pos = (wc & 1) ? (sp & 63) : (sp >> 6);
;               LAS3 const float* tb = rope + (pos * 16 + 8 * (fq & 1)) * 2;
;               const f32x4 t0 = *(LAS3 const f32x4*)(tb), t1 = *(LAS3 const f32x4*)(tb + 4), t2 = *(LAS3 const f32x4*)(tb + 8), t3 = *(LAS3 const f32x4*)(tb + 12);
;               const float sg = (fq < 2) ? -1.f : 1.f;
;               v0[0] = v0[0] * t0[0] + sg * p0[0] * t0[1]; v0[1] = v0[1] * t0[2] + sg * p0[1] * t0[3];
;               v0[2] = v0[2] * t1[0] + sg * p0[2] * t1[1]; v0[3] = v0[3] * t1[2] + sg * p0[3] * t1[3];
;               v1[0] = v1[0] * t2[0] + sg * p1[0] * t2[1]; v1[1] = v1[1] * t2[2] + sg * p1[1] * t2[3];
;               v1[2] = v1[2] * t3[0] + sg * p1[2] * t3[1]; v1[3] = v1[3] * t3[2] + sg * p1[3] * t3[3];
;             }
;             if (c128 >= vend) {
; #pragma unroll
;               for (int e = 0; e < 4; ++e) { v0[e] = silu_f(v0[e]); v1[e] = silu_f(v1[e]); }
;             } else if (c128 < 1024) {
;               v0 = v0 * (0.125f * 1.4426950408889634f); v1 = v1 * (0.125f * 1.4426950408889634f);
;             }
;             u32x4 w; w[0] = pk2(v0[0], v0[1]); w[1] = pk2(v0[2], v0[3]); w[2] = pk2(v1[0], v1[1]); w[3] = pk2(v1[2], v1[3]);
;             *(u32x4*)(qkvg + (size_t)row * NW + col0) = w;
.LBB0_257:
	v_cvt_pk_bf16_f32 v82, v90, v91
	v_cvt_pk_bf16_f32 v83, v92, v93
	v_cvt_pk_bf16_f32 v84, v94, v95
	v_cvt_pk_bf16_f32 v85, v96, v97
	v_lshl_add_u64 v[86:87], v[122:123], 1, v[98:99]
	s_and_b64 vcc, exec, s[8:9]
	s_mov_b64 s[18:19], -1
	global_store_dwordx4 v[86:87], v[82:85], off offset:256
	s_cbranch_vccnz .LBB0_261
	v_mov_b32_e32 v88, v76
	v_mov_b32_e32 v89, v77
	v_mov_b32_e32 v84, v80
	v_mov_b32_e32 v85, v81
	s_cmp_gt_i32 s89, 3
	v_mov_b32_e32 v86, v74
	v_mov_b32_e32 v87, v75
	v_mov_b32_e32 v82, v78
	v_mov_b32_e32 v83, v79
	s_cbranch_scc1 .LBB0_260
	v_pk_mul_f32 v[84:85], v[80:81], s[94:95] op_sel_hi:[1,0]
	v_pk_mul_f32 v[82:83], v[78:79], s[94:95] op_sel_hi:[1,0]
	v_pk_mul_f32 v[88:89], v[76:77], s[94:95] op_sel_hi:[1,0]
	v_pk_mul_f32 v[86:87], v[74:75], s[94:95] op_sel_hi:[1,0]

; #define LAS3 __attribute__((address_space(3)))
; DI unsigned pk2(float lo, float hi) { f32x2 v = {lo, hi}; return __builtin_bit_cast(unsigned, __builtin_convertvector(v, bf16x2v)); }
; DI float silu_f(float x) { return x * __builtin_amdgcn_rcpf(1.f + __expf(-x)); }
;   DI void operator()(const f32x4 (&acc)[2][2][4][2], const pg8::Unit& un, int wr, int wc, int fr, int fq) const {
;     ...
;           const int c128 = upn * 256 + bj * 128;
;           const int col0 = c128 + wc * 32 + fq * 8;
;           f32x4 v0 = acc[ai][bj][m][0], v1 = acc[ai][bj][m][1];
;           if (MODE == 2) {
;             u32x4 w; w[0] = pk2(v0[0], v0[1]); w[1] = pk2(v0[2], v0[3]); w[2] = pk2(v1[0], v1[1]); w[3] = pk2(v1[2], v1[3]);
;             *(u32x4*)(u + (size_t)row * 1024 + col0) = w;
;           } else {
;             if (isA && !isctx && c128 < kend) {
;               f32x4 p0, p1;
; #pragma unroll
;               for (int e = 0; e < 4; ++e) { p0[e] = __shfl_xor(v0[e], 32); p1[e] = __shfl_xor(v1[e], 32); }
;               const int sp = row & 2047;
;               const int pos = (wc & 1) ? (sp & 63) : (sp >> 6);
;               LAS3 const float* tb = rope + (pos * 16 + 8 * (fq & 1)) * 2;
;               const f32x4 t0 = *(LAS3 const f32x4*)(tb), t1 = *(LAS3 const f32x4*)(tb + 4), t2 = *(LAS3 const f32x4*)(tb + 8), t3 = *(LAS3 const f32x4*)(tb + 12);
;               const float sg = (fq < 2) ? -1.f : 1.f;
;               v0[0] = v0[0] * t0[0] + sg * p0[0] * t0[1]; v0[1] = v0[1] * t0[2] + sg * p0[1] * t0[3];
;               v0[2] = v0[2] * t1[0] + sg * p0[2] * t1[1]; v0[3] = v0[3] * t1[2] + sg * p0[3] * t1[3];
;               v1[0] = v1[0] * t2[0] + sg * p1[0] * t2[1]; v1[1] = v1[1] * t2[2] + sg * p1[1] * t2[3];
;               v1[2] = v1[2] * t3[0] + sg * p1[2] * t3[1]; v1[3] = v1[3] * t3[2] + sg * p1[3] * t3[3];
;             }
;             if (c128 >= vend) {
; #pragma unroll
;               for (int e = 0; e < 4; ++e) { v0[e] = silu_f(v0[e]); v1[e] = silu_f(v1[e]); }
;             } else if (c128 < 1024) {
;               v0 = v0 * (0.125f * 1.4426950408889634f); v1 = v1 * (0.125f * 1.4426950408889634f);
;             }
;             u32x4 w; w[0] = pk2(v0[0], v0[1]); w[1] = pk2(v0[2], v0[3]); w[2] = pk2(v1[0], v1[1]); w[3] = pk2(v1[2], v1[3]);
;             *(u32x4*)(qkvg + (size_t)row * NW + col0) = w;
.LBB0_263:
	v_or_b32_e32 v74, 48, v158
	v_ashrrev_i32_e32 v75, 31, v74
	v_lshlrev_b64 v[78:79], 13, v[74:75]
	v_cvt_pk_bf16_f32 v74, v82, v83
	v_lshl_add_u64 v[82:83], s[38:39], 0, v[78:79]
	v_cvt_pk_bf16_f32 v75, v84, v85
	v_cvt_pk_bf16_f32 v76, v86, v87
	v_cvt_pk_bf16_f32 v77, v88, v89
	v_lshl_add_u64 v[78:79], v[156:157], 1, v[82:83]
	s_and_b64 vcc, exec, s[10:11]
	s_mov_b64 s[18:19], -1
	global_store_dwordx4 v[78:79], v[74:77], off
	s_cbranch_vccnz .LBB0_267
	v_mov_b32_e32 v80, v68
	v_mov_b32_e32 v81, v69
	v_mov_b32_e32 v76, v72
	v_mov_b32_e32 v77, v73
	s_cmpk_gt_i32 s1, 0x3ff
	v_mov_b32_e32 v78, v66
	v_mov_b32_e32 v79, v67
	v_mov_b32_e32 v74, v70
	v_mov_b32_e32 v75, v71
	s_cbranch_scc1 .LBB0_266
	v_pk_mul_f32 v[76:77], v[72:73], s[94:95] op_sel_hi:[1,0]
	v_pk_mul_f32 v[74:75], v[70:71], s[94:95] op_sel_hi:[1,0]
	v_pk_mul_f32 v[80:81], v[68:69], s[94:95] op_sel_hi:[1,0]
	v_pk_mul_f32 v[78:79], v[66:67], s[94:95] op_sel_hi:[1,0]

; #define LAS3 __attribute__((address_space(3)))
; DI unsigned pk2(float lo, float hi) { f32x2 v = {lo, hi}; return __builtin_bit_cast(unsigned, __builtin_convertvector(v, bf16x2v)); }
; DI float silu_f(float x) { return x * __builtin_amdgcn_rcpf(1.f + __expf(-x)); }
;   DI void operator()(const f32x4 (&acc)[2][2][4][2], const pg8::Unit& un, int wr, int wc, int fr, int fq) const {
;     ...
;           const int c128 = upn * 256 + bj * 128;
;           const int col0 = c128 + wc * 32 + fq * 8;
;           f32x4 v0 = acc[ai][bj][m][0], v1 = acc[ai][bj][m][1];
;           if (MODE == 2) {
;             u32x4 w; w[0] = pk2(v0[0], v0[1]); w[1] = pk2(v0[2], v0[3]); w[2] = pk2(v1[0], v1[1]); w[3] = pk2(v1[2], v1[3]);
;             *(u32x4*)(u + (size_t)row * 1024 + col0) = w;
;           } else {
;             if (isA && !isctx && c128 < kend) {
;               f32x4 p0, p1;
; #pragma unroll
;               for (int e = 0; e < 4; ++e) { p0[e] = __shfl_xor(v0[e], 32); p1[e] = __shfl_xor(v1[e], 32); }
;               const int sp = row & 2047;
;               const int pos = (wc & 1) ? (sp & 63) : (sp >> 6);
;               LAS3 const float* tb = rope + (pos * 16 + 8 * (fq & 1)) * 2;
;               const f32x4 t0 = *(LAS3 const f32x4*)(tb), t1 = *(LAS3 const f32x4*)(tb + 4), t2 = *(LAS3 const f32x4*)(tb + 8), t3 = *(LAS3 const f32x4*)(tb + 12);
;               const float sg = (fq < 2) ? -1.f : 1.f;
;               v0[0] = v0[0] * t0[0] + sg * p0[0] * t0[1]; v0[1] = v0[1] * t0[2] + sg * p0[1] * t0[3];
;               v0[2] = v0[2] * t1[0] + sg * p0[2] * t1[1]; v0[3] = v0[3] * t1[2] + sg * p0[3] * t1[3];
;               v1[0] = v1[0] * t2[0] + sg * p1[0] * t2[1]; v1[1] = v1[1] * t2[2] + sg * p1[1] * t2[3];
;               v1[2] = v1[2] * t3[0] + sg * p1[2] * t3[1]; v1[3] = v1[3] * t3[2] + sg * p1[3] * t3[3];
;             }
;             if (c128 >= vend) {
; #pragma unroll
;               for (int e = 0; e < 4; ++e) { v0[e] = silu_f(v0[e]); v1[e] = silu_f(v1[e]); }
;             } else if (c128 < 1024) {
;               v0 = v0 * (0.125f * 1.4426950408889634f); v1 = v1 * (0.125f * 1.4426950408889634f);
;             }
;             u32x4 w; w[0] = pk2(v0[0], v0[1]); w[1] = pk2(v0[2], v0[3]); w[2] = pk2(v1[0], v1[1]); w[3] = pk2(v1[2], v1[3]);
;             *(u32x4*)(qkvg + (size_t)row * NW + col0) = w;
.LBB0_269:
	v_cvt_pk_bf16_f32 v66, v74, v75
	v_cvt_pk_bf16_f32 v67, v76, v77
	v_cvt_pk_bf16_f32 v68, v78, v79
	v_cvt_pk_bf16_f32 v69, v80, v81
	v_lshl_add_u64 v[70:71], v[122:123], 1, v[82:83]
	s_and_b64 vcc, exec, s[8:9]
	s_mov_b64 s[18:19], -1
	global_store_dwordx4 v[70:71], v[66:69], off offset:256
	s_cbranch_vccnz .LBB0_273
	v_mov_b32_e32 v72, v60
	v_mov_b32_e32 v73, v61
	v_mov_b32_e32 v68, v64
	v_mov_b32_e32 v69, v65
	s_cmp_gt_i32 s89, 3
	v_mov_b32_e32 v70, v58
	v_mov_b32_e32 v71, v59
	v_mov_b32_e32 v66, v62
	v_mov_b32_e32 v67, v63
	s_cbranch_scc1 .LBB0_272
	v_pk_mul_f32 v[68:69], v[64:65], s[94:95] op_sel_hi:[1,0]
	v_pk_mul_f32 v[66:67], v[62:63], s[94:95] op_sel_hi:[1,0]
	v_pk_mul_f32 v[72:73], v[60:61], s[94:95] op_sel_hi:[1,0]
	v_pk_mul_f32 v[70:71], v[58:59], s[94:95] op_sel_hi:[1,0]

; #define LAS3 __attribute__((address_space(3)))
; DI unsigned pk2(float lo, float hi) { f32x2 v = {lo, hi}; return __builtin_bit_cast(unsigned, __builtin_convertvector(v, bf16x2v)); }
; DI float silu_f(float x) { return x * __builtin_amdgcn_rcpf(1.f + __expf(-x)); }
;   DI void operator()(const f32x4 (&acc)[2][2][4][2], const pg8::Unit& un, int wr, int wc, int fr, int fq) const {
;     ...
;           const int c128 = upn * 256 + bj * 128;
;           const int col0 = c128 + wc * 32 + fq * 8;
;           f32x4 v0 = acc[ai][bj][m][0], v1 = acc[ai][bj][m][1];
;           if (MODE == 2) {
;             u32x4 w; w[0] = pk2(v0[0], v0[1]); w[1] = pk2(v0[2], v0[3]); w[2] = pk2(v1[0], v1[1]); w[3] = pk2(v1[2], v1[3]);
;             *(u32x4*)(u + (size_t)row * 1024 + col0) = w;
;           } else {
;             if (isA && !isctx && c128 < kend) {
;               f32x4 p0, p1;
; #pragma unroll
;               for (int e = 0; e < 4; ++e) { p0[e] = __shfl_xor(v0[e], 32); p1[e] = __shfl_xor(v1[e], 32); }
;               const int sp = row & 2047;
;               const int pos = (wc & 1) ? (sp & 63) : (sp >> 6);
;               LAS3 const float* tb = rope + (pos * 16 + 8 * (fq & 1)) * 2;
;               const f32x4 t0 = *(LAS3 const f32x4*)(tb), t1 = *(LAS3 const f32x4*)(tb + 4), t2 = *(LAS3 const f32x4*)(tb + 8), t3 = *(LAS3 const f32x4*)(tb + 12);
;               const float sg = (fq < 2) ? -1.f : 1.f;
;               v0[0] = v0[0] * t0[0] + sg * p0[0] * t0[1]; v0[1] = v0[1] * t0[2] + sg * p0[1] * t0[3];
;               v0[2] = v0[2] * t1[0] + sg * p0[2] * t1[1]; v0[3] = v0[3] * t1[2] + sg * p0[3] * t1[3];
;               v1[0] = v1[0] * t2[0] + sg * p1[0] * t2[1]; v1[1] = v1[1] * t2[2] + sg * p1[1] * t2[3];
;               v1[2] = v1[2] * t3[0] + sg * p1[2] * t3[1]; v1[3] = v1[3] * t3[2] + sg * p1[3] * t3[3];
;             }
;             if (c128 >= vend) {
; #pragma unroll
;               for (int e = 0; e < 4; ++e) { v0[e] = silu_f(v0[e]); v1[e] = silu_f(v1[e]); }
;             } else if (c128 < 1024) {
;               v0 = v0 * (0.125f * 1.4426950408889634f); v1 = v1 * (0.125f * 1.4426950408889634f);
;             }
;             u32x4 w; w[0] = pk2(v0[0], v0[1]); w[1] = pk2(v0[2], v0[3]); w[2] = pk2(v1[0], v1[1]); w[3] = pk2(v1[2], v1[3]);
;             *(u32x4*)(qkvg + (size_t)row * NW + col0) = w;
.LBB0_275:
	v_add_u32_e32 v58, 0x80, v158
	v_ashrrev_i32_e32 v59, 31, v58
	v_lshlrev_b64 v[62:63], 13, v[58:59]
	v_cvt_pk_bf16_f32 v58, v66, v67
	v_lshl_add_u64 v[66:67], s[38:39], 0, v[62:63]
	v_cvt_pk_bf16_f32 v59, v68, v69
	v_cvt_pk_bf16_f32 v60, v70, v71
	v_cvt_pk_bf16_f32 v61, v72, v73
	v_lshl_add_u64 v[62:63], v[156:157], 1, v[66:67]
	s_and_b64 vcc, exec, s[10:11]
	s_mov_b64 s[18:19], -1
	global_store_dwordx4 v[62:63], v[58:61], off
	s_cbranch_vccnz .LBB0_279
	v_mov_b32_e32 v64, v52
	v_mov_b32_e32 v65, v53
	v_mov_b32_e32 v60, v56
	v_mov_b32_e32 v61, v57
	s_cmpk_gt_i32 s1, 0x3ff
	v_mov_b32_e32 v62, v50
	v_mov_b32_e32 v63, v51
	v_mov_b32_e32 v58, v54
	v_mov_b32_e32 v59, v55
	s_cbranch_scc1 .LBB0_278
	v_pk_mul_f32 v[60:61], v[56:57], s[94:95] op_sel_hi:[1,0]
	v_pk_mul_f32 v[58:59], v[54:55], s[94:95] op_sel_hi:[1,0]
	v_pk_mul_f32 v[64:65], v[52:53], s[94:95] op_sel_hi:[1,0]
	v_pk_mul_f32 v[62:63], v[50:51], s[94:95] op_sel_hi:[1,0]

; #define LAS3 __attribute__((address_space(3)))
; DI unsigned pk2(float lo, float hi) { f32x2 v = {lo, hi}; return __builtin_bit_cast(unsigned, __builtin_convertvector(v, bf16x2v)); }
; DI float silu_f(float x) { return x * __builtin_amdgcn_rcpf(1.f + __expf(-x)); }
;   DI void operator()(const f32x4 (&acc)[2][2][4][2], const pg8::Unit& un, int wr, int wc, int fr, int fq) const {
;     ...
;           const int c128 = upn * 256 + bj * 128;
;           const int col0 = c128 + wc * 32 + fq * 8;
;           f32x4 v0 = acc[ai][bj][m][0], v1 = acc[ai][bj][m][1];
;           if (MODE == 2) {
;             u32x4 w; w[0] = pk2(v0[0], v0[1]); w[1] = pk2(v0[2], v0[3]); w[2] = pk2(v1[0], v1[1]); w[3] = pk2(v1[2], v1[3]);
;             *(u32x4*)(u + (size_t)row * 1024 + col0) = w;
;           } else {
;             if (isA && !isctx && c128 < kend) {
;               f32x4 p0, p1;
; #pragma unroll
;               for (int e = 0; e < 4; ++e) { p0[e] = __shfl_xor(v0[e], 32); p1[e] = __shfl_xor(v1[e], 32); }
;               const int sp = row & 2047;
;               const int pos = (wc & 1) ? (sp & 63) : (sp >> 6);
;               LAS3 const float* tb = rope + (pos * 16 + 8 * (fq & 1)) * 2;
;               const f32x4 t0 = *(LAS3 const f32x4*)(tb), t1 = *(LAS3 const f32x4*)(tb + 4), t2 = *(LAS3 const f32x4*)(tb + 8), t3 = *(LAS3 const f32x4*)(tb + 12);
;               const float sg = (fq < 2) ? -1.f : 1.f;
;               v0[0] = v0[0] * t0[0] + sg * p0[0] * t0[1]; v0[1] = v0[1] * t0[2] + sg * p0[1] * t0[3];
;               v0[2] = v0[2] * t1[0] + sg * p0[2] * t1[1]; v0[3] = v0[3] * t1[2] + sg * p0[3] * t1[3];
;               v1[0] = v1[0] * t2[0] + sg * p1[0] * t2[1]; v1[1] = v1[1] * t2[2] + sg * p1[1] * t2[3];
;               v1[2] = v1[2] * t3[0] + sg * p1[2] * t3[1]; v1[3] = v1[3] * t3[2] + sg * p1[3] * t3[3];
;             }
;             if (c128 >= vend) {
; #pragma unroll
;               for (int e = 0; e < 4; ++e) { v0[e] = silu_f(v0[e]); v1[e] = silu_f(v1[e]); }
;             } else if (c128 < 1024) {
;               v0 = v0 * (0.125f * 1.4426950408889634f); v1 = v1 * (0.125f * 1.4426950408889634f);
;             }
;             u32x4 w; w[0] = pk2(v0[0], v0[1]); w[1] = pk2(v0[2], v0[3]); w[2] = pk2(v1[0], v1[1]); w[3] = pk2(v1[2], v1[3]);
;             *(u32x4*)(qkvg + (size_t)row * NW + col0) = w;
.LBB0_281:
	v_cvt_pk_bf16_f32 v50, v58, v59
	v_cvt_pk_bf16_f32 v51, v60, v61
	v_cvt_pk_bf16_f32 v52, v62, v63
	v_cvt_pk_bf16_f32 v53, v64, v65
	v_lshl_add_u64 v[54:55], v[122:123], 1, v[66:67]
	s_and_b64 vcc, exec, s[8:9]
	s_mov_b64 s[18:19], -1
	global_store_dwordx4 v[54:55], v[50:53], off offset:256
	s_cbranch_vccnz .LBB0_285
	v_mov_b32_e32 v56, v44
	v_mov_b32_e32 v57, v45
	v_mov_b32_e32 v52, v48
	v_mov_b32_e32 v53, v49
	s_cmp_gt_i32 s89, 3
	v_mov_b32_e32 v54, v42
	v_mov_b32_e32 v55, v43
	v_mov_b32_e32 v50, v46
	v_mov_b32_e32 v51, v47
	s_cbranch_scc1 .LBB0_284
	v_pk_mul_f32 v[52:53], v[48:49], s[94:95] op_sel_hi:[1,0]
	v_pk_mul_f32 v[50:51], v[46:47], s[94:95] op_sel_hi:[1,0]
	v_pk_mul_f32 v[56:57], v[44:45], s[94:95] op_sel_hi:[1,0]
	v_pk_mul_f32 v[54:55], v[42:43], s[94:95] op_sel_hi:[1,0]

; #define LAS3 __attribute__((address_space(3)))
; DI unsigned pk2(float lo, float hi) { f32x2 v = {lo, hi}; return __builtin_bit_cast(unsigned, __builtin_convertvector(v, bf16x2v)); }
; DI float silu_f(float x) { return x * __builtin_amdgcn_rcpf(1.f + __expf(-x)); }
;   DI void operator()(const f32x4 (&acc)[2][2][4][2], const pg8::Unit& un, int wr, int wc, int fr, int fq) const {
;     ...
;           const int c128 = upn * 256 + bj * 128;
;           const int col0 = c128 + wc * 32 + fq * 8;
;           f32x4 v0 = acc[ai][bj][m][0], v1 = acc[ai][bj][m][1];
;           if (MODE == 2) {
;             u32x4 w; w[0] = pk2(v0[0], v0[1]); w[1] = pk2(v0[2], v0[3]); w[2] = pk2(v1[0], v1[1]); w[3] = pk2(v1[2], v1[3]);
;             *(u32x4*)(u + (size_t)row * 1024 + col0) = w;
;           } else {
;             if (isA && !isctx && c128 < kend) {
;               f32x4 p0, p1;
; #pragma unroll
;               for (int e = 0; e < 4; ++e) { p0[e] = __shfl_xor(v0[e], 32); p1[e] = __shfl_xor(v1[e], 32); }
;               const int sp = row & 2047;
;               const int pos = (wc & 1) ? (sp & 63) : (sp >> 6);
;               LAS3 const float* tb = rope + (pos * 16 + 8 * (fq & 1)) * 2;
;               const f32x4 t0 = *(LAS3 const f32x4*)(tb), t1 = *(LAS3 const f32x4*)(tb + 4), t2 = *(LAS3 const f32x4*)(tb + 8), t3 = *(LAS3 const f32x4*)(tb + 12);
;               const float sg = (fq < 2) ? -1.f : 1.f;
;               v0[0] = v0[0] * t0[0] + sg * p0[0] * t0[1]; v0[1] = v0[1] * t0[2] + sg * p0[1] * t0[3];
;               v0[2] = v0[2] * t1[0] + sg * p0[2] * t1[1]; v0[3] = v0[3] * t1[2] + sg * p0[3] * t1[3];
;               v1[0] = v1[0] * t2[0] + sg * p1[0] * t2[1]; v1[1] = v1[1] * t2[2] + sg * p1[1] * t2[3];
;               v1[2] = v1[2] * t3[0] + sg * p1[2] * t3[1]; v1[3] = v1[3] * t3[2] + sg * p1[3] * t3[3];
;             }
;             if (c128 >= vend) {
; #pragma unroll
;               for (int e = 0; e < 4; ++e) { v0[e] = silu_f(v0[e]); v1[e] = silu_f(v1[e]); }
;             } else if (c128 < 1024) {
;               v0 = v0 * (0.125f * 1.4426950408889634f); v1 = v1 * (0.125f * 1.4426950408889634f);
;             }
;             u32x4 w; w[0] = pk2(v0[0], v0[1]); w[1] = pk2(v0[2], v0[3]); w[2] = pk2(v1[0], v1[1]); w[3] = pk2(v1[2], v1[3]);
;             *(u32x4*)(qkvg + (size_t)row * NW + col0) = w;
.LBB0_287:
	v_add_u32_e32 v42, 0x90, v158
	v_ashrrev_i32_e32 v43, 31, v42
	v_lshlrev_b64 v[46:47], 13, v[42:43]
	v_cvt_pk_bf16_f32 v42, v50, v51
	v_lshl_add_u64 v[50:51], s[38:39], 0, v[46:47]
	v_cvt_pk_bf16_f32 v43, v52, v53
	v_cvt_pk_bf16_f32 v44, v54, v55
	v_cvt_pk_bf16_f32 v45, v56, v57
	v_lshl_add_u64 v[46:47], v[156:157], 1, v[50:51]
	s_and_b64 vcc, exec, s[10:11]
	s_mov_b64 s[18:19], -1
	global_store_dwordx4 v[46:47], v[42:45], off
	s_cbranch_vccnz .LBB0_291
	v_mov_b32_e32 v48, v36
	v_mov_b32_e32 v49, v37
	v_mov_b32_e32 v44, v40
	v_mov_b32_e32 v45, v41
	s_cmpk_gt_i32 s1, 0x3ff
	v_mov_b32_e32 v46, v34
	v_mov_b32_e32 v47, v35
	v_mov_b32_e32 v42, v38
	v_mov_b32_e32 v43, v39
	s_cbranch_scc1 .LBB0_290
	v_pk_mul_f32 v[44:45], v[40:41], s[94:95] op_sel_hi:[1,0]
	v_pk_mul_f32 v[42:43], v[38:39], s[94:95] op_sel_hi:[1,0]
	v_pk_mul_f32 v[48:49], v[36:37], s[94:95] op_sel_hi:[1,0]
	v_pk_mul_f32 v[46:47], v[34:35], s[94:95] op_sel_hi:[1,0]

; #define LAS3 __attribute__((address_space(3)))
; DI unsigned pk2(float lo, float hi) { f32x2 v = {lo, hi}; return __builtin_bit_cast(unsigned, __builtin_convertvector(v, bf16x2v)); }
; DI float silu_f(float x) { return x * __builtin_amdgcn_rcpf(1.f + __expf(-x)); }
;   DI void operator()(const f32x4 (&acc)[2][2][4][2], const pg8::Unit& un, int wr, int wc, int fr, int fq) const {
;     ...
;           const int c128 = upn * 256 + bj * 128;
;           const int col0 = c128 + wc * 32 + fq * 8;
;           f32x4 v0 = acc[ai][bj][m][0], v1 = acc[ai][bj][m][1];
;           if (MODE == 2) {
;             u32x4 w; w[0] = pk2(v0[0], v0[1]); w[1] = pk2(v0[2], v0[3]); w[2] = pk2(v1[0], v1[1]); w[3] = pk2(v1[2], v1[3]);
;             *(u32x4*)(u + (size_t)row * 1024 + col0) = w;
;           } else {
;             if (isA && !isctx && c128 < kend) {
;               f32x4 p0, p1;
; #pragma unroll
;               for (int e = 0; e < 4; ++e) { p0[e] = __shfl_xor(v0[e], 32); p1[e] = __shfl_xor(v1[e], 32); }
;               const int sp = row & 2047;
;               const int pos = (wc & 1) ? (sp & 63) : (sp >> 6);
;               LAS3 const float* tb = rope + (pos * 16 + 8 * (fq & 1)) * 2;
;               const f32x4 t0 = *(LAS3 const f32x4*)(tb), t1 = *(LAS3 const f32x4*)(tb + 4), t2 = *(LAS3 const f32x4*)(tb + 8), t3 = *(LAS3 const f32x4*)(tb + 12);
;               const float sg = (fq < 2) ? -1.f : 1.f;
;               v0[0] = v0[0] * t0[0] + sg * p0[0] * t0[1]; v0[1] = v0[1] * t0[2] + sg * p0[1] * t0[3];
;               v0[2] = v0[2] * t1[0] + sg * p0[2] * t1[1]; v0[3] = v0[3] * t1[2] + sg * p0[3] * t1[3];
;               v1[0] = v1[0] * t2[0] + sg * p1[0] * t2[1]; v1[1] = v1[1] * t2[2] + sg * p1[1] * t2[3];
;               v1[2] = v1[2] * t3[0] + sg * p1[2] * t3[1]; v1[3] = v1[3] * t3[2] + sg * p1[3] * t3[3];
;             }
;             if (c128 >= vend) {
; #pragma unroll
;               for (int e = 0; e < 4; ++e) { v0[e] = silu_f(v0[e]); v1[e] = silu_f(v1[e]); }
;             } else if (c128 < 1024) {
;               v0 = v0 * (0.125f * 1.4426950408889634f); v1 = v1 * (0.125f * 1.4426950408889634f);
;             }
;             u32x4 w; w[0] = pk2(v0[0], v0[1]); w[1] = pk2(v0[2], v0[3]); w[2] = pk2(v1[0], v1[1]); w[3] = pk2(v1[2], v1[3]);
;             *(u32x4*)(qkvg + (size_t)row * NW + col0) = w;
.LBB0_293:
	v_cvt_pk_bf16_f32 v34, v42, v43
	v_cvt_pk_bf16_f32 v35, v44, v45
	v_cvt_pk_bf16_f32 v36, v46, v47
	v_cvt_pk_bf16_f32 v37, v48, v49
	v_lshl_add_u64 v[38:39], v[122:123], 1, v[50:51]
	s_and_b64 vcc, exec, s[8:9]
	s_mov_b64 s[18:19], -1
	global_store_dwordx4 v[38:39], v[34:37], off offset:256
	s_cbranch_vccnz .LBB0_297
	v_mov_b32_e32 v40, v28
	v_mov_b32_e32 v41, v29
	v_mov_b32_e32 v36, v32
	v_mov_b32_e32 v37, v33
	s_cmp_gt_i32 s89, 3
	v_mov_b32_e32 v38, v26
	v_mov_b32_e32 v39, v27
	v_mov_b32_e32 v34, v30
	v_mov_b32_e32 v35, v31
	s_cbranch_scc1 .LBB0_296
	v_pk_mul_f32 v[36:37], v[32:33], s[94:95] op_sel_hi:[1,0]
	v_pk_mul_f32 v[34:35], v[30:31], s[94:95] op_sel_hi:[1,0]
	v_pk_mul_f32 v[40:41], v[28:29], s[94:95] op_sel_hi:[1,0]
	v_pk_mul_f32 v[38:39], v[26:27], s[94:95] op_sel_hi:[1,0]

; #define LAS3 __attribute__((address_space(3)))
; DI unsigned pk2(float lo, float hi) { f32x2 v = {lo, hi}; return __builtin_bit_cast(unsigned, __builtin_convertvector(v, bf16x2v)); }
; DI float silu_f(float x) { return x * __builtin_amdgcn_rcpf(1.f + __expf(-x)); }
;   DI void operator()(const f32x4 (&acc)[2][2][4][2], const pg8::Unit& un, int wr, int wc, int fr, int fq) const {
;     ...
;           const int c128 = upn * 256 + bj * 128;
;           const int col0 = c128 + wc * 32 + fq * 8;
;           f32x4 v0 = acc[ai][bj][m][0], v1 = acc[ai][bj][m][1];
;           if (MODE == 2) {
;             u32x4 w; w[0] = pk2(v0[0], v0[1]); w[1] = pk2(v0[2], v0[3]); w[2] = pk2(v1[0], v1[1]); w[3] = pk2(v1[2], v1[3]);
;             *(u32x4*)(u + (size_t)row * 1024 + col0) = w;
;           } else {
;             if (isA && !isctx && c128 < kend) {
;               f32x4 p0, p1;
; #pragma unroll
;               for (int e = 0; e < 4; ++e) { p0[e] = __shfl_xor(v0[e], 32); p1[e] = __shfl_xor(v1[e], 32); }
;               const int sp = row & 2047;
;               const int pos = (wc & 1) ? (sp & 63) : (sp >> 6);
;               LAS3 const float* tb = rope + (pos * 16 + 8 * (fq & 1)) * 2;
;               const f32x4 t0 = *(LAS3 const f32x4*)(tb), t1 = *(LAS3 const f32x4*)(tb + 4), t2 = *(LAS3 const f32x4*)(tb + 8), t3 = *(LAS3 const f32x4*)(tb + 12);
;               const float sg = (fq < 2) ? -1.f : 1.f;
;               v0[0] = v0[0] * t0[0] + sg * p0[0] * t0[1]; v0[1] = v0[1] * t0[2] + sg * p0[1] * t0[3];
;               v0[2] = v0[2] * t1[0] + sg * p0[2] * t1[1]; v0[3] = v0[3] * t1[2] + sg * p0[3] * t1[3];
;               v1[0] = v1[0] * t2[0] + sg * p1[0] * t2[1]; v1[1] = v1[1] * t2[2] + sg * p1[1] * t2[3];
;               v1[2] = v1[2] * t3[0] + sg * p1[2] * t3[1]; v1[3] = v1[3] * t3[2] + sg * p1[3] * t3[3];
;             }
;             if (c128 >= vend) {
; #pragma unroll
;               for (int e = 0; e < 4; ++e) { v0[e] = silu_f(v0[e]); v1[e] = silu_f(v1[e]); }
;             } else if (c128 < 1024) {
;               v0 = v0 * (0.125f * 1.4426950408889634f); v1 = v1 * (0.125f * 1.4426950408889634f);
;             }
;             u32x4 w; w[0] = pk2(v0[0], v0[1]); w[1] = pk2(v0[2], v0[3]); w[2] = pk2(v1[0], v1[1]); w[3] = pk2(v1[2], v1[3]);
;             *(u32x4*)(qkvg + (size_t)row * NW + col0) = w;
.LBB0_299:
	v_add_u32_e32 v26, 0xa0, v158
	v_ashrrev_i32_e32 v27, 31, v26
	v_lshlrev_b64 v[30:31], 13, v[26:27]
	v_cvt_pk_bf16_f32 v26, v34, v35
	v_lshl_add_u64 v[34:35], s[38:39], 0, v[30:31]
	v_cvt_pk_bf16_f32 v27, v36, v37
	v_cvt_pk_bf16_f32 v28, v38, v39
	v_cvt_pk_bf16_f32 v29, v40, v41
	v_lshl_add_u64 v[30:31], v[156:157], 1, v[34:35]
	s_and_b64 vcc, exec, s[10:11]
	s_mov_b64 s[18:19], -1
	global_store_dwordx4 v[30:31], v[26:29], off
	s_cbranch_vccnz .LBB0_303
	v_mov_b32_e32 v32, v20
	v_mov_b32_e32 v33, v21
	v_mov_b32_e32 v28, v24
	v_mov_b32_e32 v29, v25
	s_cmpk_gt_i32 s1, 0x3ff
	v_mov_b32_e32 v30, v18
	v_mov_b32_e32 v31, v19
	v_mov_b32_e32 v26, v22
	v_mov_b32_e32 v27, v23
	s_cbranch_scc1 .LBB0_302
	v_pk_mul_f32 v[28:29], v[24:25], s[94:95] op_sel_hi:[1,0]
	v_pk_mul_f32 v[26:27], v[22:23], s[94:95] op_sel_hi:[1,0]
	v_pk_mul_f32 v[32:33], v[20:21], s[94:95] op_sel_hi:[1,0]
	v_pk_mul_f32 v[30:31], v[18:19], s[94:95] op_sel_hi:[1,0]

; #define LAS3 __attribute__((address_space(3)))
; DI unsigned pk2(float lo, float hi) { f32x2 v = {lo, hi}; return __builtin_bit_cast(unsigned, __builtin_convertvector(v, bf16x2v)); }
; DI float silu_f(float x) { return x * __builtin_amdgcn_rcpf(1.f + __expf(-x)); }
;   DI void operator()(const f32x4 (&acc)[2][2][4][2], const pg8::Unit& un, int wr, int wc, int fr, int fq) const {
;     ...
;           const int c128 = upn * 256 + bj * 128;
;           const int col0 = c128 + wc * 32 + fq * 8;
;           f32x4 v0 = acc[ai][bj][m][0], v1 = acc[ai][bj][m][1];
;           if (MODE == 2) {
;             u32x4 w; w[0] = pk2(v0[0], v0[1]); w[1] = pk2(v0[2], v0[3]); w[2] = pk2(v1[0], v1[1]); w[3] = pk2(v1[2], v1[3]);
;             *(u32x4*)(u + (size_t)row * 1024 + col0) = w;
;           } else {
;             if (isA && !isctx && c128 < kend) {
;               f32x4 p0, p1;
; #pragma unroll
;               for (int e = 0; e < 4; ++e) { p0[e] = __shfl_xor(v0[e], 32); p1[e] = __shfl_xor(v1[e], 32); }
;               const int sp = row & 2047;
;               const int pos = (wc & 1) ? (sp & 63) : (sp >> 6);
;               LAS3 const float* tb = rope + (pos * 16 + 8 * (fq & 1)) * 2;
;               const f32x4 t0 = *(LAS3 const f32x4*)(tb), t1 = *(LAS3 const f32x4*)(tb + 4), t2 = *(LAS3 const f32x4*)(tb + 8), t3 = *(LAS3 const f32x4*)(tb + 12);
;               const float sg = (fq < 2) ? -1.f : 1.f;
;               v0[0] = v0[0] * t0[0] + sg * p0[0] * t0[1]; v0[1] = v0[1] * t0[2] + sg * p0[1] * t0[3];
;               v0[2] = v0[2] * t1[0] + sg * p0[2] * t1[1]; v0[3] = v0[3] * t1[2] + sg * p0[3] * t1[3];
;               v1[0] = v1[0] * t2[0] + sg * p1[0] * t2[1]; v1[1] = v1[1] * t2[2] + sg * p1[1] * t2[3];
;               v1[2] = v1[2] * t3[0] + sg * p1[2] * t3[1]; v1[3] = v1[3] * t3[2] + sg * p1[3] * t3[3];
;             }
;             if (c128 >= vend) {
; #pragma unroll
;               for (int e = 0; e < 4; ++e) { v0[e] = silu_f(v0[e]); v1[e] = silu_f(v1[e]); }
;             } else if (c128 < 1024) {
;               v0 = v0 * (0.125f * 1.4426950408889634f); v1 = v1 * (0.125f * 1.4426950408889634f);
;             }
;             u32x4 w; w[0] = pk2(v0[0], v0[1]); w[1] = pk2(v0[2], v0[3]); w[2] = pk2(v1[0], v1[1]); w[3] = pk2(v1[2], v1[3]);
;             *(u32x4*)(qkvg + (size_t)row * NW + col0) = w;
.LBB0_305:
	v_cvt_pk_bf16_f32 v18, v26, v27
	v_cvt_pk_bf16_f32 v19, v28, v29
	v_cvt_pk_bf16_f32 v20, v30, v31
	v_cvt_pk_bf16_f32 v21, v32, v33
	v_lshl_add_u64 v[22:23], v[122:123], 1, v[34:35]
	s_and_b64 vcc, exec, s[8:9]
	s_mov_b64 s[8:9], -1
	global_store_dwordx4 v[22:23], v[18:21], off offset:256
	s_cbranch_vccnz .LBB0_309
	v_mov_b32_e32 v24, v12
	v_mov_b32_e32 v25, v13
	v_mov_b32_e32 v20, v16
	v_mov_b32_e32 v21, v17
	s_cmp_gt_i32 s89, 3
	v_mov_b32_e32 v22, v10
	v_mov_b32_e32 v23, v11
	v_mov_b32_e32 v18, v14
	v_mov_b32_e32 v19, v15
	s_cbranch_scc1 .LBB0_308
	v_pk_mul_f32 v[20:21], v[16:17], s[94:95] op_sel_hi:[1,0]
	v_pk_mul_f32 v[18:19], v[14:15], s[94:95] op_sel_hi:[1,0]
	v_pk_mul_f32 v[24:25], v[12:13], s[94:95] op_sel_hi:[1,0]
	v_pk_mul_f32 v[22:23], v[10:11], s[94:95] op_sel_hi:[1,0]

; #define LAS3 __attribute__((address_space(3)))
; DI unsigned pk2(float lo, float hi) { f32x2 v = {lo, hi}; return __builtin_bit_cast(unsigned, __builtin_convertvector(v, bf16x2v)); }
; DI float silu_f(float x) { return x * __builtin_amdgcn_rcpf(1.f + __expf(-x)); }
;   DI void operator()(const f32x4 (&acc)[2][2][4][2], const pg8::Unit& un, int wr, int wc, int fr, int fq) const {
;     ...
;           const int c128 = upn * 256 + bj * 128;
;           const int col0 = c128 + wc * 32 + fq * 8;
;           f32x4 v0 = acc[ai][bj][m][0], v1 = acc[ai][bj][m][1];
;           if (MODE == 2) {
;             u32x4 w; w[0] = pk2(v0[0], v0[1]); w[1] = pk2(v0[2], v0[3]); w[2] = pk2(v1[0], v1[1]); w[3] = pk2(v1[2], v1[3]);
;             *(u32x4*)(u + (size_t)row * 1024 + col0) = w;
;           } else {
;             if (isA && !isctx && c128 < kend) {
;               f32x4 p0, p1;
; #pragma unroll
;               for (int e = 0; e < 4; ++e) { p0[e] = __shfl_xor(v0[e], 32); p1[e] = __shfl_xor(v1[e], 32); }
;               const int sp = row & 2047;
;               const int pos = (wc & 1) ? (sp & 63) : (sp >> 6);
;               LAS3 const float* tb = rope + (pos * 16 + 8 * (fq & 1)) * 2;
;               const f32x4 t0 = *(LAS3 const f32x4*)(tb), t1 = *(LAS3 const f32x4*)(tb + 4), t2 = *(LAS3 const f32x4*)(tb + 8), t3 = *(LAS3 const f32x4*)(tb + 12);
;               const float sg = (fq < 2) ? -1.f : 1.f;
;               v0[0] = v0[0] * t0[0] + sg * p0[0] * t0[1]; v0[1] = v0[1] * t0[2] + sg * p0[1] * t0[3];
;               v0[2] = v0[2] * t1[0] + sg * p0[2] * t1[1]; v0[3] = v0[3] * t1[2] + sg * p0[3] * t1[3];
;               v1[0] = v1[0] * t2[0] + sg * p1[0] * t2[1]; v1[1] = v1[1] * t2[2] + sg * p1[1] * t2[3];
;               v1[2] = v1[2] * t3[0] + sg * p1[2] * t3[1]; v1[3] = v1[3] * t3[2] + sg * p1[3] * t3[3];
;             }
;             if (c128 >= vend) {
; #pragma unroll
;               for (int e = 0; e < 4; ++e) { v0[e] = silu_f(v0[e]); v1[e] = silu_f(v1[e]); }
;             } else if (c128 < 1024) {
;               v0 = v0 * (0.125f * 1.4426950408889634f); v1 = v1 * (0.125f * 1.4426950408889634f);
;             }
;             u32x4 w; w[0] = pk2(v0[0], v0[1]); w[1] = pk2(v0[2], v0[3]); w[2] = pk2(v1[0], v1[1]); w[3] = pk2(v1[2], v1[3]);
;             *(u32x4*)(qkvg + (size_t)row * NW + col0) = w;
.LBB0_311:
	v_add_u32_e32 v10, 0xb0, v158
	v_ashrrev_i32_e32 v11, 31, v10
	v_lshlrev_b64 v[14:15], 13, v[10:11]
	v_cvt_pk_bf16_f32 v10, v18, v19
	v_lshl_add_u64 v[18:19], s[38:39], 0, v[14:15]
	v_cvt_pk_bf16_f32 v11, v20, v21
	v_cvt_pk_bf16_f32 v12, v22, v23
	v_cvt_pk_bf16_f32 v13, v24, v25
	v_lshl_add_u64 v[14:15], v[156:157], 1, v[18:19]
	s_and_b64 vcc, exec, s[10:11]
	s_mov_b64 s[8:9], -1
	global_store_dwordx4 v[14:15], v[10:13], off
	s_cbranch_vccnz .LBB0_315
	v_mov_b32_e32 v16, v4
	v_mov_b32_e32 v17, v5
	v_mov_b32_e32 v12, v8
	v_mov_b32_e32 v13, v9
	s_cmpk_gt_i32 s1, 0x3ff
	v_mov_b32_e32 v14, v2
	v_mov_b32_e32 v15, v3
	v_mov_b32_e32 v10, v6
	v_mov_b32_e32 v11, v7
	s_cbranch_scc1 .LBB0_314
	v_pk_mul_f32 v[12:13], v[8:9], s[94:95] op_sel_hi:[1,0]
	v_pk_mul_f32 v[10:11], v[6:7], s[94:95] op_sel_hi:[1,0]
	v_pk_mul_f32 v[16:17], v[4:5], s[94:95] op_sel_hi:[1,0]
	v_pk_mul_f32 v[14:15], v[2:3], s[94:95] op_sel_hi:[1,0]

; DI unsigned xb_ld(unsigned* p)              { return __hip_atomic_load(p, __ATOMIC_RELAXED, __HIP_MEMORY_SCOPE_AGENT); }
; DI unsigned xb_add(unsigned* p, unsigned v) { return __hip_atomic_fetch_add(p, v, __ATOMIC_RELAXED, __HIP_MEMORY_SCOPE_AGENT); }
; #define XB_SPIN(cond, bar) do { unsigned _sp = 0; while (cond) { __builtin_amdgcn_s_sleep(1); \
;     if ((++_sp & 255u) == 0u) { if (xb_ld(&(bar)[XB_TMO])) break; if (_sp > XB_SPIN_CAP) { atomicAdd(&(bar)[XB_TMO], 1u); break; } } } } while (0)
; DI void xcd_barrier(unsigned* bar, volatile LAS3 unsigned* st) {
;     ...
;     const unsigned old = xb_add(&bar[XB_XSUB(x)], 1u);
;     const unsigned gen = old / nloc;
;     if (old + 1u == (gen + 1u) * nloc) {
;       __builtin_amdgcn_fence(__ATOMIC_RELEASE, "agent");
;       asm volatile("s_waitcnt vmcnt(0)" ::: "memory");
;       const unsigned og = xb_add(&bar[XB_TOP], 1u);
;       const unsigned tg = og / nx;
;       if (og + 1u == (tg + 1u) * nx) xb_add(&bar[XB_TOPGEN], 1u);
;       else XB_SPIN(xb_ld(&bar[XB_TOPGEN]) == tg, bar);
;       __builtin_amdgcn_fence(__ATOMIC_ACQUIRE, "agent");
;       xb_add(&bar[XB_XGEN(x)], 1u);
;       asm volatile("s_waitcnt vmcnt(0)" ::: "memory");
;     } else {
;       XB_SPIN(xb_ld(&bar[XB_XGEN(x)]) == gen, bar);
.LBB0_324:
	s_or_b64 exec, exec, s[10:11]
	s_waitcnt vmcnt(0)
	v_readfirstlane_b32 s2, v3
	v_sub_u32_e32 v4, 0, v2
	v_readlane_b32 s8, v254, 40
	v_add_u32_e32 v3, s2, v0
	v_cvt_f32_u32_e32 v0, v2
	v_readlane_b32 s9, v254, 41
	s_mov_b64 s[10:11], -1
	v_rcp_iflag_f32_e32 v0, v0
	s_nop 0
	v_mul_f32_e32 v0, 0x4f7ffffe, v0
	v_cvt_u32_f32_e32 v0, v0
	v_mul_lo_u32 v4, v4, v0
	v_mul_hi_u32 v4, v0, v4
	v_add_u32_e32 v0, v0, v4
	v_mul_hi_u32 v0, v3, v0
	v_mul_lo_u32 v4, v0, v2
	v_sub_u32_e32 v4, v3, v4
	v_cmp_ge_u32_e32 vcc, v4, v2
	v_add_u32_e32 v5, 1, v0
	v_add_u32_e32 v3, 1, v3
	v_cndmask_b32_e32 v0, v0, v5, vcc
	v_sub_u32_e32 v5, v4, v2
	v_cndmask_b32_e32 v4, v4, v5, vcc
	v_cmp_ge_u32_e32 vcc, v4, v2
	v_add_u32_e32 v4, 1, v0
	s_nop 0
	v_cndmask_b32_e32 v0, v0, v4, vcc
	v_mul_lo_u32 v4, v2, v0
	v_add_u32_e32 v2, v4, v2
	v_cmp_ne_u32_e32 vcc, v3, v2
	v_mov_b32_e32 v2, s8
	v_mov_b32_e32 v3, s9
	s_and_saveexec_b64 s[8:9], vcc
	s_cbranch_execz .LBB0_450
	v_readlane_b32 s10, v254, 40
	v_readlane_b32 s11, v254, 41
	s_mov_b64 s[12:13], 0
	s_nop 3
	global_load_dword v2, v1, s[10:11] sc1
	s_waitcnt vmcnt(0)
	v_cmp_eq_u32_e32 vcc, v2, v0
	s_and_saveexec_b64 s[10:11], vcc
	s_cbranch_execz .LBB0_449
	s_mov_b32 s2, 1
	s_branch .LBB0_328

; #define PG8_STAGE(bufoff, gbase, voff) do { _Pragma("unroll") for (int _i = 0; _i < 2; ++_i) \
;     __builtin_amdgcn_global_load_lds((const unsigned*)((const char*)(gbase) + (voff)[_i]), (PG8_LAS unsigned*)(lds + (bufoff) + ldsw + _i * 8192), 16, 0, 0); } while (0)
; #define PG8_LDA(dst, b, h) do { _Pragma("unroll") for (int m = 0; m < 4; ++m) _Pragma("unroll") for (int k = 0; k < 2; ++k) dst[m][k] = *(const PG8_LAS bf16x8*)(lds + PG8_SA(b, h) + aoff + m * 2048 + k * 1024); } while (0)
; #define PG8_LDB(dst, b, h) do { _Pragma("unroll") for (int n = 0; n < 2; ++n) _Pragma("unroll") for (int k = 0; k < 2; ++k) dst[n][k] = *(const PG8_LAS bf16x8*)(lds + PG8_SB(b, h) + boff + n * 2048 + k * 1024); } while (0)
; #define PG8_MMA(ai, bj, At, Bt) do { __builtin_amdgcn_s_setprio(1); _Pragma("unroll") for (int m = 0; m < 4; ++m) _Pragma("unroll") for (int n = 0; n < 2; ++n) _Pragma("unroll") for (int k = 0; k < 2; ++k) \
;     acc[ai][bj][m][n] = __builtin_amdgcn_mfma_f32_16x16x32_bf16(Bt[n][k], At[m][k], acc[ai][bj][m][n], 0, 0, 0); __builtin_amdgcn_s_setprio(0); } while (0)
; #define PG8_WAIT_V(n) asm volatile("s_waitcnt vmcnt(" #n ")" ::: "memory")
; template <class Epi>
; DI void gemm_phase(PG8_LAS unsigned char* lds, const Gemm g, const StaticOrder& S, const Epi& E) {
;     ...
;     for (int t = 0; t < nt; t += 2) {
;       const bool last = (t == nt - 2);
;       const char* a1 = cA + (size_t)(t + 1) * kstep;
;       const char* a2 = last ? nA : cA + (size_t)(t + 2) * kstep; const char* b2 = last ? nB : cB + (size_t)(t + 2) * kstep;
;       const char* a3 = a2 + kstep; const char* b3 = b2 + kstep;
;       PG8_LDB(B0, 0, 0); PG8_SCHED; PG8_LDA(At, 0, 0); PG8_STAGE(PG8_SA(1, 1), a1 + hstepA, voffA);
;       PG8_WAIT_L(8); PG8_BAR; PG8_WAIT_L(0); PG8_MMA(0, 0, At, B0); PG8_BAR; PG8_SCHED;
;       PG8_LDB(B1, 0, 1); PG8_STAGE(PG8_SB(0, 0), b2, voffB);
;       PG8_BAR; PG8_WAIT_L(0); PG8_MMA(0, 1, At, B1); PG8_BAR;
;       PG8_LDA(At, 0, 1); PG8_STAGE(PG8_SA(0, 0), a2, voffA);
;       PG8_BAR; PG8_WAIT_L(0); PG8_MMA(1, 0, At, B0); PG8_BAR; PG8_SCHED;
;       PG8_STAGE(PG8_SB(0, 1), b2 + hstepB, voffB);
;       PG8_WAIT_V(6); PG8_BAR; PG8_MMA(1, 1, At, B1); PG8_BAR;
;       PG8_LDB(B0, 1, 0); PG8_SCHED; PG8_LDA(At, 1, 0); PG8_STAGE(PG8_SA(0, 1), a2 + hstepA, voffA);
;       PG8_WAIT_L(8); PG8_BAR; PG8_WAIT_L(0); PG8_MMA(0, 0, At, B0); PG8_BAR; PG8_SCHED;
.LBB0_351:
	s_add_u32 s10, s8, 0xfffc0080
	s_addc_u32 s11, s9, -1
	s_add_i32 s26, 0, 0x10000
	v_add_u32_e32 v162, s26, v142
	ds_read_b128 v[130:133], v162
	ds_read_b128 v[134:137], v162 offset:1024
	ds_read_b128 v[156:159], v162 offset:2048
	ds_read_b128 v[162:165], v162 offset:3072
	s_cmp_eq_u32 s25, 12
	s_cselect_b32 s19, s13, s11
	s_cselect_b32 s18, s21, s10
	s_cselect_b32 s11, s1, s24
	s_cselect_b32 s10, s22, s23
	v_lshl_add_u64 v[198:199], s[8:9], 0, v[152:153]
	s_add_i32 m0, s84, 0xc000
	ds_read_b128 v[166:169], v161
	ds_read_b128 v[170:173], v161 offset:1024
	ds_read_b128 v[174:177], v161 offset:2048
	ds_read_b128 v[178:181], v161 offset:3072
	ds_read_b128 v[182:185], v161 offset:4096
	ds_read_b128 v[186:189], v161 offset:5120
	ds_read_b128 v[190:193], v161 offset:6144
	ds_read_b128 v[194:197], v161 offset:7168
	global_load_lds_dwordx4 v[198:199], off
	v_lshl_add_u64 v[198:199], s[8:9], 0, v[154:155]
	s_add_i32 m0, s84, 0xe000
	s_nop 0
	global_load_lds_dwordx4 v[198:199], off
	s_waitcnt lgkmcnt(8)
	s_barrier
	s_waitcnt lgkmcnt(0)
	s_setprio 1
	s_waitcnt lgkmcnt(0)
	v_mfma_f32_16x16x32_bf16 v[126:129], v[130:133], v[166:169], v[126:129]
	v_mfma_f32_16x16x32_bf16 v[122:125], v[156:159], v[166:169], v[122:125]
	v_mfma_f32_16x16x32_bf16 v[110:113], v[130:133], v[174:177], v[110:113]
	v_mfma_f32_16x16x32_bf16 v[106:109], v[156:159], v[174:177], v[106:109]
	v_mfma_f32_16x16x32_bf16 v[94:97], v[130:133], v[182:185], v[94:97]
	v_mfma_f32_16x16x32_bf16 v[90:93], v[156:159], v[182:185], v[90:93]
	v_mfma_f32_16x16x32_bf16 v[78:81], v[130:133], v[190:193], v[78:81]
	v_mfma_f32_16x16x32_bf16 v[74:77], v[156:159], v[190:193], v[74:77]
	v_mfma_f32_16x16x32_bf16 v[126:129], v[134:137], v[170:173], v[126:129]
	v_mfma_f32_16x16x32_bf16 v[122:125], v[162:165], v[170:173], v[122:125]
	v_mfma_f32_16x16x32_bf16 v[110:113], v[134:137], v[178:181], v[110:113]
	v_mfma_f32_16x16x32_bf16 v[106:109], v[162:165], v[178:181], v[106:109]
	v_mfma_f32_16x16x32_bf16 v[94:97], v[134:137], v[186:189], v[94:97]
	v_mfma_f32_16x16x32_bf16 v[90:93], v[162:165], v[186:189], v[90:93]
	v_mfma_f32_16x16x32_bf16 v[78:81], v[134:137], v[194:197], v[78:81]
	v_mfma_f32_16x16x32_bf16 v[74:77], v[162:165], v[194:197], v[74:77]
	s_setprio 0
	s_barrier
	s_add_i32 s33, 0, 0x14000
	v_add_u32_e32 v206, s33, v142
	s_add_i32 s26, s26, s75
	ds_read_b128 v[198:201], v206
	ds_read_b128 v[202:205], v206 offset:1024
	ds_read_b128 v[226:229], v206 offset:2048
	ds_read_b128 v[230:233], v206 offset:3072
	v_lshl_add_u64 v[206:207], s[10:11], 0, v[0:1]
	s_mov_b32 m0, s26
	v_lshl_add_u64 v[234:235], s[10:11], 0, v[138:139]
	global_load_lds_dwordx4 v[206:207], off
	s_add_i32 m0, s26, 0x2000
	s_nop 0
	global_load_lds_dwordx4 v[234:235], off
	s_barrier
	s_waitcnt lgkmcnt(0)
	s_setprio 1
	s_waitcnt lgkmcnt(0)
	v_mfma_f32_16x16x32_bf16 v[118:121], v[198:201], v[166:169], v[118:121]
	v_mfma_f32_16x16x32_bf16 v[114:117], v[226:229], v[166:169], v[114:117]
	v_mfma_f32_16x16x32_bf16 v[102:105], v[198:201], v[174:177], v[102:105]
	v_mfma_f32_16x16x32_bf16 v[98:101], v[226:229], v[174:177], v[98:101]
	v_mfma_f32_16x16x32_bf16 v[86:89], v[198:201], v[182:185], v[86:89]
	v_mfma_f32_16x16x32_bf16 v[82:85], v[226:229], v[182:185], v[82:85]
	v_mfma_f32_16x16x32_bf16 v[70:73], v[198:201], v[190:193], v[70:73]
	v_mfma_f32_16x16x32_bf16 v[66:69], v[226:229], v[190:193], v[66:69]
	v_mfma_f32_16x16x32_bf16 v[118:121], v[202:205], v[170:173], v[118:121]
	v_mfma_f32_16x16x32_bf16 v[114:117], v[230:233], v[170:173], v[114:117]
	v_mfma_f32_16x16x32_bf16 v[102:105], v[202:205], v[178:181], v[102:105]
	v_mfma_f32_16x16x32_bf16 v[98:101], v[230:233], v[178:181], v[98:101]
	v_mfma_f32_16x16x32_bf16 v[86:89], v[202:205], v[186:189], v[86:89]
	v_mfma_f32_16x16x32_bf16 v[82:85], v[230:233], v[186:189], v[82:85]
	v_mfma_f32_16x16x32_bf16 v[70:73], v[202:205], v[194:197], v[70:73]
	v_mfma_f32_16x16x32_bf16 v[66:69], v[230:233], v[194:197], v[66:69]
	s_setprio 0
	s_mov_b32 m0, s84
	v_lshl_add_u64 v[236:237], s[18:19], 0, v[148:149]
	s_barrier
	ds_read_b128 v[166:169], v161 offset:16384
	ds_read_b128 v[170:173], v161 offset:17408
	ds_read_b128 v[174:177], v161 offset:18432
	ds_read_b128 v[178:181], v161 offset:19456
	ds_read_b128 v[182:185], v161 offset:20480
	ds_read_b128 v[186:189], v161 offset:21504
	ds_read_b128 v[190:193], v161 offset:22528
	ds_read_b128 v[194:197], v161 offset:23552
	global_load_lds_dwordx4 v[236:237], off
	v_lshl_add_u64 v[238:239], s[18:19], 0, v[140:141]
	s_mov_b32 m0, s85
	s_nop 0
	global_load_lds_dwordx4 v[238:239], off
	s_barrier
	s_waitcnt lgkmcnt(0)
	s_setprio 1
	s_waitcnt lgkmcnt(0)
	v_mfma_f32_16x16x32_bf16 v[62:65], v[130:133], v[166:169], v[62:65]
	v_mfma_f32_16x16x32_bf16 v[58:61], v[156:159], v[166:169], v[58:61]
	v_mfma_f32_16x16x32_bf16 v[46:49], v[130:133], v[174:177], v[46:49]
	v_mfma_f32_16x16x32_bf16 v[42:45], v[156:159], v[174:177], v[42:45]
	v_mfma_f32_16x16x32_bf16 v[30:33], v[130:133], v[182:185], v[30:33]
	v_mfma_f32_16x16x32_bf16 v[26:29], v[156:159], v[182:185], v[26:29]
	v_mfma_f32_16x16x32_bf16 v[14:17], v[130:133], v[190:193], v[14:17]
	v_mfma_f32_16x16x32_bf16 v[10:13], v[156:159], v[190:193], v[10:13]
	v_mfma_f32_16x16x32_bf16 v[62:65], v[134:137], v[170:173], v[62:65]
	v_mfma_f32_16x16x32_bf16 v[58:61], v[162:165], v[170:173], v[58:61]
	v_mfma_f32_16x16x32_bf16 v[46:49], v[134:137], v[178:181], v[46:49]
	v_mfma_f32_16x16x32_bf16 v[42:45], v[162:165], v[178:181], v[42:45]
	v_mfma_f32_16x16x32_bf16 v[30:33], v[134:137], v[186:189], v[30:33]
	v_mfma_f32_16x16x32_bf16 v[26:29], v[162:165], v[186:189], v[26:29]
	v_mfma_f32_16x16x32_bf16 v[14:17], v[134:137], v[194:197], v[14:17]
	v_mfma_f32_16x16x32_bf16 v[10:13], v[162:165], v[194:197], v[10:13]
	s_setprio 0
	s_barrier
; #define PG8_STAGE(bufoff, gbase, voff) do { _Pragma("unroll") for (int _i = 0; _i < 2; ++_i) \
;     __builtin_amdgcn_global_load_lds((const unsigned*)((const char*)(gbase) + (voff)[_i]), (PG8_LAS unsigned*)(lds + (bufoff) + ldsw + _i * 8192), 16, 0, 0); } while (0)
; #define PG8_LDA(dst, b, h) do { _Pragma("unroll") for (int m = 0; m < 4; ++m) _Pragma("unroll") for (int k = 0; k < 2; ++k) dst[m][k] = *(const PG8_LAS bf16x8*)(lds + PG8_SA(b, h) + aoff + m * 2048 + k * 1024); } while (0)
; #define PG8_LDB(dst, b, h) do { _Pragma("unroll") for (int n = 0; n < 2; ++n) _Pragma("unroll") for (int k = 0; k < 2; ++k) dst[n][k] = *(const PG8_LAS bf16x8*)(lds + PG8_SB(b, h) + boff + n * 2048 + k * 1024); } while (0)
; #define PG8_MMA(ai, bj, At, Bt) do { __builtin_amdgcn_s_setprio(1); _Pragma("unroll") for (int m = 0; m < 4; ++m) _Pragma("unroll") for (int n = 0; n < 2; ++n) _Pragma("unroll") for (int k = 0; k < 2; ++k) \
;     acc[ai][bj][m][n] = __builtin_amdgcn_mfma_f32_16x16x32_bf16(Bt[n][k], At[m][k], acc[ai][bj][m][n], 0, 0, 0); __builtin_amdgcn_s_setprio(0); } while (0)
; #define PG8_WAIT_V(n) asm volatile("s_waitcnt vmcnt(" #n ")" ::: "memory")
; #define PG8_WAIT_L(n) asm volatile("s_waitcnt lgkmcnt(" #n ")" ::: "memory")
; #define PG8_BAR __builtin_amdgcn_s_barrier()
; #define PG8_SCHED __builtin_amdgcn_sched_barrier(0)
; template <class Epi>
; DI void gemm_phase(PG8_LAS unsigned char* lds, const Gemm g, const StaticOrder& S, const Epi& E) {
;     ...
;       PG8_BAR; PG8_WAIT_L(0); PG8_MMA(1, 0, At, B0); PG8_BAR; PG8_SCHED;
;       PG8_STAGE(PG8_SB(0, 1), b2 + hstepB, voffB);
;       PG8_WAIT_V(6); PG8_BAR; PG8_MMA(1, 1, At, B1); PG8_BAR;
;       PG8_LDB(B0, 1, 0); PG8_SCHED; PG8_LDA(At, 1, 0); PG8_STAGE(PG8_SA(0, 1), a2 + hstepA, voffA);
;       PG8_WAIT_L(8); PG8_BAR; PG8_WAIT_L(0); PG8_MMA(0, 0, At, B0); PG8_BAR; PG8_SCHED;
;       PG8_LDB(B1, 1, 1); PG8_STAGE(PG8_SB(1, 0), b3, voffB);
;       PG8_BAR; PG8_WAIT_L(0); PG8_MMA(0, 1, At, B1); PG8_BAR;
	s_add_u32 s26, s10, 0x40000
	s_addc_u32 s27, s11, 0
	s_add_i32 s33, s33, s75
	v_lshl_add_u64 v[130:131], s[26:27], 0, v[0:1]
	s_mov_b32 m0, s33
	s_nop 0
	global_load_lds_dwordx4 v[130:131], off
	v_lshl_add_u64 v[130:131], s[26:27], 0, v[138:139]
	s_add_i32 m0, s33, 0x2000
	s_nop 0
	global_load_lds_dwordx4 v[130:131], off
	s_waitcnt vmcnt(6)
	s_barrier
	s_setprio 1
	v_mfma_f32_16x16x32_bf16 v[54:57], v[198:201], v[166:169], v[54:57]
	v_mfma_f32_16x16x32_bf16 v[50:53], v[226:229], v[166:169], v[50:53]
	v_mfma_f32_16x16x32_bf16 v[38:41], v[198:201], v[174:177], v[38:41]
	v_mfma_f32_16x16x32_bf16 v[34:37], v[226:229], v[174:177], v[34:37]
	v_mfma_f32_16x16x32_bf16 v[22:25], v[198:201], v[182:185], v[22:25]
	v_mfma_f32_16x16x32_bf16 v[18:21], v[226:229], v[182:185], v[18:21]
	v_mfma_f32_16x16x32_bf16 v[6:9], v[198:201], v[190:193], v[6:9]
	v_mfma_f32_16x16x32_bf16 v[2:5], v[226:229], v[190:193], v[2:5]
	v_mfma_f32_16x16x32_bf16 v[54:57], v[202:205], v[170:173], v[54:57]
	v_mfma_f32_16x16x32_bf16 v[50:53], v[230:233], v[170:173], v[50:53]
	v_mfma_f32_16x16x32_bf16 v[38:41], v[202:205], v[178:181], v[38:41]
	v_mfma_f32_16x16x32_bf16 v[34:37], v[230:233], v[178:181], v[34:37]
	v_mfma_f32_16x16x32_bf16 v[22:25], v[202:205], v[186:189], v[22:25]
	v_mfma_f32_16x16x32_bf16 v[18:21], v[230:233], v[186:189], v[18:21]
	v_mfma_f32_16x16x32_bf16 v[6:9], v[202:205], v[194:197], v[6:9]
	v_mfma_f32_16x16x32_bf16 v[2:5], v[230:233], v[194:197], v[2:5]
	s_setprio 0
	s_add_i32 s26, 0, 0x18000
	v_add_u32_e32 v162, s26, v142
	s_barrier
	ds_read_b128 v[130:133], v162
	ds_read_b128 v[134:137], v162 offset:1024
	ds_read_b128 v[156:159], v162 offset:2048
	ds_read_b128 v[162:165], v162 offset:3072
	s_add_u32 s18, s18, 0x40000
	s_addc_u32 s19, s19, 0
	s_mov_b32 m0, s86
	v_lshl_add_u64 v[198:199], s[18:19], 0, v[148:149]
	ds_read_b128 v[166:169], v161 offset:32768
	ds_read_b128 v[170:173], v161 offset:33792
	ds_read_b128 v[174:177], v161 offset:34816
	ds_read_b128 v[178:181], v161 offset:35840
	ds_read_b128 v[182:185], v161 offset:36864
	ds_read_b128 v[186:189], v161 offset:37888
	ds_read_b128 v[190:193], v161 offset:38912
	ds_read_b128 v[194:197], v161 offset:39936
	global_load_lds_dwordx4 v[198:199], off
	v_lshl_add_u64 v[198:199], s[18:19], 0, v[140:141]
	s_mov_b32 m0, s87
	s_nop 0
	global_load_lds_dwordx4 v[198:199], off
	s_waitcnt lgkmcnt(8)
	s_barrier
	s_waitcnt lgkmcnt(0)
	s_setprio 1
	s_waitcnt lgkmcnt(0)
	v_mfma_f32_16x16x32_bf16 v[126:129], v[130:133], v[166:169], v[126:129]
	v_mfma_f32_16x16x32_bf16 v[122:125], v[156:159], v[166:169], v[122:125]
	v_mfma_f32_16x16x32_bf16 v[110:113], v[130:133], v[174:177], v[110:113]
	v_mfma_f32_16x16x32_bf16 v[106:109], v[156:159], v[174:177], v[106:109]
	v_mfma_f32_16x16x32_bf16 v[94:97], v[130:133], v[182:185], v[94:97]
	v_mfma_f32_16x16x32_bf16 v[90:93], v[156:159], v[182:185], v[90:93]
	v_mfma_f32_16x16x32_bf16 v[78:81], v[130:133], v[190:193], v[78:81]
	v_mfma_f32_16x16x32_bf16 v[74:77], v[156:159], v[190:193], v[74:77]
	v_mfma_f32_16x16x32_bf16 v[126:129], v[134:137], v[170:173], v[126:129]
	v_mfma_f32_16x16x32_bf16 v[122:125], v[162:165], v[170:173], v[122:125]
	v_mfma_f32_16x16x32_bf16 v[110:113], v[134:137], v[178:181], v[110:113]
	v_mfma_f32_16x16x32_bf16 v[106:109], v[162:165], v[178:181], v[106:109]
	v_mfma_f32_16x16x32_bf16 v[94:97], v[134:137], v[186:189], v[94:97]
	v_mfma_f32_16x16x32_bf16 v[90:93], v[162:165], v[186:189], v[90:93]
	v_mfma_f32_16x16x32_bf16 v[78:81], v[134:137], v[194:197], v[78:81]
	v_mfma_f32_16x16x32_bf16 v[74:77], v[162:165], v[194:197], v[74:77]
	s_setprio 0
	s_barrier
	s_add_i32 s18, 0, 0x1c000
	s_add_i32 s19, s26, s75
	v_add_u32_e32 v212, s18, v142
	v_lshl_add_u64 v[206:207], v[206:207], 0, s[82:83]
	s_mov_b32 m0, s19
	ds_read_b128 v[198:201], v212
	ds_read_b128 v[202:205], v212 offset:1024
	ds_read_b128 v[226:229], v212 offset:2048
	ds_read_b128 v[230:233], v212 offset:3072
	global_load_lds_dwordx4 v[206:207], off
	v_lshl_add_u64 v[206:207], v[234:235], 0, s[82:83]
	s_add_i32 m0, s19, 0x2000
	s_nop 0
	global_load_lds_dwordx4 v[206:207], off
	s_barrier
; #define LAS3 __attribute__((address_space(3)))
; template <class Epi>
; DI void gemm_phase(PG8_LAS unsigned char* lds, const Gemm g, const StaticOrder& S, const Epi& E) {
;     ...
;       PG8_BAR; PG8_WAIT_L(0); PG8_MMA(0, 1, At, B1); PG8_BAR;
;       PG8_LDA(At, 1, 1); PG8_STAGE(PG8_SA(1, 0), a3, voffA);
;       PG8_BAR; PG8_WAIT_L(0); PG8_MMA(1, 0, At, B0); PG8_BAR; PG8_SCHED;
;       PG8_STAGE(PG8_SB(1, 1), b3 + hstepB, voffB);
;       PG8_WAIT_V(6); PG8_BAR; PG8_MMA(1, 1, At, B1); PG8_BAR;
;     }
;   DI void operator()(const f32x4 (&acc)[2][2][4][2], const pg8::Unit& un, int wr, int wc, int fr, int fq) const {
;     ...
;           const int c128 = upn * 256 + bj * 128;
;           const int col0 = c128 + wc * 32 + fq * 8;
;           f32x4 v0 = acc[ai][bj][m][0], v1 = acc[ai][bj][m][1];
;           if (MODE == 2) {
;             u32x4 w; w[0] = pk2(v0[0], v0[1]); w[1] = pk2(v0[2], v0[3]); w[2] = pk2(v1[0], v1[1]); w[3] = pk2(v1[2], v1[3]);
;             *(u32x4*)(u + (size_t)row * 1024 + col0) = w;
;           } else {
;             if (isA && !isctx && c128 < kend) {
;               f32x4 p0, p1;
; #pragma unroll
;               for (int e = 0; e < 4; ++e) { p0[e] = __shfl_xor(v0[e], 32); p1[e] = __shfl_xor(v1[e], 32); }
;               const int sp = row & 2047;
;               const int pos = (wc & 1) ? (sp & 63) : (sp >> 6);
;               LAS3 const float* tb = rope + (pos * 16 + 8 * (fq & 1)) * 2;
;               const f32x4 t0 = *(LAS3 const f32x4*)(tb), t1 = *(LAS3 const f32x4*)(tb + 4), t2 = *(LAS3 const f32x4*)(tb + 8), t3 = *(LAS3 const f32x4*)(tb + 12);
;               const float sg = (fq < 2) ? -1.f : 1.f;
;               v0[0] = v0[0] * t0[0] + sg * p0[0] * t0[1]; v0[1] = v0[1] * t0[2] + sg * p0[1] * t0[3];
;               v0[2] = v0[2] * t1[0] + sg * p0[2] * t1[1]; v0[3] = v0[3] * t1[2] + sg * p0[3] * t1[3];
;               v1[0] = v1[0] * t2[0] + sg * p1[0] * t2[1]; v1[1] = v1[1] * t2[2] + sg * p1[1] * t2[3];
;               v1[2] = v1[2] * t3[0] + sg * p1[2] * t3[1]; v1[3] = v1[3] * t3[2] + sg * p1[3] * t3[3];
;             }
;             if (c128 >= vend) {
; #pragma unroll
;               for (int e = 0; e < 4; ++e) { v0[e] = silu_f(v0[e]); v1[e] = silu_f(v1[e]); }
;             } else if (c128 < 1024) {
;               v0 = v0 * (0.125f * 1.4426950408889634f); v1 = v1 * (0.125f * 1.4426950408889634f);
;             }
	s_waitcnt lgkmcnt(0)
	s_setprio 1
	s_waitcnt lgkmcnt(0)
	v_mfma_f32_16x16x32_bf16 v[118:121], v[198:201], v[166:169], v[118:121]
	v_mfma_f32_16x16x32_bf16 v[114:117], v[226:229], v[166:169], v[114:117]
	v_mfma_f32_16x16x32_bf16 v[102:105], v[198:201], v[174:177], v[102:105]
	v_mfma_f32_16x16x32_bf16 v[98:101], v[226:229], v[174:177], v[98:101]
	v_mfma_f32_16x16x32_bf16 v[86:89], v[198:201], v[182:185], v[86:89]
	v_mfma_f32_16x16x32_bf16 v[82:85], v[226:229], v[182:185], v[82:85]
	v_mfma_f32_16x16x32_bf16 v[70:73], v[198:201], v[190:193], v[70:73]
	v_mfma_f32_16x16x32_bf16 v[66:69], v[226:229], v[190:193], v[66:69]
	v_mfma_f32_16x16x32_bf16 v[118:121], v[202:205], v[170:173], v[118:121]
	v_mfma_f32_16x16x32_bf16 v[114:117], v[230:233], v[170:173], v[114:117]
	v_mfma_f32_16x16x32_bf16 v[102:105], v[202:205], v[178:181], v[102:105]
	v_mfma_f32_16x16x32_bf16 v[98:101], v[230:233], v[178:181], v[98:101]
	v_mfma_f32_16x16x32_bf16 v[86:89], v[202:205], v[186:189], v[86:89]
	v_mfma_f32_16x16x32_bf16 v[82:85], v[230:233], v[186:189], v[82:85]
	v_mfma_f32_16x16x32_bf16 v[70:73], v[202:205], v[194:197], v[70:73]
	v_mfma_f32_16x16x32_bf16 v[66:69], v[230:233], v[194:197], v[66:69]
	s_setprio 0
	s_mov_b32 m0, s96
	v_lshl_add_u64 v[206:207], v[236:237], 0, s[82:83]
	s_barrier
	ds_read_b128 v[166:169], v161 offset:49152
	ds_read_b128 v[170:173], v161 offset:50176
	ds_read_b128 v[174:177], v161 offset:51200
	ds_read_b128 v[178:181], v161 offset:52224
	ds_read_b128 v[182:185], v161 offset:53248
	ds_read_b128 v[186:189], v161 offset:54272
	ds_read_b128 v[190:193], v161 offset:55296
	ds_read_b128 v[194:197], v161 offset:56320
	global_load_lds_dwordx4 v[206:207], off
	v_lshl_add_u64 v[206:207], v[238:239], 0, s[82:83]
	s_mov_b32 m0, s97
	s_nop 0
	global_load_lds_dwordx4 v[206:207], off
	s_barrier
	s_waitcnt lgkmcnt(0)
	s_setprio 1
	s_waitcnt lgkmcnt(0)
	v_mfma_f32_16x16x32_bf16 v[62:65], v[130:133], v[166:169], v[62:65]
	v_mfma_f32_16x16x32_bf16 v[58:61], v[156:159], v[166:169], v[58:61]
	v_mfma_f32_16x16x32_bf16 v[46:49], v[130:133], v[174:177], v[46:49]
	v_mfma_f32_16x16x32_bf16 v[42:45], v[156:159], v[174:177], v[42:45]
	v_mfma_f32_16x16x32_bf16 v[30:33], v[130:133], v[182:185], v[30:33]
	v_mfma_f32_16x16x32_bf16 v[26:29], v[156:159], v[182:185], v[26:29]
	v_mfma_f32_16x16x32_bf16 v[14:17], v[130:133], v[190:193], v[14:17]
	v_mfma_f32_16x16x32_bf16 v[10:13], v[156:159], v[190:193], v[10:13]
	v_mfma_f32_16x16x32_bf16 v[62:65], v[134:137], v[170:173], v[62:65]
	v_mfma_f32_16x16x32_bf16 v[58:61], v[162:165], v[170:173], v[58:61]
	v_mfma_f32_16x16x32_bf16 v[46:49], v[134:137], v[178:181], v[46:49]
	v_mfma_f32_16x16x32_bf16 v[42:45], v[162:165], v[178:181], v[42:45]
	v_mfma_f32_16x16x32_bf16 v[30:33], v[134:137], v[186:189], v[30:33]
	v_mfma_f32_16x16x32_bf16 v[26:29], v[162:165], v[186:189], v[26:29]
	v_mfma_f32_16x16x32_bf16 v[14:17], v[134:137], v[194:197], v[14:17]
	v_mfma_f32_16x16x32_bf16 v[10:13], v[162:165], v[194:197], v[10:13]
	s_setprio 0
	s_barrier
	s_add_u32 s10, s10, 0x40080
	s_addc_u32 s11, s11, 0
	s_add_i32 s18, s18, s75
	v_lshl_add_u64 v[130:131], s[10:11], 0, v[0:1]
	s_mov_b32 m0, s18
	s_nop 0
	global_load_lds_dwordx4 v[130:131], off
	v_lshl_add_u64 v[130:131], s[10:11], 0, v[138:139]
	s_add_i32 m0, s18, 0x2000
	s_nop 0
	global_load_lds_dwordx4 v[130:131], off
	s_waitcnt vmcnt(6)
	s_barrier
	s_setprio 1
	v_mfma_f32_16x16x32_bf16 v[54:57], v[198:201], v[166:169], v[54:57]
	v_mfma_f32_16x16x32_bf16 v[50:53], v[226:229], v[166:169], v[50:53]
	v_mfma_f32_16x16x32_bf16 v[38:41], v[198:201], v[174:177], v[38:41]
	v_mfma_f32_16x16x32_bf16 v[34:37], v[226:229], v[174:177], v[34:37]
	v_mfma_f32_16x16x32_bf16 v[22:25], v[198:201], v[182:185], v[22:25]
	v_mfma_f32_16x16x32_bf16 v[18:21], v[226:229], v[182:185], v[18:21]
	v_mfma_f32_16x16x32_bf16 v[6:9], v[198:201], v[190:193], v[6:9]
	v_mfma_f32_16x16x32_bf16 v[2:5], v[226:229], v[190:193], v[2:5]
	v_mfma_f32_16x16x32_bf16 v[54:57], v[202:205], v[170:173], v[54:57]
	v_mfma_f32_16x16x32_bf16 v[50:53], v[230:233], v[170:173], v[50:53]
	v_mfma_f32_16x16x32_bf16 v[38:41], v[202:205], v[178:181], v[38:41]
	v_mfma_f32_16x16x32_bf16 v[34:37], v[230:233], v[178:181], v[34:37]
	v_mfma_f32_16x16x32_bf16 v[22:25], v[202:205], v[186:189], v[22:25]
	v_mfma_f32_16x16x32_bf16 v[18:21], v[230:233], v[186:189], v[18:21]
	v_mfma_f32_16x16x32_bf16 v[6:9], v[202:205], v[194:197], v[6:9]
	v_mfma_f32_16x16x32_bf16 v[2:5], v[230:233], v[194:197], v[2:5]
	s_setprio 0
	s_add_i32 s25, s25, 2
	s_add_u32 s8, s8, 0x100
	s_addc_u32 s9, s9, 0
	s_add_u32 s23, s23, 0x100
	s_addc_u32 s24, s24, 0
	s_cmp_gt_u32 s25, 13
	s_barrier
	s_cbranch_scc0 .LBB0_351
	s_cmp_lt_i32 s89, 8
	s_cselect_b64 s[10:11], -1, 0
	s_mov_b64 s[8:9], -1
	s_and_b64 vcc, exec, s[10:11]
	s_cbranch_vccz .LBB0_356
	v_mov_b32_e32 v136, v124
	v_mov_b32_e32 v137, v125
	v_mov_b32_e32 v132, v128
	v_mov_b32_e32 v133, v129
	s_cmp_gt_i32 s89, -1
	v_mov_b32_e32 v134, v122
	v_mov_b32_e32 v135, v123
	v_mov_b32_e32 v130, v126
	v_mov_b32_e32 v131, v127
	s_cbranch_scc1 .LBB0_355
	v_pk_mul_f32 v[132:133], v[128:129], s[94:95] op_sel_hi:[1,0]
	v_pk_mul_f32 v[130:131], v[126:127], s[94:95] op_sel_hi:[1,0]
	v_pk_mul_f32 v[136:137], v[124:125], s[94:95] op_sel_hi:[1,0]
	v_pk_mul_f32 v[134:135], v[122:123], s[94:95] op_sel_hi:[1,0]

; #define LAS3 __attribute__((address_space(3)))
; DI unsigned pk2(float lo, float hi) { f32x2 v = {lo, hi}; return __builtin_bit_cast(unsigned, __builtin_convertvector(v, bf16x2v)); }
; DI float silu_f(float x) { return x * __builtin_amdgcn_rcpf(1.f + __expf(-x)); }
;   DI void operator()(const f32x4 (&acc)[2][2][4][2], const pg8::Unit& un, int wr, int wc, int fr, int fq) const {
;     ...
;           const int c128 = upn * 256 + bj * 128;
;           const int col0 = c128 + wc * 32 + fq * 8;
;           f32x4 v0 = acc[ai][bj][m][0], v1 = acc[ai][bj][m][1];
;           if (MODE == 2) {
;             u32x4 w; w[0] = pk2(v0[0], v0[1]); w[1] = pk2(v0[2], v0[3]); w[2] = pk2(v1[0], v1[1]); w[3] = pk2(v1[2], v1[3]);
;             *(u32x4*)(u + (size_t)row * 1024 + col0) = w;
;           } else {
;             if (isA && !isctx && c128 < kend) {
;               f32x4 p0, p1;
; #pragma unroll
;               for (int e = 0; e < 4; ++e) { p0[e] = __shfl_xor(v0[e], 32); p1[e] = __shfl_xor(v1[e], 32); }
;               const int sp = row & 2047;
;               const int pos = (wc & 1) ? (sp & 63) : (sp >> 6);
;               LAS3 const float* tb = rope + (pos * 16 + 8 * (fq & 1)) * 2;
;               const f32x4 t0 = *(LAS3 const f32x4*)(tb), t1 = *(LAS3 const f32x4*)(tb + 4), t2 = *(LAS3 const f32x4*)(tb + 8), t3 = *(LAS3 const f32x4*)(tb + 12);
;               const float sg = (fq < 2) ? -1.f : 1.f;
;               v0[0] = v0[0] * t0[0] + sg * p0[0] * t0[1]; v0[1] = v0[1] * t0[2] + sg * p0[1] * t0[3];
;               v0[2] = v0[2] * t1[0] + sg * p0[2] * t1[1]; v0[3] = v0[3] * t1[2] + sg * p0[3] * t1[3];
;               v1[0] = v1[0] * t2[0] + sg * p1[0] * t2[1]; v1[1] = v1[1] * t2[2] + sg * p1[1] * t2[3];
;               v1[2] = v1[2] * t3[0] + sg * p1[2] * t3[1]; v1[3] = v1[3] * t3[2] + sg * p1[3] * t3[3];
;             }
;             if (c128 >= vend) {
; #pragma unroll
;               for (int e = 0; e < 4; ++e) { v0[e] = silu_f(v0[e]); v1[e] = silu_f(v1[e]); }
;             } else if (c128 < 1024) {
;               v0 = v0 * (0.125f * 1.4426950408889634f); v1 = v1 * (0.125f * 1.4426950408889634f);
;             }
;             u32x4 w; w[0] = pk2(v0[0], v0[1]); w[1] = pk2(v0[2], v0[3]); w[2] = pk2(v1[0], v1[1]); w[3] = pk2(v1[2], v1[3]);
;             *(u32x4*)(qkvg + (size_t)row * NW + col0) = w;
.LBB0_358:
	v_lshl_add_u32 v158, s20, 8, v160
	s_lshl_b32 s1, s89, 8
	s_add_i32 s8, s1, 0x400
	v_ashrrev_i32_e32 v159, 31, v158
	v_lshlrev_b64 v[126:127], 13, v[158:159]
	v_or_b32_e32 v156, s8, v150
	s_addk_i32 s1, 0x480
	v_cvt_pk_bf16_f32 v122, v130, v131
	v_lshl_add_u64 v[130:131], s[38:39], 0, v[126:127]
	v_ashrrev_i32_e32 v157, 31, v156
	s_cmpk_lt_i32 s1, 0xc00
	v_cvt_pk_bf16_f32 v123, v132, v133
	v_cvt_pk_bf16_f32 v124, v134, v135
	v_cvt_pk_bf16_f32 v125, v136, v137
	v_lshl_add_u64 v[126:127], v[156:157], 1, v[130:131]
	s_cselect_b64 s[18:19], -1, 0
	s_cmpk_gt_i32 s1, 0xbff
	s_mov_b64 s[70:71], -1
	global_store_dwordx4 v[126:127], v[122:125], off
	s_cbranch_scc1 .LBB0_362
	v_mov_b32_e32 v128, v116
	v_mov_b32_e32 v129, v117
	v_mov_b32_e32 v124, v120
	v_mov_b32_e32 v125, v121
	s_cmpk_gt_i32 s1, 0x3ff
	v_mov_b32_e32 v126, v114
	v_mov_b32_e32 v127, v115
	v_mov_b32_e32 v122, v118
	v_mov_b32_e32 v123, v119
	s_cbranch_scc1 .LBB0_361
	v_pk_mul_f32 v[124:125], v[120:121], s[94:95] op_sel_hi:[1,0]
	v_pk_mul_f32 v[122:123], v[118:119], s[94:95] op_sel_hi:[1,0]
	v_pk_mul_f32 v[128:129], v[116:117], s[94:95] op_sel_hi:[1,0]
	v_pk_mul_f32 v[126:127], v[114:115], s[94:95] op_sel_hi:[1,0]

; #define LAS3 __attribute__((address_space(3)))
; DI unsigned pk2(float lo, float hi) { f32x2 v = {lo, hi}; return __builtin_bit_cast(unsigned, __builtin_convertvector(v, bf16x2v)); }
; DI float silu_f(float x) { return x * __builtin_amdgcn_rcpf(1.f + __expf(-x)); }
;   DI void operator()(const f32x4 (&acc)[2][2][4][2], const pg8::Unit& un, int wr, int wc, int fr, int fq) const {
;     ...
;           const int c128 = upn * 256 + bj * 128;
;           const int col0 = c128 + wc * 32 + fq * 8;
;           f32x4 v0 = acc[ai][bj][m][0], v1 = acc[ai][bj][m][1];
;           if (MODE == 2) {
;             u32x4 w; w[0] = pk2(v0[0], v0[1]); w[1] = pk2(v0[2], v0[3]); w[2] = pk2(v1[0], v1[1]); w[3] = pk2(v1[2], v1[3]);
;             *(u32x4*)(u + (size_t)row * 1024 + col0) = w;
;           } else {
;             if (isA && !isctx && c128 < kend) {
;               f32x4 p0, p1;
; #pragma unroll
;               for (int e = 0; e < 4; ++e) { p0[e] = __shfl_xor(v0[e], 32); p1[e] = __shfl_xor(v1[e], 32); }
;               const int sp = row & 2047;
;               const int pos = (wc & 1) ? (sp & 63) : (sp >> 6);
;               LAS3 const float* tb = rope + (pos * 16 + 8 * (fq & 1)) * 2;
;               const f32x4 t0 = *(LAS3 const f32x4*)(tb), t1 = *(LAS3 const f32x4*)(tb + 4), t2 = *(LAS3 const f32x4*)(tb + 8), t3 = *(LAS3 const f32x4*)(tb + 12);
;               const float sg = (fq < 2) ? -1.f : 1.f;
;               v0[0] = v0[0] * t0[0] + sg * p0[0] * t0[1]; v0[1] = v0[1] * t0[2] + sg * p0[1] * t0[3];
;               v0[2] = v0[2] * t1[0] + sg * p0[2] * t1[1]; v0[3] = v0[3] * t1[2] + sg * p0[3] * t1[3];
;               v1[0] = v1[0] * t2[0] + sg * p1[0] * t2[1]; v1[1] = v1[1] * t2[2] + sg * p1[1] * t2[3];
;               v1[2] = v1[2] * t3[0] + sg * p1[2] * t3[1]; v1[3] = v1[3] * t3[2] + sg * p1[3] * t3[3];
;             }
;             if (c128 >= vend) {
; #pragma unroll
;               for (int e = 0; e < 4; ++e) { v0[e] = silu_f(v0[e]); v1[e] = silu_f(v1[e]); }
;             } else if (c128 < 1024) {
;               v0 = v0 * (0.125f * 1.4426950408889634f); v1 = v1 * (0.125f * 1.4426950408889634f);
;             }
;             u32x4 w; w[0] = pk2(v0[0], v0[1]); w[1] = pk2(v0[2], v0[3]); w[2] = pk2(v1[0], v1[1]); w[3] = pk2(v1[2], v1[3]);
;             *(u32x4*)(qkvg + (size_t)row * NW + col0) = w;
.LBB0_364:
	s_ashr_i32 s9, s8, 31
	v_cvt_pk_bf16_f32 v114, v122, v123
	v_lshl_add_u64 v[122:123], s[8:9], 0, v[150:151]
	v_cvt_pk_bf16_f32 v115, v124, v125
	v_cvt_pk_bf16_f32 v116, v126, v127
	v_cvt_pk_bf16_f32 v117, v128, v129
	v_lshl_add_u64 v[118:119], v[122:123], 1, v[130:131]
	global_store_dwordx4 v[118:119], v[114:117], off offset:256
	s_andn2_b64 vcc, exec, s[10:11]
	s_nop 0
	v_cndmask_b32_e64 v114, 0, 1, s[10:11]
	v_cmp_ne_u32_e64 s[8:9], 1, v114
	s_mov_b64 s[10:11], -1
	s_cbranch_vccnz .LBB0_368
	v_mov_b32_e32 v120, v108
	v_mov_b32_e32 v121, v109
	v_mov_b32_e32 v116, v112
	v_mov_b32_e32 v117, v113
	s_cmp_gt_i32 s89, -1
	v_mov_b32_e32 v118, v106
	v_mov_b32_e32 v119, v107
	v_mov_b32_e32 v114, v110
	v_mov_b32_e32 v115, v111
	s_cbranch_scc1 .LBB0_367
	v_pk_mul_f32 v[116:117], v[112:113], s[94:95] op_sel_hi:[1,0]
	v_pk_mul_f32 v[114:115], v[110:111], s[94:95] op_sel_hi:[1,0]
	v_pk_mul_f32 v[120:121], v[108:109], s[94:95] op_sel_hi:[1,0]
	v_pk_mul_f32 v[118:119], v[106:107], s[94:95] op_sel_hi:[1,0]

; #define LAS3 __attribute__((address_space(3)))
; DI unsigned pk2(float lo, float hi) { f32x2 v = {lo, hi}; return __builtin_bit_cast(unsigned, __builtin_convertvector(v, bf16x2v)); }
; DI float silu_f(float x) { return x * __builtin_amdgcn_rcpf(1.f + __expf(-x)); }
;   DI void operator()(const f32x4 (&acc)[2][2][4][2], const pg8::Unit& un, int wr, int wc, int fr, int fq) const {
;     ...
;           const int c128 = upn * 256 + bj * 128;
;           const int col0 = c128 + wc * 32 + fq * 8;
;           f32x4 v0 = acc[ai][bj][m][0], v1 = acc[ai][bj][m][1];
;           if (MODE == 2) {
;             u32x4 w; w[0] = pk2(v0[0], v0[1]); w[1] = pk2(v0[2], v0[3]); w[2] = pk2(v1[0], v1[1]); w[3] = pk2(v1[2], v1[3]);
;             *(u32x4*)(u + (size_t)row * 1024 + col0) = w;
;           } else {
;             if (isA && !isctx && c128 < kend) {
;               f32x4 p0, p1;
; #pragma unroll
;               for (int e = 0; e < 4; ++e) { p0[e] = __shfl_xor(v0[e], 32); p1[e] = __shfl_xor(v1[e], 32); }
;               const int sp = row & 2047;
;               const int pos = (wc & 1) ? (sp & 63) : (sp >> 6);
;               LAS3 const float* tb = rope + (pos * 16 + 8 * (fq & 1)) * 2;
;               const f32x4 t0 = *(LAS3 const f32x4*)(tb), t1 = *(LAS3 const f32x4*)(tb + 4), t2 = *(LAS3 const f32x4*)(tb + 8), t3 = *(LAS3 const f32x4*)(tb + 12);
;               const float sg = (fq < 2) ? -1.f : 1.f;
;               v0[0] = v0[0] * t0[0] + sg * p0[0] * t0[1]; v0[1] = v0[1] * t0[2] + sg * p0[1] * t0[3];
;               v0[2] = v0[2] * t1[0] + sg * p0[2] * t1[1]; v0[3] = v0[3] * t1[2] + sg * p0[3] * t1[3];
;               v1[0] = v1[0] * t2[0] + sg * p1[0] * t2[1]; v1[1] = v1[1] * t2[2] + sg * p1[1] * t2[3];
;               v1[2] = v1[2] * t3[0] + sg * p1[2] * t3[1]; v1[3] = v1[3] * t3[2] + sg * p1[3] * t3[3];
;             }
;             if (c128 >= vend) {
; #pragma unroll
;               for (int e = 0; e < 4; ++e) { v0[e] = silu_f(v0[e]); v1[e] = silu_f(v1[e]); }
;             } else if (c128 < 1024) {
;               v0 = v0 * (0.125f * 1.4426950408889634f); v1 = v1 * (0.125f * 1.4426950408889634f);
;             }
;             u32x4 w; w[0] = pk2(v0[0], v0[1]); w[1] = pk2(v0[2], v0[3]); w[2] = pk2(v1[0], v1[1]); w[3] = pk2(v1[2], v1[3]);
;             *(u32x4*)(qkvg + (size_t)row * NW + col0) = w;
.LBB0_376:
	v_cvt_pk_bf16_f32 v98, v106, v107
	v_cvt_pk_bf16_f32 v99, v108, v109
	v_cvt_pk_bf16_f32 v100, v110, v111
	v_cvt_pk_bf16_f32 v101, v112, v113
	v_lshl_add_u64 v[102:103], v[122:123], 1, v[114:115]
	s_and_b64 vcc, exec, s[8:9]
	s_mov_b64 s[18:19], -1
	global_store_dwordx4 v[102:103], v[98:101], off offset:256
	s_cbranch_vccnz .LBB0_380
	v_mov_b32_e32 v104, v92
	v_mov_b32_e32 v105, v93
	v_mov_b32_e32 v100, v96
	v_mov_b32_e32 v101, v97
	s_cmp_gt_i32 s89, -1
	v_mov_b32_e32 v102, v90
	v_mov_b32_e32 v103, v91
	v_mov_b32_e32 v98, v94
	v_mov_b32_e32 v99, v95
	s_cbranch_scc1 .LBB0_379
	v_pk_mul_f32 v[100:101], v[96:97], s[94:95] op_sel_hi:[1,0]
	v_pk_mul_f32 v[98:99], v[94:95], s[94:95] op_sel_hi:[1,0]
	v_pk_mul_f32 v[104:105], v[92:93], s[94:95] op_sel_hi:[1,0]
	v_pk_mul_f32 v[102:103], v[90:91], s[94:95] op_sel_hi:[1,0]

; #define LAS3 __attribute__((address_space(3)))
; DI unsigned pk2(float lo, float hi) { f32x2 v = {lo, hi}; return __builtin_bit_cast(unsigned, __builtin_convertvector(v, bf16x2v)); }
; DI float silu_f(float x) { return x * __builtin_amdgcn_rcpf(1.f + __expf(-x)); }
;   DI void operator()(const f32x4 (&acc)[2][2][4][2], const pg8::Unit& un, int wr, int wc, int fr, int fq) const {
;     ...
;           const int c128 = upn * 256 + bj * 128;
;           const int col0 = c128 + wc * 32 + fq * 8;
;           f32x4 v0 = acc[ai][bj][m][0], v1 = acc[ai][bj][m][1];
;           if (MODE == 2) {
;             u32x4 w; w[0] = pk2(v0[0], v0[1]); w[1] = pk2(v0[2], v0[3]); w[2] = pk2(v1[0], v1[1]); w[3] = pk2(v1[2], v1[3]);
;             *(u32x4*)(u + (size_t)row * 1024 + col0) = w;
;           } else {
;             if (isA && !isctx && c128 < kend) {
;               f32x4 p0, p1;
; #pragma unroll
;               for (int e = 0; e < 4; ++e) { p0[e] = __shfl_xor(v0[e], 32); p1[e] = __shfl_xor(v1[e], 32); }
;               const int sp = row & 2047;
;               const int pos = (wc & 1) ? (sp & 63) : (sp >> 6);
;               LAS3 const float* tb = rope + (pos * 16 + 8 * (fq & 1)) * 2;
;               const f32x4 t0 = *(LAS3 const f32x4*)(tb), t1 = *(LAS3 const f32x4*)(tb + 4), t2 = *(LAS3 const f32x4*)(tb + 8), t3 = *(LAS3 const f32x4*)(tb + 12);
;               const float sg = (fq < 2) ? -1.f : 1.f;
;               v0[0] = v0[0] * t0[0] + sg * p0[0] * t0[1]; v0[1] = v0[1] * t0[2] + sg * p0[1] * t0[3];
;               v0[2] = v0[2] * t1[0] + sg * p0[2] * t1[1]; v0[3] = v0[3] * t1[2] + sg * p0[3] * t1[3];
;               v1[0] = v1[0] * t2[0] + sg * p1[0] * t2[1]; v1[1] = v1[1] * t2[2] + sg * p1[1] * t2[3];
;               v1[2] = v1[2] * t3[0] + sg * p1[2] * t3[1]; v1[3] = v1[3] * t3[2] + sg * p1[3] * t3[3];
;             }
;             if (c128 >= vend) {
; #pragma unroll
;               for (int e = 0; e < 4; ++e) { v0[e] = silu_f(v0[e]); v1[e] = silu_f(v1[e]); }
;             } else if (c128 < 1024) {
;               v0 = v0 * (0.125f * 1.4426950408889634f); v1 = v1 * (0.125f * 1.4426950408889634f);
;             }
;             u32x4 w; w[0] = pk2(v0[0], v0[1]); w[1] = pk2(v0[2], v0[3]); w[2] = pk2(v1[0], v1[1]); w[3] = pk2(v1[2], v1[3]);
;             *(u32x4*)(qkvg + (size_t)row * NW + col0) = w;
.LBB0_388:
	v_cvt_pk_bf16_f32 v82, v90, v91
	v_cvt_pk_bf16_f32 v83, v92, v93
	v_cvt_pk_bf16_f32 v84, v94, v95
	v_cvt_pk_bf16_f32 v85, v96, v97
	v_lshl_add_u64 v[86:87], v[122:123], 1, v[98:99]
	s_and_b64 vcc, exec, s[8:9]
	s_mov_b64 s[18:19], -1
	global_store_dwordx4 v[86:87], v[82:85], off offset:256
	s_cbranch_vccnz .LBB0_392
	v_mov_b32_e32 v88, v76
	v_mov_b32_e32 v89, v77
	v_mov_b32_e32 v84, v80
	v_mov_b32_e32 v85, v81
	s_cmp_gt_i32 s89, -1
	v_mov_b32_e32 v86, v74
	v_mov_b32_e32 v87, v75
	v_mov_b32_e32 v82, v78
	v_mov_b32_e32 v83, v79
	s_cbranch_scc1 .LBB0_391
	v_pk_mul_f32 v[84:85], v[80:81], s[94:95] op_sel_hi:[1,0]
	v_pk_mul_f32 v[82:83], v[78:79], s[94:95] op_sel_hi:[1,0]
	v_pk_mul_f32 v[88:89], v[76:77], s[94:95] op_sel_hi:[1,0]
	v_pk_mul_f32 v[86:87], v[74:75], s[94:95] op_sel_hi:[1,0]

; #define LAS3 __attribute__((address_space(3)))
; DI unsigned pk2(float lo, float hi) { f32x2 v = {lo, hi}; return __builtin_bit_cast(unsigned, __builtin_convertvector(v, bf16x2v)); }
; DI float silu_f(float x) { return x * __builtin_amdgcn_rcpf(1.f + __expf(-x)); }
;   DI void operator()(const f32x4 (&acc)[2][2][4][2], const pg8::Unit& un, int wr, int wc, int fr, int fq) const {
;     ...
;           const int c128 = upn * 256 + bj * 128;
;           const int col0 = c128 + wc * 32 + fq * 8;
;           f32x4 v0 = acc[ai][bj][m][0], v1 = acc[ai][bj][m][1];
;           if (MODE == 2) {
;             u32x4 w; w[0] = pk2(v0[0], v0[1]); w[1] = pk2(v0[2], v0[3]); w[2] = pk2(v1[0], v1[1]); w[3] = pk2(v1[2], v1[3]);
;             *(u32x4*)(u + (size_t)row * 1024 + col0) = w;
;           } else {
;             if (isA && !isctx && c128 < kend) {
;               f32x4 p0, p1;
; #pragma unroll
;               for (int e = 0; e < 4; ++e) { p0[e] = __shfl_xor(v0[e], 32); p1[e] = __shfl_xor(v1[e], 32); }
;               const int sp = row & 2047;
;               const int pos = (wc & 1) ? (sp & 63) : (sp >> 6);
;               LAS3 const float* tb = rope + (pos * 16 + 8 * (fq & 1)) * 2;
;               const f32x4 t0 = *(LAS3 const f32x4*)(tb), t1 = *(LAS3 const f32x4*)(tb + 4), t2 = *(LAS3 const f32x4*)(tb + 8), t3 = *(LAS3 const f32x4*)(tb + 12);
;               const float sg = (fq < 2) ? -1.f : 1.f;
;               v0[0] = v0[0] * t0[0] + sg * p0[0] * t0[1]; v0[1] = v0[1] * t0[2] + sg * p0[1] * t0[3];
;               v0[2] = v0[2] * t1[0] + sg * p0[2] * t1[1]; v0[3] = v0[3] * t1[2] + sg * p0[3] * t1[3];
;               v1[0] = v1[0] * t2[0] + sg * p1[0] * t2[1]; v1[1] = v1[1] * t2[2] + sg * p1[1] * t2[3];
;               v1[2] = v1[2] * t3[0] + sg * p1[2] * t3[1]; v1[3] = v1[3] * t3[2] + sg * p1[3] * t3[3];
;             }
;             if (c128 >= vend) {
; #pragma unroll
;               for (int e = 0; e < 4; ++e) { v0[e] = silu_f(v0[e]); v1[e] = silu_f(v1[e]); }
;             } else if (c128 < 1024) {
;               v0 = v0 * (0.125f * 1.4426950408889634f); v1 = v1 * (0.125f * 1.4426950408889634f);
;             }
;             u32x4 w; w[0] = pk2(v0[0], v0[1]); w[1] = pk2(v0[2], v0[3]); w[2] = pk2(v1[0], v1[1]); w[3] = pk2(v1[2], v1[3]);
;             *(u32x4*)(qkvg + (size_t)row * NW + col0) = w;
.LBB0_400:
	v_cvt_pk_bf16_f32 v66, v74, v75
	v_cvt_pk_bf16_f32 v67, v76, v77
	v_cvt_pk_bf16_f32 v68, v78, v79
	v_cvt_pk_bf16_f32 v69, v80, v81
	v_lshl_add_u64 v[70:71], v[122:123], 1, v[82:83]
	s_and_b64 vcc, exec, s[8:9]
	s_mov_b64 s[18:19], -1
	global_store_dwordx4 v[70:71], v[66:69], off offset:256
	s_cbranch_vccnz .LBB0_404
	v_mov_b32_e32 v72, v60
	v_mov_b32_e32 v73, v61
	v_mov_b32_e32 v68, v64
	v_mov_b32_e32 v69, v65
	s_cmp_gt_i32 s89, -1
	v_mov_b32_e32 v70, v58
	v_mov_b32_e32 v71, v59
	v_mov_b32_e32 v66, v62
	v_mov_b32_e32 v67, v63
	s_cbranch_scc1 .LBB0_403
	v_pk_mul_f32 v[68:69], v[64:65], s[94:95] op_sel_hi:[1,0]
	v_pk_mul_f32 v[66:67], v[62:63], s[94:95] op_sel_hi:[1,0]
	v_pk_mul_f32 v[72:73], v[60:61], s[94:95] op_sel_hi:[1,0]
	v_pk_mul_f32 v[70:71], v[58:59], s[94:95] op_sel_hi:[1,0]

; #define LAS3 __attribute__((address_space(3)))
; DI unsigned pk2(float lo, float hi) { f32x2 v = {lo, hi}; return __builtin_bit_cast(unsigned, __builtin_convertvector(v, bf16x2v)); }
; DI float silu_f(float x) { return x * __builtin_amdgcn_rcpf(1.f + __expf(-x)); }
;   DI void operator()(const f32x4 (&acc)[2][2][4][2], const pg8::Unit& un, int wr, int wc, int fr, int fq) const {
;     ...
;           const int c128 = upn * 256 + bj * 128;
;           const int col0 = c128 + wc * 32 + fq * 8;
;           f32x4 v0 = acc[ai][bj][m][0], v1 = acc[ai][bj][m][1];
;           if (MODE == 2) {
;             u32x4 w; w[0] = pk2(v0[0], v0[1]); w[1] = pk2(v0[2], v0[3]); w[2] = pk2(v1[0], v1[1]); w[3] = pk2(v1[2], v1[3]);
;             *(u32x4*)(u + (size_t)row * 1024 + col0) = w;
;           } else {
;             if (isA && !isctx && c128 < kend) {
;               f32x4 p0, p1;
; #pragma unroll
;               for (int e = 0; e < 4; ++e) { p0[e] = __shfl_xor(v0[e], 32); p1[e] = __shfl_xor(v1[e], 32); }
;               const int sp = row & 2047;
;               const int pos = (wc & 1) ? (sp & 63) : (sp >> 6);
;               LAS3 const float* tb = rope + (pos * 16 + 8 * (fq & 1)) * 2;
;               const f32x4 t0 = *(LAS3 const f32x4*)(tb), t1 = *(LAS3 const f32x4*)(tb + 4), t2 = *(LAS3 const f32x4*)(tb + 8), t3 = *(LAS3 const f32x4*)(tb + 12);
;               const float sg = (fq < 2) ? -1.f : 1.f;
;               v0[0] = v0[0] * t0[0] + sg * p0[0] * t0[1]; v0[1] = v0[1] * t0[2] + sg * p0[1] * t0[3];
;               v0[2] = v0[2] * t1[0] + sg * p0[2] * t1[1]; v0[3] = v0[3] * t1[2] + sg * p0[3] * t1[3];
;               v1[0] = v1[0] * t2[0] + sg * p1[0] * t2[1]; v1[1] = v1[1] * t2[2] + sg * p1[1] * t2[3];
;               v1[2] = v1[2] * t3[0] + sg * p1[2] * t3[1]; v1[3] = v1[3] * t3[2] + sg * p1[3] * t3[3];
;             }
;             if (c128 >= vend) {
; #pragma unroll
;               for (int e = 0; e < 4; ++e) { v0[e] = silu_f(v0[e]); v1[e] = silu_f(v1[e]); }
;             } else if (c128 < 1024) {
;               v0 = v0 * (0.125f * 1.4426950408889634f); v1 = v1 * (0.125f * 1.4426950408889634f);
;             }
;             u32x4 w; w[0] = pk2(v0[0], v0[1]); w[1] = pk2(v0[2], v0[3]); w[2] = pk2(v1[0], v1[1]); w[3] = pk2(v1[2], v1[3]);
;             *(u32x4*)(qkvg + (size_t)row * NW + col0) = w;
.LBB0_412:
	v_cvt_pk_bf16_f32 v50, v58, v59
	v_cvt_pk_bf16_f32 v51, v60, v61
	v_cvt_pk_bf16_f32 v52, v62, v63
	v_cvt_pk_bf16_f32 v53, v64, v65
	v_lshl_add_u64 v[54:55], v[122:123], 1, v[66:67]
	s_and_b64 vcc, exec, s[8:9]
	s_mov_b64 s[18:19], -1
	global_store_dwordx4 v[54:55], v[50:53], off offset:256
	s_cbranch_vccnz .LBB0_416
	v_mov_b32_e32 v56, v44
	v_mov_b32_e32 v57, v45
	v_mov_b32_e32 v52, v48
	v_mov_b32_e32 v53, v49
	s_cmp_gt_i32 s89, -1
	v_mov_b32_e32 v54, v42
	v_mov_b32_e32 v55, v43
	v_mov_b32_e32 v50, v46
	v_mov_b32_e32 v51, v47
	s_cbranch_scc1 .LBB0_415
	v_pk_mul_f32 v[52:53], v[48:49], s[94:95] op_sel_hi:[1,0]
	v_pk_mul_f32 v[50:51], v[46:47], s[94:95] op_sel_hi:[1,0]
	v_pk_mul_f32 v[56:57], v[44:45], s[94:95] op_sel_hi:[1,0]
	v_pk_mul_f32 v[54:55], v[42:43], s[94:95] op_sel_hi:[1,0]

; #define LAS3 __attribute__((address_space(3)))
; DI unsigned pk2(float lo, float hi) { f32x2 v = {lo, hi}; return __builtin_bit_cast(unsigned, __builtin_convertvector(v, bf16x2v)); }
; DI float silu_f(float x) { return x * __builtin_amdgcn_rcpf(1.f + __expf(-x)); }
;   DI void operator()(const f32x4 (&acc)[2][2][4][2], const pg8::Unit& un, int wr, int wc, int fr, int fq) const {
;     ...
;           const int c128 = upn * 256 + bj * 128;
;           const int col0 = c128 + wc * 32 + fq * 8;
;           f32x4 v0 = acc[ai][bj][m][0], v1 = acc[ai][bj][m][1];
;           if (MODE == 2) {
;             u32x4 w; w[0] = pk2(v0[0], v0[1]); w[1] = pk2(v0[2], v0[3]); w[2] = pk2(v1[0], v1[1]); w[3] = pk2(v1[2], v1[3]);
;             *(u32x4*)(u + (size_t)row * 1024 + col0) = w;
;           } else {
;             if (isA && !isctx && c128 < kend) {
;               f32x4 p0, p1;
; #pragma unroll
;               for (int e = 0; e < 4; ++e) { p0[e] = __shfl_xor(v0[e], 32); p1[e] = __shfl_xor(v1[e], 32); }
;               const int sp = row & 2047;
;               const int pos = (wc & 1) ? (sp & 63) : (sp >> 6);
;               LAS3 const float* tb = rope + (pos * 16 + 8 * (fq & 1)) * 2;
;               const f32x4 t0 = *(LAS3 const f32x4*)(tb), t1 = *(LAS3 const f32x4*)(tb + 4), t2 = *(LAS3 const f32x4*)(tb + 8), t3 = *(LAS3 const f32x4*)(tb + 12);
;               const float sg = (fq < 2) ? -1.f : 1.f;
;               v0[0] = v0[0] * t0[0] + sg * p0[0] * t0[1]; v0[1] = v0[1] * t0[2] + sg * p0[1] * t0[3];
;               v0[2] = v0[2] * t1[0] + sg * p0[2] * t1[1]; v0[3] = v0[3] * t1[2] + sg * p0[3] * t1[3];
;               v1[0] = v1[0] * t2[0] + sg * p1[0] * t2[1]; v1[1] = v1[1] * t2[2] + sg * p1[1] * t2[3];
;               v1[2] = v1[2] * t3[0] + sg * p1[2] * t3[1]; v1[3] = v1[3] * t3[2] + sg * p1[3] * t3[3];
;             }
;             if (c128 >= vend) {
; #pragma unroll
;               for (int e = 0; e < 4; ++e) { v0[e] = silu_f(v0[e]); v1[e] = silu_f(v1[e]); }
;             } else if (c128 < 1024) {
;               v0 = v0 * (0.125f * 1.4426950408889634f); v1 = v1 * (0.125f * 1.4426950408889634f);
;             }
;             u32x4 w; w[0] = pk2(v0[0], v0[1]); w[1] = pk2(v0[2], v0[3]); w[2] = pk2(v1[0], v1[1]); w[3] = pk2(v1[2], v1[3]);
;             *(u32x4*)(qkvg + (size_t)row * NW + col0) = w;
.LBB0_424:
	v_cvt_pk_bf16_f32 v34, v42, v43
	v_cvt_pk_bf16_f32 v35, v44, v45
	v_cvt_pk_bf16_f32 v36, v46, v47
	v_cvt_pk_bf16_f32 v37, v48, v49
	v_lshl_add_u64 v[38:39], v[122:123], 1, v[50:51]
	s_and_b64 vcc, exec, s[8:9]
	s_mov_b64 s[18:19], -1
	global_store_dwordx4 v[38:39], v[34:37], off offset:256
	s_cbranch_vccnz .LBB0_428
	v_mov_b32_e32 v40, v28
	v_mov_b32_e32 v41, v29
	v_mov_b32_e32 v36, v32
	v_mov_b32_e32 v37, v33
	s_cmp_gt_i32 s89, -1
	v_mov_b32_e32 v38, v26
	v_mov_b32_e32 v39, v27
	v_mov_b32_e32 v34, v30
	v_mov_b32_e32 v35, v31
	s_cbranch_scc1 .LBB0_427
	v_pk_mul_f32 v[36:37], v[32:33], s[94:95] op_sel_hi:[1,0]
	v_pk_mul_f32 v[34:35], v[30:31], s[94:95] op_sel_hi:[1,0]
	v_pk_mul_f32 v[40:41], v[28:29], s[94:95] op_sel_hi:[1,0]
	v_pk_mul_f32 v[38:39], v[26:27], s[94:95] op_sel_hi:[1,0]

; #define LAS3 __attribute__((address_space(3)))
; DI unsigned pk2(float lo, float hi) { f32x2 v = {lo, hi}; return __builtin_bit_cast(unsigned, __builtin_convertvector(v, bf16x2v)); }
; DI float silu_f(float x) { return x * __builtin_amdgcn_rcpf(1.f + __expf(-x)); }
;   DI void operator()(const f32x4 (&acc)[2][2][4][2], const pg8::Unit& un, int wr, int wc, int fr, int fq) const {
;     ...
;           const int c128 = upn * 256 + bj * 128;
;           const int col0 = c128 + wc * 32 + fq * 8;
;           f32x4 v0 = acc[ai][bj][m][0], v1 = acc[ai][bj][m][1];
;           if (MODE == 2) {
;             u32x4 w; w[0] = pk2(v0[0], v0[1]); w[1] = pk2(v0[2], v0[3]); w[2] = pk2(v1[0], v1[1]); w[3] = pk2(v1[2], v1[3]);
;             *(u32x4*)(u + (size_t)row * 1024 + col0) = w;
;           } else {
;             if (isA && !isctx && c128 < kend) {
;               f32x4 p0, p1;
; #pragma unroll
;               for (int e = 0; e < 4; ++e) { p0[e] = __shfl_xor(v0[e], 32); p1[e] = __shfl_xor(v1[e], 32); }
;               const int sp = row & 2047;
;               const int pos = (wc & 1) ? (sp & 63) : (sp >> 6);
;               LAS3 const float* tb = rope + (pos * 16 + 8 * (fq & 1)) * 2;
;               const f32x4 t0 = *(LAS3 const f32x4*)(tb), t1 = *(LAS3 const f32x4*)(tb + 4), t2 = *(LAS3 const f32x4*)(tb + 8), t3 = *(LAS3 const f32x4*)(tb + 12);
;               const float sg = (fq < 2) ? -1.f : 1.f;
;               v0[0] = v0[0] * t0[0] + sg * p0[0] * t0[1]; v0[1] = v0[1] * t0[2] + sg * p0[1] * t0[3];
;               v0[2] = v0[2] * t1[0] + sg * p0[2] * t1[1]; v0[3] = v0[3] * t1[2] + sg * p0[3] * t1[3];
;               v1[0] = v1[0] * t2[0] + sg * p1[0] * t2[1]; v1[1] = v1[1] * t2[2] + sg * p1[1] * t2[3];
;               v1[2] = v1[2] * t3[0] + sg * p1[2] * t3[1]; v1[3] = v1[3] * t3[2] + sg * p1[3] * t3[3];
;             }
;             if (c128 >= vend) {
; #pragma unroll
;               for (int e = 0; e < 4; ++e) { v0[e] = silu_f(v0[e]); v1[e] = silu_f(v1[e]); }
;             } else if (c128 < 1024) {
;               v0 = v0 * (0.125f * 1.4426950408889634f); v1 = v1 * (0.125f * 1.4426950408889634f);
;             }
;             u32x4 w; w[0] = pk2(v0[0], v0[1]); w[1] = pk2(v0[2], v0[3]); w[2] = pk2(v1[0], v1[1]); w[3] = pk2(v1[2], v1[3]);
;             *(u32x4*)(qkvg + (size_t)row * NW + col0) = w;
.LBB0_436:
	v_cvt_pk_bf16_f32 v18, v26, v27
	v_cvt_pk_bf16_f32 v19, v28, v29
	v_cvt_pk_bf16_f32 v20, v30, v31
	v_cvt_pk_bf16_f32 v21, v32, v33
	v_lshl_add_u64 v[22:23], v[122:123], 1, v[34:35]
	s_and_b64 vcc, exec, s[8:9]
	s_mov_b64 s[8:9], -1
	global_store_dwordx4 v[22:23], v[18:21], off offset:256
	s_cbranch_vccnz .LBB0_440
	v_mov_b32_e32 v24, v12
	v_mov_b32_e32 v25, v13
	v_mov_b32_e32 v20, v16
	v_mov_b32_e32 v21, v17
	s_cmp_gt_i32 s89, -1
	v_mov_b32_e32 v22, v10
	v_mov_b32_e32 v23, v11
	v_mov_b32_e32 v18, v14
	v_mov_b32_e32 v19, v15
	s_cbranch_scc1 .LBB0_439
	v_pk_mul_f32 v[20:21], v[16:17], s[94:95] op_sel_hi:[1,0]
	v_pk_mul_f32 v[18:19], v[14:15], s[94:95] op_sel_hi:[1,0]
	v_pk_mul_f32 v[24:25], v[12:13], s[94:95] op_sel_hi:[1,0]
	v_pk_mul_f32 v[22:23], v[10:11], s[94:95] op_sel_hi:[1,0]

; DI unsigned xb_ld(unsigned* p)              { return __hip_atomic_load(p, __ATOMIC_RELAXED, __HIP_MEMORY_SCOPE_AGENT); }
; DI unsigned xb_add(unsigned* p, unsigned v) { return __hip_atomic_fetch_add(p, v, __ATOMIC_RELAXED, __HIP_MEMORY_SCOPE_AGENT); }
; #define XB_SPIN(cond, bar) do { unsigned _sp = 0; while (cond) { __builtin_amdgcn_s_sleep(1); \
;     if ((++_sp & 255u) == 0u) { if (xb_ld(&(bar)[XB_TMO])) break; if (_sp > XB_SPIN_CAP) { atomicAdd(&(bar)[XB_TMO], 1u); break; } } } } while (0)
; DI void xcd_barrier(unsigned* bar, volatile LAS3 unsigned* st) {
;     ...
;     const unsigned old = xb_add(&bar[XB_XSUB(x)], 1u);
;     const unsigned gen = old / nloc;
;     if (old + 1u == (gen + 1u) * nloc) {
;       __builtin_amdgcn_fence(__ATOMIC_RELEASE, "agent");
;       asm volatile("s_waitcnt vmcnt(0)" ::: "memory");
;       const unsigned og = xb_add(&bar[XB_TOP], 1u);
;       const unsigned tg = og / nx;
;       if (og + 1u == (tg + 1u) * nx) xb_add(&bar[XB_TOPGEN], 1u);
;       else XB_SPIN(xb_ld(&bar[XB_TOPGEN]) == tg, bar);
;       __builtin_amdgcn_fence(__ATOMIC_ACQUIRE, "agent");
;       xb_add(&bar[XB_XGEN(x)], 1u);
;       asm volatile("s_waitcnt vmcnt(0)" ::: "memory");
;     } else {
;       XB_SPIN(xb_ld(&bar[XB_XGEN(x)]) == gen, bar);
;       __builtin_amdgcn_fence(__ATOMIC_ACQUIRE, "agent");
;       asm volatile("s_waitcnt vmcnt(0)" ::: "memory");
;     }
.LBB0_449:
	s_or_b64 exec, exec, s[10:11]
	v_readlane_b32 s10, v254, 28
	v_readlane_b32 s11, v254, 29
	s_nop 1
	v_mov_b32_e32 v2, s10
	v_mov_b32_e32 v3, s11
	s_orn2_b64 s[10:11], s[12:13], exec

; #define LAS3 __attribute__((address_space(3)))
; DI int opaque_tid() { int t = threadIdx.x; asm volatile("" : "+v"(t)); return t; }
;     ...
;   LAS3 float* ropel = (LAS3 float*)((LAS3 char*)smem + 131072);
;   if (MODE == 0) {
;     const int tid = opaque_tid();
;     for (int e = tid; e < 64 * 16 * 2; e += NTHR) ropel[e] = p.rope[e];
;     __syncthreads();
.LBB0_578:
	s_load_dword s69, s[86:87], 0x0
	v_mov_b32_e32 v2, v208
	s_movk_i32 s0, 0x800
	s_nop 0
	v_cmp_gt_i32_e32 vcc, s0, v2
	s_and_saveexec_b64 s[0:1], vcc
	s_cbranch_execz .LBB0_591
	v_max_i32_e32 v0, 0x600, v2
	v_sub_u32_e32 v0, v0, v2
	v_add_u32_e32 v0, 0x1ff, v0
	s_movk_i32 s2, 0x1ff
	v_cmp_lt_u32_e32 vcc, s2, v0
	s_mov_b64 s[8:9], -1
	s_and_saveexec_b64 s[6:7], vcc
	s_cbranch_execz .LBB0_588
	v_lshrrev_b32_e32 v0, 9, v0
	v_add_u32_e32 v4, -1, v0
	v_add_u32_e32 v3, 0x200, v2
	v_lshrrev_b32_e32 v5, 1, v4
	v_add_u32_e32 v6, 1, v5
	v_cmp_lt_u32_e32 vcc, 13, v4
	v_mov_b32_e32 v9, 0
	v_mov_b32_e32 v4, v2
	v_mov_b32_e32 v5, v3
	s_and_saveexec_b64 s[8:9], vcc
	s_cbranch_execz .LBB0_584
	v_readlane_b32 s2, v255, 21
	v_and_b32_e32 v7, -8, v6
	s_mov_b64 s[10:11], 0
	v_lshl_add_u32 v8, v2, 2, s2
	s_mov_b32 s2, 0
	v_mov_b32_e32 v4, v2
	v_mov_b32_e32 v5, v3

; DI float silu_f(float x) { return x * __builtin_amdgcn_rcpf(1.f + __expf(-x)); }
;   DI void operator()(const f32x4 (&acc)[2][2][4][2], const pg8::Unit& un, int wr, int wc, int fr, int fq) const {
;     ...
;             if (c128 >= vend) {
; #pragma unroll
;               for (int e = 0; e < 4; ++e) { v0[e] = silu_f(v0[e]); v1[e] = silu_f(v1[e]); }
;             } else if (c128 < 1024) {
;               v0 = v0 * (0.125f * 1.4426950408889634f); v1 = v1 * (0.125f * 1.4426950408889634f);
;             }
.LBB0_602:
	s_cmp_lt_i32 s86, 6
	s_cselect_b64 s[16:17], -1, 0
	s_mov_b64 s[14:15], -1
	s_and_b64 vcc, exec, s[16:17]
	s_cbranch_vccz .LBB0_606
	v_mov_b32_e32 v132, v128
	v_mov_b32_e32 v133, v129
	v_mov_b32_e32 v136, v124
	v_mov_b32_e32 v137, v125
	s_cmp_gt_i32 s86, 3
	v_mov_b32_e32 v130, v126
	v_mov_b32_e32 v131, v127
	v_mov_b32_e32 v134, v122
	v_mov_b32_e32 v135, v123
	s_cbranch_scc1 .LBB0_605
	v_pk_mul_f32 v[132:133], v[128:129], s[94:95] op_sel_hi:[1,0]
	v_pk_mul_f32 v[130:131], v[126:127], s[94:95] op_sel_hi:[1,0]
	v_pk_mul_f32 v[136:137], v[124:125], s[94:95] op_sel_hi:[1,0]
	v_pk_mul_f32 v[134:135], v[122:123], s[94:95] op_sel_hi:[1,0]

; #define LAS3 __attribute__((address_space(3)))
; DI unsigned pk2(float lo, float hi) { f32x2 v = {lo, hi}; return __builtin_bit_cast(unsigned, __builtin_convertvector(v, bf16x2v)); }
; DI float silu_f(float x) { return x * __builtin_amdgcn_rcpf(1.f + __expf(-x)); }
;   DI void operator()(const f32x4 (&acc)[2][2][4][2], const pg8::Unit& un, int wr, int wc, int fr, int fq) const {
;     ...
;             u32x4 w; w[0] = pk2(v0[0], v0[1]); w[1] = pk2(v0[2], v0[3]); w[2] = pk2(v1[0], v1[1]); w[3] = pk2(v1[2], v1[3]);
;             *(u32x4*)(u + (size_t)row * 1024 + col0) = w;
;           } else {
;             if (isA && !isctx && c128 < kend) {
;               f32x4 p0, p1;
; #pragma unroll
;               for (int e = 0; e < 4; ++e) { p0[e] = __shfl_xor(v0[e], 32); p1[e] = __shfl_xor(v1[e], 32); }
;               const int sp = row & 2047;
;               const int pos = (wc & 1) ? (sp & 63) : (sp >> 6);
;               LAS3 const float* tb = rope + (pos * 16 + 8 * (fq & 1)) * 2;
;               const f32x4 t0 = *(LAS3 const f32x4*)(tb), t1 = *(LAS3 const f32x4*)(tb + 4), t2 = *(LAS3 const f32x4*)(tb + 8), t3 = *(LAS3 const f32x4*)(tb + 12);
;               const float sg = (fq < 2) ? -1.f : 1.f;
;               v0[0] = v0[0] * t0[0] + sg * p0[0] * t0[1]; v0[1] = v0[1] * t0[2] + sg * p0[1] * t0[3];
;               v0[2] = v0[2] * t1[0] + sg * p0[2] * t1[1]; v0[3] = v0[3] * t1[2] + sg * p0[3] * t1[3];
;               v1[0] = v1[0] * t2[0] + sg * p1[0] * t2[1]; v1[1] = v1[1] * t2[2] + sg * p1[1] * t2[3];
;               v1[2] = v1[2] * t3[0] + sg * p1[2] * t3[1]; v1[3] = v1[3] * t3[2] + sg * p1[3] * t3[3];
;             }
;             if (c128 >= vend) {
; #pragma unroll
;               for (int e = 0; e < 4; ++e) { v0[e] = silu_f(v0[e]); v1[e] = silu_f(v1[e]); }
;             } else if (c128 < 1024) {
;               v0 = v0 * (0.125f * 1.4426950408889634f); v1 = v1 * (0.125f * 1.4426950408889634f);
;             }
;             u32x4 w; w[0] = pk2(v0[0], v0[1]); w[1] = pk2(v0[2], v0[3]); w[2] = pk2(v1[0], v1[1]); w[3] = pk2(v1[2], v1[3]);
;             *(u32x4*)(qkvg + (size_t)row * NW + col0) = w;
.LBB0_608:
	s_lshl_b32 s14, s86, 8
	v_or_b32_e32 v128, s97, v142
	v_mov_b32_e32 v126, s38
	v_mov_b32_e32 v127, s39
	s_or_b32 s1, s14, 0x80
	v_cvt_pk_bf16_f32 v122, v130, v131
	v_mad_i64_i32 v[130:131], s[20:21], v128, s92, v[126:127]
	s_cmpk_lt_i32 s1, 0x500
	s_cselect_b64 s[20:21], -1, 0
	v_or_b32_e32 v158, s14, v150
	s_and_b64 s[20:21], s[12:13], s[20:21]
	v_ashrrev_i32_e32 v159, 31, v158
	v_cndmask_b32_e64 v128, 0, 1, s[20:21]
	v_cvt_pk_bf16_f32 v123, v132, v133
	v_cvt_pk_bf16_f32 v124, v134, v135
	v_cvt_pk_bf16_f32 v125, v136, v137
	v_lshl_add_u64 v[126:127], v[158:159], 1, v[130:131]
	v_cmp_ne_u32_e64 s[12:13], 1, v128
	s_andn2_b64 vcc, exec, s[20:21]
	global_store_dwordx4 v[126:127], v[122:125], off
	s_cbranch_vccnz .LBB0_610
	s_nop 0
	v_and_b32_e32 v123, 64, v214
	v_xor_b32_e32 v122, 32, v214
	v_add_u32_e32 v123, 64, v123
	v_cmp_lt_i32_e32 vcc, v122, v123
	s_nop 1
	v_cndmask_b32_e32 v122, v214, v122, vcc
	v_lshlrev_b32_e32 v126, 2, v122
	ds_bpermute_b32 v136, v126, v118
	ds_bpermute_b32 v137, v126, v119
	ds_read_b128 v[122:125], v166
	ds_bpermute_b32 v174, v126, v120
	ds_bpermute_b32 v176, v126, v121
	ds_bpermute_b32 v170, v126, v114
	ds_bpermute_b32 v171, v126, v115
	ds_bpermute_b32 v175, v126, v116
	ds_bpermute_b32 v177, v126, v117
	ds_read_b128 v[126:129], v166 offset:16
	ds_read_b128 v[132:135], v166 offset:32
	ds_read_b128 v[166:169], v166 offset:48
	s_waitcnt lgkmcnt(0)
	v_mov_b32_e32 v173, v124
	v_pk_mul_f32 v[136:137], v[152:153], v[136:137]
	v_mov_b32_e32 v124, v123
	v_mov_b32_e32 v172, v122
	v_pk_mul_f32 v[122:123], v[136:137], v[124:125]
	v_mul_f32_e32 v124, v152, v174
	v_mul_f32_e32 v120, v120, v126
	v_mul_f32_e32 v124, v124, v127
	v_mul_f32_e32 v127, v152, v176
	v_mov_b32_e32 v126, v121
	v_pk_mul_f32 v[126:127], v[126:127], v[128:129]
	v_mul_f32_e32 v129, v152, v177
	v_mov_b32_e32 v121, v126
	v_mov_b32_e32 v125, v127
	v_mov_b32_e32 v128, v117
	v_pk_fma_f32 v[118:119], v[118:119], v[172:173], v[122:123]
	v_pk_add_f32 v[120:121], v[120:121], v[124:125]
	v_mov_b32_e32 v123, v134
	v_pk_mul_f32 v[124:125], v[152:153], v[170:171]
	v_mov_b32_e32 v134, v133
	v_mul_f32_e32 v126, v152, v175
	v_pk_mul_f32 v[128:129], v[128:129], v[168:169]
	v_mov_b32_e32 v122, v132
	v_pk_mul_f32 v[124:125], v[124:125], v[134:135]
	v_mul_f32_e32 v116, v116, v166
	v_mul_f32_e32 v126, v126, v167
	v_mov_b32_e32 v117, v128
	v_mov_b32_e32 v127, v129
	v_pk_fma_f32 v[114:115], v[114:115], v[122:123], v[124:125]
	v_pk_add_f32 v[116:117], v[116:117], v[126:127]
.LBB0_610:
	s_cmpk_lt_i32 s1, 0x600
	s_cselect_b64 s[70:71], -1, 0
	s_cmpk_gt_i32 s1, 0x5ff
	s_mov_b64 vcc, -1
	s_cbranch_scc1 .LBB0_614
	v_mov_b32_e32 v124, v120
	v_mov_b32_e32 v125, v121
	v_mov_b32_e32 v128, v116
	v_mov_b32_e32 v129, v117
	s_cmpk_gt_i32 s1, 0x3ff
	v_mov_b32_e32 v122, v118
	v_mov_b32_e32 v123, v119
	v_mov_b32_e32 v126, v114
	v_mov_b32_e32 v127, v115
	s_cbranch_scc1 .LBB0_613
	v_pk_mul_f32 v[124:125], v[120:121], s[94:95] op_sel_hi:[1,0]
	v_pk_mul_f32 v[122:123], v[118:119], s[94:95] op_sel_hi:[1,0]
	v_pk_mul_f32 v[128:129], v[116:117], s[94:95] op_sel_hi:[1,0]
	v_pk_mul_f32 v[126:127], v[114:115], s[94:95] op_sel_hi:[1,0]

; DI float silu_f(float x) { return x * __builtin_amdgcn_rcpf(1.f + __expf(-x)); }
;   DI void operator()(const f32x4 (&acc)[2][2][4][2], const pg8::Unit& un, int wr, int wc, int fr, int fq) const {
;     ...
;             if (c128 >= vend) {
; #pragma unroll
;               for (int e = 0; e < 4; ++e) { v0[e] = silu_f(v0[e]); v1[e] = silu_f(v1[e]); }
;             } else if (c128 < 1024) {
;               v0 = v0 * (0.125f * 1.4426950408889634f); v1 = v1 * (0.125f * 1.4426950408889634f);
;             }
.LBB0_618:
	v_cndmask_b32_e64 v114, 0, 1, s[16:17]
	v_cmp_ne_u32_e64 s[14:15], 1, v114
	s_andn2_b64 vcc, exec, s[16:17]
	s_mov_b64 s[16:17], -1
	s_cbranch_vccnz .LBB0_622
	v_mov_b32_e32 v116, v112
	v_mov_b32_e32 v117, v113
	v_mov_b32_e32 v120, v108
	v_mov_b32_e32 v121, v109
	s_cmp_gt_i32 s86, 3
	v_mov_b32_e32 v114, v110
	v_mov_b32_e32 v115, v111
	v_mov_b32_e32 v118, v106
	v_mov_b32_e32 v119, v107
	s_cbranch_scc1 .LBB0_621
	v_pk_mul_f32 v[116:117], v[112:113], s[94:95] op_sel_hi:[1,0]
	v_pk_mul_f32 v[114:115], v[110:111], s[94:95] op_sel_hi:[1,0]
	v_pk_mul_f32 v[120:121], v[108:109], s[94:95] op_sel_hi:[1,0]
	v_pk_mul_f32 v[118:119], v[106:107], s[94:95] op_sel_hi:[1,0]

; #define LAS3 __attribute__((address_space(3)))
; DI unsigned pk2(float lo, float hi) { f32x2 v = {lo, hi}; return __builtin_bit_cast(unsigned, __builtin_convertvector(v, bf16x2v)); }
; DI float silu_f(float x) { return x * __builtin_amdgcn_rcpf(1.f + __expf(-x)); }
;   DI void operator()(const f32x4 (&acc)[2][2][4][2], const pg8::Unit& un, int wr, int wc, int fr, int fq) const {
;     ...
;             u32x4 w; w[0] = pk2(v0[0], v0[1]); w[1] = pk2(v0[2], v0[3]); w[2] = pk2(v1[0], v1[1]); w[3] = pk2(v1[2], v1[3]);
;             *(u32x4*)(u + (size_t)row * 1024 + col0) = w;
;           } else {
;             if (isA && !isctx && c128 < kend) {
;               f32x4 p0, p1;
; #pragma unroll
;               for (int e = 0; e < 4; ++e) { p0[e] = __shfl_xor(v0[e], 32); p1[e] = __shfl_xor(v1[e], 32); }
;               const int sp = row & 2047;
;               const int pos = (wc & 1) ? (sp & 63) : (sp >> 6);
;               LAS3 const float* tb = rope + (pos * 16 + 8 * (fq & 1)) * 2;
;               const f32x4 t0 = *(LAS3 const f32x4*)(tb), t1 = *(LAS3 const f32x4*)(tb + 4), t2 = *(LAS3 const f32x4*)(tb + 8), t3 = *(LAS3 const f32x4*)(tb + 12);
;               const float sg = (fq < 2) ? -1.f : 1.f;
;               v0[0] = v0[0] * t0[0] + sg * p0[0] * t0[1]; v0[1] = v0[1] * t0[2] + sg * p0[1] * t0[3];
;               v0[2] = v0[2] * t1[0] + sg * p0[2] * t1[1]; v0[3] = v0[3] * t1[2] + sg * p0[3] * t1[3];
;               v1[0] = v1[0] * t2[0] + sg * p1[0] * t2[1]; v1[1] = v1[1] * t2[2] + sg * p1[1] * t2[3];
;               v1[2] = v1[2] * t3[0] + sg * p1[2] * t3[1]; v1[3] = v1[3] * t3[2] + sg * p1[3] * t3[3];
;             }
;             if (c128 >= vend) {
; #pragma unroll
;               for (int e = 0; e < 4; ++e) { v0[e] = silu_f(v0[e]); v1[e] = silu_f(v1[e]); }
;             } else if (c128 < 1024) {
;               v0 = v0 * (0.125f * 1.4426950408889634f); v1 = v1 * (0.125f * 1.4426950408889634f);
;             }
;             u32x4 w; w[0] = pk2(v0[0], v0[1]); w[1] = pk2(v0[2], v0[3]); w[2] = pk2(v1[0], v1[1]); w[3] = pk2(v1[2], v1[3]);
;             *(u32x4*)(qkvg + (size_t)row * NW + col0) = w;
.LBB0_624:
	v_or_b32_e32 v112, s97, v161
	v_mov_b32_e32 v110, s38
	v_mov_b32_e32 v111, s39
	v_cvt_pk_bf16_f32 v106, v114, v115
	v_mad_i64_i32 v[114:115], s[16:17], v112, s92, v[110:111]
	v_cvt_pk_bf16_f32 v107, v116, v117
	v_cvt_pk_bf16_f32 v108, v118, v119
	v_cvt_pk_bf16_f32 v109, v120, v121
	v_lshl_add_u64 v[110:111], v[158:159], 1, v[114:115]
	s_and_b64 vcc, exec, s[12:13]
	global_store_dwordx4 v[110:111], v[106:109], off
	s_cbranch_vccnz .LBB0_626
	s_nop 0
	v_and_b32_e32 v107, 64, v214
	v_xor_b32_e32 v106, 32, v214
	v_add_u32_e32 v107, 64, v107
	v_cmp_lt_i32_e32 vcc, v106, v107
	s_nop 1
	v_cndmask_b32_e32 v106, v214, v106, vcc
	v_lshlrev_b32_e32 v110, 2, v106
	ds_bpermute_b32 v120, v110, v102
	ds_bpermute_b32 v121, v110, v103
	ds_read_b128 v[106:109], v124
	ds_bpermute_b32 v132, v110, v104
	ds_bpermute_b32 v134, v110, v105
	ds_bpermute_b32 v128, v110, v98
	ds_bpermute_b32 v129, v110, v99
	ds_bpermute_b32 v133, v110, v100
	ds_bpermute_b32 v135, v110, v101
	ds_read_b128 v[110:113], v124 offset:16
	ds_read_b128 v[116:119], v124 offset:32
	ds_read_b128 v[124:127], v124 offset:48
	s_waitcnt lgkmcnt(0)
	v_mov_b32_e32 v131, v108
	v_pk_mul_f32 v[120:121], v[152:153], v[120:121]
	v_mov_b32_e32 v108, v107
	v_mov_b32_e32 v130, v106
	v_pk_mul_f32 v[106:107], v[120:121], v[108:109]
	v_mul_f32_e32 v108, v152, v132
	v_mul_f32_e32 v104, v104, v110
	v_mul_f32_e32 v108, v108, v111
	v_mul_f32_e32 v111, v152, v134
	v_mov_b32_e32 v110, v105
	v_pk_mul_f32 v[110:111], v[110:111], v[112:113]
	v_mul_f32_e32 v113, v152, v135
	v_mov_b32_e32 v105, v110
	v_mov_b32_e32 v109, v111
	v_mov_b32_e32 v112, v101
	v_pk_fma_f32 v[102:103], v[102:103], v[130:131], v[106:107]
	v_pk_add_f32 v[104:105], v[104:105], v[108:109]
	v_mov_b32_e32 v107, v118
	v_pk_mul_f32 v[108:109], v[152:153], v[128:129]
	v_mov_b32_e32 v118, v117
	v_mul_f32_e32 v110, v152, v133
	v_pk_mul_f32 v[112:113], v[112:113], v[126:127]
	v_mov_b32_e32 v106, v116
	v_pk_mul_f32 v[108:109], v[108:109], v[118:119]
	v_mul_f32_e32 v100, v100, v124
	v_mul_f32_e32 v110, v110, v125
	v_mov_b32_e32 v101, v112
	v_mov_b32_e32 v111, v113
	v_pk_fma_f32 v[98:99], v[98:99], v[106:107], v[108:109]
	v_pk_add_f32 v[100:101], v[100:101], v[110:111]
.LBB0_626:
	s_nop 0
	v_cndmask_b32_e64 v106, 0, 1, s[70:71]
	v_cmp_ne_u32_e64 s[16:17], 1, v106
	s_andn2_b64 vcc, exec, s[70:71]
	s_mov_b64 s[70:71], -1
	s_cbranch_vccnz .LBB0_630
	v_mov_b32_e32 v108, v104
	v_mov_b32_e32 v109, v105
	v_mov_b32_e32 v112, v100
	v_mov_b32_e32 v113, v101
	s_cmpk_gt_i32 s1, 0x3ff
	v_mov_b32_e32 v106, v102
	v_mov_b32_e32 v107, v103
	v_mov_b32_e32 v110, v98
	v_mov_b32_e32 v111, v99
	s_cbranch_scc1 .LBB0_629
	v_pk_mul_f32 v[108:109], v[104:105], s[94:95] op_sel_hi:[1,0]
	v_pk_mul_f32 v[106:107], v[102:103], s[94:95] op_sel_hi:[1,0]
	v_pk_mul_f32 v[112:113], v[100:101], s[94:95] op_sel_hi:[1,0]
	v_pk_mul_f32 v[110:111], v[98:99], s[94:95] op_sel_hi:[1,0]

; DI float silu_f(float x) { return x * __builtin_amdgcn_rcpf(1.f + __expf(-x)); }
;   DI void operator()(const f32x4 (&acc)[2][2][4][2], const pg8::Unit& un, int wr, int wc, int fr, int fq) const {
;     ...
;             if (c128 >= vend) {
; #pragma unroll
;               for (int e = 0; e < 4; ++e) { v0[e] = silu_f(v0[e]); v1[e] = silu_f(v1[e]); }
;             } else if (c128 < 1024) {
;               v0 = v0 * (0.125f * 1.4426950408889634f); v1 = v1 * (0.125f * 1.4426950408889634f);
;             }
.LBB0_634:
	s_and_b64 vcc, exec, s[14:15]
	s_mov_b64 s[70:71], -1
	s_cbranch_vccnz .LBB0_638
	v_mov_b32_e32 v100, v96
	v_mov_b32_e32 v101, v97
	v_mov_b32_e32 v104, v92
	v_mov_b32_e32 v105, v93
	s_cmp_gt_i32 s86, 3
	v_mov_b32_e32 v98, v94
	v_mov_b32_e32 v99, v95
	v_mov_b32_e32 v102, v90
	v_mov_b32_e32 v103, v91
	s_cbranch_scc1 .LBB0_637
	v_pk_mul_f32 v[100:101], v[96:97], s[94:95] op_sel_hi:[1,0]
	v_pk_mul_f32 v[98:99], v[94:95], s[94:95] op_sel_hi:[1,0]
	v_pk_mul_f32 v[104:105], v[92:93], s[94:95] op_sel_hi:[1,0]
	v_pk_mul_f32 v[102:103], v[90:91], s[94:95] op_sel_hi:[1,0]

; #define LAS3 __attribute__((address_space(3)))
; DI unsigned pk2(float lo, float hi) { f32x2 v = {lo, hi}; return __builtin_bit_cast(unsigned, __builtin_convertvector(v, bf16x2v)); }
; DI float silu_f(float x) { return x * __builtin_amdgcn_rcpf(1.f + __expf(-x)); }
;   DI void operator()(const f32x4 (&acc)[2][2][4][2], const pg8::Unit& un, int wr, int wc, int fr, int fq) const {
;     ...
;             u32x4 w; w[0] = pk2(v0[0], v0[1]); w[1] = pk2(v0[2], v0[3]); w[2] = pk2(v1[0], v1[1]); w[3] = pk2(v1[2], v1[3]);
;             *(u32x4*)(u + (size_t)row * 1024 + col0) = w;
;           } else {
;             if (isA && !isctx && c128 < kend) {
;               f32x4 p0, p1;
; #pragma unroll
;               for (int e = 0; e < 4; ++e) { p0[e] = __shfl_xor(v0[e], 32); p1[e] = __shfl_xor(v1[e], 32); }
;               const int sp = row & 2047;
;               const int pos = (wc & 1) ? (sp & 63) : (sp >> 6);
;               LAS3 const float* tb = rope + (pos * 16 + 8 * (fq & 1)) * 2;
;               const f32x4 t0 = *(LAS3 const f32x4*)(tb), t1 = *(LAS3 const f32x4*)(tb + 4), t2 = *(LAS3 const f32x4*)(tb + 8), t3 = *(LAS3 const f32x4*)(tb + 12);
;               const float sg = (fq < 2) ? -1.f : 1.f;
;               v0[0] = v0[0] * t0[0] + sg * p0[0] * t0[1]; v0[1] = v0[1] * t0[2] + sg * p0[1] * t0[3];
;               v0[2] = v0[2] * t1[0] + sg * p0[2] * t1[1]; v0[3] = v0[3] * t1[2] + sg * p0[3] * t1[3];
;               v1[0] = v1[0] * t2[0] + sg * p1[0] * t2[1]; v1[1] = v1[1] * t2[2] + sg * p1[1] * t2[3];
;               v1[2] = v1[2] * t3[0] + sg * p1[2] * t3[1]; v1[3] = v1[3] * t3[2] + sg * p1[3] * t3[3];
;             }
;             if (c128 >= vend) {
; #pragma unroll
;               for (int e = 0; e < 4; ++e) { v0[e] = silu_f(v0[e]); v1[e] = silu_f(v1[e]); }
;             } else if (c128 < 1024) {
;               v0 = v0 * (0.125f * 1.4426950408889634f); v1 = v1 * (0.125f * 1.4426950408889634f);
;             }
;             u32x4 w; w[0] = pk2(v0[0], v0[1]); w[1] = pk2(v0[2], v0[3]); w[2] = pk2(v1[0], v1[1]); w[3] = pk2(v1[2], v1[3]);
;             *(u32x4*)(qkvg + (size_t)row * NW + col0) = w;
.LBB0_640:
	v_or_b32_e32 v96, s97, v162
	v_mov_b32_e32 v94, s38
	v_mov_b32_e32 v95, s39
	v_cvt_pk_bf16_f32 v90, v98, v99
	v_mad_i64_i32 v[98:99], s[20:21], v96, s92, v[94:95]
	v_cvt_pk_bf16_f32 v91, v100, v101
	v_cvt_pk_bf16_f32 v92, v102, v103
	v_cvt_pk_bf16_f32 v93, v104, v105
	v_lshl_add_u64 v[94:95], v[158:159], 1, v[98:99]
	s_and_b64 vcc, exec, s[12:13]
	global_store_dwordx4 v[94:95], v[90:93], off
	s_cbranch_vccnz .LBB0_642
	s_nop 0
	v_and_b32_e32 v91, 64, v214
	v_xor_b32_e32 v90, 32, v214
	v_add_u32_e32 v91, 64, v91
	v_cmp_lt_i32_e32 vcc, v90, v91
	s_nop 1
	v_cndmask_b32_e32 v90, v214, v90, vcc
	v_lshlrev_b32_e32 v94, 2, v90
	ds_bpermute_b32 v108, v94, v86
	ds_bpermute_b32 v109, v94, v87
	ds_read_b128 v[90:93], v106
	ds_bpermute_b32 v114, v94, v88
	ds_bpermute_b32 v116, v94, v89
	ds_bpermute_b32 v110, v94, v82
	ds_bpermute_b32 v111, v94, v83
	ds_bpermute_b32 v115, v94, v84
	ds_bpermute_b32 v117, v94, v85
	ds_read_b128 v[94:97], v106 offset:16
	ds_read_b128 v[100:103], v106 offset:32
	ds_read_b128 v[104:107], v106 offset:48
	s_waitcnt lgkmcnt(0)
	v_mov_b32_e32 v113, v92
	v_pk_mul_f32 v[108:109], v[152:153], v[108:109]
	v_mov_b32_e32 v92, v91
	v_mov_b32_e32 v112, v90
	v_pk_mul_f32 v[90:91], v[108:109], v[92:93]
	v_mul_f32_e32 v92, v152, v114
	v_mul_f32_e32 v88, v88, v94
	v_mul_f32_e32 v92, v92, v95
	v_mul_f32_e32 v95, v152, v116
	v_mov_b32_e32 v94, v89
	v_pk_mul_f32 v[94:95], v[94:95], v[96:97]
	v_mul_f32_e32 v97, v152, v117
	v_mov_b32_e32 v89, v94
	v_mov_b32_e32 v93, v95
	v_mov_b32_e32 v96, v85
	v_pk_fma_f32 v[86:87], v[86:87], v[112:113], v[90:91]
	v_pk_add_f32 v[88:89], v[88:89], v[92:93]
	v_mov_b32_e32 v91, v102
	v_pk_mul_f32 v[92:93], v[152:153], v[110:111]
	v_mov_b32_e32 v102, v101
	v_mul_f32_e32 v94, v152, v115
	v_pk_mul_f32 v[96:97], v[96:97], v[106:107]
	v_mov_b32_e32 v90, v100
	v_pk_mul_f32 v[92:93], v[92:93], v[102:103]
	v_mul_f32_e32 v84, v84, v104
	v_mul_f32_e32 v94, v94, v105
	v_mov_b32_e32 v85, v96
	v_mov_b32_e32 v95, v97
	v_pk_fma_f32 v[82:83], v[82:83], v[90:91], v[92:93]
	v_pk_add_f32 v[84:85], v[84:85], v[94:95]
.LBB0_642:
	s_and_b64 vcc, exec, s[16:17]
	s_mov_b64 s[70:71], -1
	s_cbranch_vccnz .LBB0_646
	v_mov_b32_e32 v92, v88
	v_mov_b32_e32 v93, v89
	v_mov_b32_e32 v96, v84
	v_mov_b32_e32 v97, v85
	s_cmpk_gt_i32 s1, 0x3ff
	v_mov_b32_e32 v90, v86
	v_mov_b32_e32 v91, v87
	v_mov_b32_e32 v94, v82
	v_mov_b32_e32 v95, v83
	s_cbranch_scc1 .LBB0_645
	v_pk_mul_f32 v[92:93], v[88:89], s[94:95] op_sel_hi:[1,0]
	v_pk_mul_f32 v[90:91], v[86:87], s[94:95] op_sel_hi:[1,0]
	v_pk_mul_f32 v[96:97], v[84:85], s[94:95] op_sel_hi:[1,0]
	v_pk_mul_f32 v[94:95], v[82:83], s[94:95] op_sel_hi:[1,0]

; DI float silu_f(float x) { return x * __builtin_amdgcn_rcpf(1.f + __expf(-x)); }
;   DI void operator()(const f32x4 (&acc)[2][2][4][2], const pg8::Unit& un, int wr, int wc, int fr, int fq) const {
;     ...
;             if (c128 >= vend) {
; #pragma unroll
;               for (int e = 0; e < 4; ++e) { v0[e] = silu_f(v0[e]); v1[e] = silu_f(v1[e]); }
;             } else if (c128 < 1024) {
;               v0 = v0 * (0.125f * 1.4426950408889634f); v1 = v1 * (0.125f * 1.4426950408889634f);
;             }
.LBB0_650:
	s_and_b64 vcc, exec, s[14:15]
	s_mov_b64 s[70:71], -1
	s_cbranch_vccnz .LBB0_654
	v_mov_b32_e32 v84, v80
	v_mov_b32_e32 v85, v81
	v_mov_b32_e32 v88, v76
	v_mov_b32_e32 v89, v77
	s_cmp_gt_i32 s86, 3
	v_mov_b32_e32 v82, v78
	v_mov_b32_e32 v83, v79
	v_mov_b32_e32 v86, v74
	v_mov_b32_e32 v87, v75
	s_cbranch_scc1 .LBB0_653
	v_pk_mul_f32 v[84:85], v[80:81], s[94:95] op_sel_hi:[1,0]
	v_pk_mul_f32 v[82:83], v[78:79], s[94:95] op_sel_hi:[1,0]
	v_pk_mul_f32 v[88:89], v[76:77], s[94:95] op_sel_hi:[1,0]
	v_pk_mul_f32 v[86:87], v[74:75], s[94:95] op_sel_hi:[1,0]

; #define LAS3 __attribute__((address_space(3)))
; DI unsigned pk2(float lo, float hi) { f32x2 v = {lo, hi}; return __builtin_bit_cast(unsigned, __builtin_convertvector(v, bf16x2v)); }
; DI float silu_f(float x) { return x * __builtin_amdgcn_rcpf(1.f + __expf(-x)); }
;   DI void operator()(const f32x4 (&acc)[2][2][4][2], const pg8::Unit& un, int wr, int wc, int fr, int fq) const {
;     ...
;             u32x4 w; w[0] = pk2(v0[0], v0[1]); w[1] = pk2(v0[2], v0[3]); w[2] = pk2(v1[0], v1[1]); w[3] = pk2(v1[2], v1[3]);
;             *(u32x4*)(u + (size_t)row * 1024 + col0) = w;
;           } else {
;             if (isA && !isctx && c128 < kend) {
;               f32x4 p0, p1;
; #pragma unroll
;               for (int e = 0; e < 4; ++e) { p0[e] = __shfl_xor(v0[e], 32); p1[e] = __shfl_xor(v1[e], 32); }
;               const int sp = row & 2047;
;               const int pos = (wc & 1) ? (sp & 63) : (sp >> 6);
;               LAS3 const float* tb = rope + (pos * 16 + 8 * (fq & 1)) * 2;
;               const f32x4 t0 = *(LAS3 const f32x4*)(tb), t1 = *(LAS3 const f32x4*)(tb + 4), t2 = *(LAS3 const f32x4*)(tb + 8), t3 = *(LAS3 const f32x4*)(tb + 12);
;               const float sg = (fq < 2) ? -1.f : 1.f;
;               v0[0] = v0[0] * t0[0] + sg * p0[0] * t0[1]; v0[1] = v0[1] * t0[2] + sg * p0[1] * t0[3];
;               v0[2] = v0[2] * t1[0] + sg * p0[2] * t1[1]; v0[3] = v0[3] * t1[2] + sg * p0[3] * t1[3];
;               v1[0] = v1[0] * t2[0] + sg * p1[0] * t2[1]; v1[1] = v1[1] * t2[2] + sg * p1[1] * t2[3];
;               v1[2] = v1[2] * t3[0] + sg * p1[2] * t3[1]; v1[3] = v1[3] * t3[2] + sg * p1[3] * t3[3];
;             }
;             if (c128 >= vend) {
; #pragma unroll
;               for (int e = 0; e < 4; ++e) { v0[e] = silu_f(v0[e]); v1[e] = silu_f(v1[e]); }
;             } else if (c128 < 1024) {
;               v0 = v0 * (0.125f * 1.4426950408889634f); v1 = v1 * (0.125f * 1.4426950408889634f);
;             }
;             u32x4 w; w[0] = pk2(v0[0], v0[1]); w[1] = pk2(v0[2], v0[3]); w[2] = pk2(v1[0], v1[1]); w[3] = pk2(v1[2], v1[3]);
;             *(u32x4*)(qkvg + (size_t)row * NW + col0) = w;
.LBB0_656:
	v_or_b32_e32 v80, s97, v163
	v_mov_b32_e32 v78, s38
	v_mov_b32_e32 v79, s39
	v_cvt_pk_bf16_f32 v74, v82, v83
	v_mad_i64_i32 v[82:83], s[20:21], v80, s92, v[78:79]
	v_cvt_pk_bf16_f32 v75, v84, v85
	v_cvt_pk_bf16_f32 v76, v86, v87
	v_cvt_pk_bf16_f32 v77, v88, v89
	v_lshl_add_u64 v[78:79], v[158:159], 1, v[82:83]
	s_and_b64 vcc, exec, s[12:13]
	global_store_dwordx4 v[78:79], v[74:77], off
	s_cbranch_vccnz .LBB0_658
	s_nop 0
	v_and_b32_e32 v75, 64, v214
	v_xor_b32_e32 v74, 32, v214
	v_add_u32_e32 v75, 64, v75
	v_cmp_lt_i32_e32 vcc, v74, v75
	s_nop 1
	v_cndmask_b32_e32 v74, v214, v74, vcc
	v_lshlrev_b32_e32 v78, 2, v74
	ds_bpermute_b32 v92, v78, v70
	ds_bpermute_b32 v93, v78, v71
	ds_read_b128 v[74:77], v90
	ds_bpermute_b32 v98, v78, v72
	ds_bpermute_b32 v100, v78, v73
	ds_bpermute_b32 v94, v78, v66
	ds_bpermute_b32 v95, v78, v67
	ds_bpermute_b32 v99, v78, v68
	ds_bpermute_b32 v101, v78, v69
	ds_read_b128 v[78:81], v90 offset:16
	ds_read_b128 v[84:87], v90 offset:32
	ds_read_b128 v[88:91], v90 offset:48
	s_waitcnt lgkmcnt(0)
	v_mov_b32_e32 v97, v76
	v_pk_mul_f32 v[92:93], v[152:153], v[92:93]
	v_mov_b32_e32 v76, v75
	v_mov_b32_e32 v96, v74
	v_pk_mul_f32 v[74:75], v[92:93], v[76:77]
	v_mul_f32_e32 v76, v152, v98
	v_mul_f32_e32 v72, v72, v78
	v_mul_f32_e32 v76, v76, v79
	v_mul_f32_e32 v79, v152, v100
	v_mov_b32_e32 v78, v73
	v_pk_mul_f32 v[78:79], v[78:79], v[80:81]
	v_mul_f32_e32 v81, v152, v101
	v_mov_b32_e32 v73, v78
	v_mov_b32_e32 v77, v79
	v_mov_b32_e32 v80, v69
	v_pk_fma_f32 v[70:71], v[70:71], v[96:97], v[74:75]
	v_pk_add_f32 v[72:73], v[72:73], v[76:77]
	v_mov_b32_e32 v75, v86
	v_pk_mul_f32 v[76:77], v[152:153], v[94:95]
	v_mov_b32_e32 v86, v85
	v_mul_f32_e32 v78, v152, v99
	v_pk_mul_f32 v[80:81], v[80:81], v[90:91]
	v_mov_b32_e32 v74, v84
	v_pk_mul_f32 v[76:77], v[76:77], v[86:87]
	v_mul_f32_e32 v68, v68, v88
	v_mul_f32_e32 v78, v78, v89
	v_mov_b32_e32 v69, v80
	v_mov_b32_e32 v79, v81
	v_pk_fma_f32 v[66:67], v[66:67], v[74:75], v[76:77]
	v_pk_add_f32 v[68:69], v[68:69], v[78:79]
.LBB0_658:
	s_and_b64 vcc, exec, s[16:17]
	s_mov_b64 s[70:71], -1
	s_cbranch_vccnz .LBB0_662
	v_mov_b32_e32 v76, v72
	v_mov_b32_e32 v77, v73
	v_mov_b32_e32 v80, v68
	v_mov_b32_e32 v81, v69
	s_cmpk_gt_i32 s1, 0x3ff
	v_mov_b32_e32 v74, v70
	v_mov_b32_e32 v75, v71
	v_mov_b32_e32 v78, v66
	v_mov_b32_e32 v79, v67
	s_cbranch_scc1 .LBB0_661
	v_pk_mul_f32 v[76:77], v[72:73], s[94:95] op_sel_hi:[1,0]
	v_pk_mul_f32 v[74:75], v[70:71], s[94:95] op_sel_hi:[1,0]
	v_pk_mul_f32 v[80:81], v[68:69], s[94:95] op_sel_hi:[1,0]
	v_pk_mul_f32 v[78:79], v[66:67], s[94:95] op_sel_hi:[1,0]

; DI float silu_f(float x) { return x * __builtin_amdgcn_rcpf(1.f + __expf(-x)); }
;   DI void operator()(const f32x4 (&acc)[2][2][4][2], const pg8::Unit& un, int wr, int wc, int fr, int fq) const {
;     ...
;             if (c128 >= vend) {
; #pragma unroll
;               for (int e = 0; e < 4; ++e) { v0[e] = silu_f(v0[e]); v1[e] = silu_f(v1[e]); }
;             } else if (c128 < 1024) {
;               v0 = v0 * (0.125f * 1.4426950408889634f); v1 = v1 * (0.125f * 1.4426950408889634f);
;             }
.LBB0_666:
	s_and_b64 vcc, exec, s[14:15]
	s_mov_b64 s[70:71], -1
	s_cbranch_vccnz .LBB0_670
	v_mov_b32_e32 v68, v64
	v_mov_b32_e32 v69, v65
	v_mov_b32_e32 v72, v60
	v_mov_b32_e32 v73, v61
	s_cmp_gt_i32 s86, 3
	v_mov_b32_e32 v66, v62
	v_mov_b32_e32 v67, v63
	v_mov_b32_e32 v70, v58
	v_mov_b32_e32 v71, v59
	s_cbranch_scc1 .LBB0_669
	v_pk_mul_f32 v[68:69], v[64:65], s[94:95] op_sel_hi:[1,0]
	v_pk_mul_f32 v[66:67], v[62:63], s[94:95] op_sel_hi:[1,0]
	v_pk_mul_f32 v[72:73], v[60:61], s[94:95] op_sel_hi:[1,0]
	v_pk_mul_f32 v[70:71], v[58:59], s[94:95] op_sel_hi:[1,0]

; #define LAS3 __attribute__((address_space(3)))
; DI unsigned pk2(float lo, float hi) { f32x2 v = {lo, hi}; return __builtin_bit_cast(unsigned, __builtin_convertvector(v, bf16x2v)); }
; DI float silu_f(float x) { return x * __builtin_amdgcn_rcpf(1.f + __expf(-x)); }
;   DI void operator()(const f32x4 (&acc)[2][2][4][2], const pg8::Unit& un, int wr, int wc, int fr, int fq) const {
;     ...
;         const int row = upm * 256 + ai * 128 + wr * 64 + m * 16 + fr;
; #pragma unroll
;         for (int bj = 0; bj < 2; ++bj) {
;           const int c128 = upn * 256 + bj * 128;
;           const int col0 = c128 + wc * 32 + fq * 8;
;           f32x4 v0 = acc[ai][bj][m][0], v1 = acc[ai][bj][m][1];
;           if (MODE == 2) {
;             u32x4 w; w[0] = pk2(v0[0], v0[1]); w[1] = pk2(v0[2], v0[3]); w[2] = pk2(v1[0], v1[1]); w[3] = pk2(v1[2], v1[3]);
;             *(u32x4*)(u + (size_t)row * 1024 + col0) = w;
;           } else {
;             if (isA && !isctx && c128 < kend) {
;               f32x4 p0, p1;
; #pragma unroll
;               for (int e = 0; e < 4; ++e) { p0[e] = __shfl_xor(v0[e], 32); p1[e] = __shfl_xor(v1[e], 32); }
;               const int sp = row & 2047;
;               const int pos = (wc & 1) ? (sp & 63) : (sp >> 6);
;               LAS3 const float* tb = rope + (pos * 16 + 8 * (fq & 1)) * 2;
;               const f32x4 t0 = *(LAS3 const f32x4*)(tb), t1 = *(LAS3 const f32x4*)(tb + 4), t2 = *(LAS3 const f32x4*)(tb + 8), t3 = *(LAS3 const f32x4*)(tb + 12);
;               const float sg = (fq < 2) ? -1.f : 1.f;
;               v0[0] = v0[0] * t0[0] + sg * p0[0] * t0[1]; v0[1] = v0[1] * t0[2] + sg * p0[1] * t0[3];
;               v0[2] = v0[2] * t1[0] + sg * p0[2] * t1[1]; v0[3] = v0[3] * t1[2] + sg * p0[3] * t1[3];
;               v1[0] = v1[0] * t2[0] + sg * p1[0] * t2[1]; v1[1] = v1[1] * t2[2] + sg * p1[1] * t2[3];
;               v1[2] = v1[2] * t3[0] + sg * p1[2] * t3[1]; v1[3] = v1[3] * t3[2] + sg * p1[3] * t3[3];
;             }
;             if (c128 >= vend) {
; #pragma unroll
;               for (int e = 0; e < 4; ++e) { v0[e] = silu_f(v0[e]); v1[e] = silu_f(v1[e]); }
;             } else if (c128 < 1024) {
;               v0 = v0 * (0.125f * 1.4426950408889634f); v1 = v1 * (0.125f * 1.4426950408889634f);
;             }
.LBB0_672:
	v_or_b32_e32 v64, s97, v142
	v_mov_b32_e32 v62, s38
	v_mov_b32_e32 v63, s39
	v_cvt_pk_bf16_f32 v58, v66, v67
	v_mad_i64_i32 v[66:67], s[20:21], v64, s92, v[62:63]
	v_cvt_pk_bf16_f32 v59, v68, v69
	v_cvt_pk_bf16_f32 v60, v70, v71
	v_cvt_pk_bf16_f32 v61, v72, v73
	v_lshl_add_u64 v[62:63], v[158:159], 1, v[66:67]
	s_and_b64 vcc, exec, s[12:13]
	global_store_dwordx4 v[62:63], v[58:61], off
	s_cbranch_vccnz .LBB0_674
	s_nop 0
	v_and_b32_e32 v59, 64, v214
	v_xor_b32_e32 v58, 32, v214
	v_add_u32_e32 v59, 64, v59
	v_cmp_lt_i32_e32 vcc, v58, v59
	s_nop 1
	v_cndmask_b32_e32 v58, v214, v58, vcc
	v_lshlrev_b32_e32 v62, 2, v58
	ds_bpermute_b32 v76, v62, v54
	ds_bpermute_b32 v77, v62, v55
	ds_read_b128 v[58:61], v74
	ds_bpermute_b32 v82, v62, v56
	ds_bpermute_b32 v84, v62, v57
	ds_bpermute_b32 v78, v62, v50
	ds_bpermute_b32 v79, v62, v51
	ds_bpermute_b32 v83, v62, v52
	ds_bpermute_b32 v85, v62, v53
	ds_read_b128 v[62:65], v74 offset:16
	ds_read_b128 v[68:71], v74 offset:32
	ds_read_b128 v[72:75], v74 offset:48
	s_waitcnt lgkmcnt(0)
	v_mov_b32_e32 v81, v60
	v_pk_mul_f32 v[76:77], v[152:153], v[76:77]
	v_mov_b32_e32 v60, v59
	v_mov_b32_e32 v80, v58
	v_pk_mul_f32 v[58:59], v[76:77], v[60:61]
	v_mul_f32_e32 v60, v152, v82
	v_mul_f32_e32 v56, v56, v62
	v_mul_f32_e32 v60, v60, v63
	v_mul_f32_e32 v63, v152, v84
	v_mov_b32_e32 v62, v57
	v_pk_mul_f32 v[62:63], v[62:63], v[64:65]
	v_mul_f32_e32 v65, v152, v85
	v_mov_b32_e32 v57, v62
	v_mov_b32_e32 v61, v63
	v_mov_b32_e32 v64, v53
	v_pk_fma_f32 v[54:55], v[54:55], v[80:81], v[58:59]
	v_pk_add_f32 v[56:57], v[56:57], v[60:61]
	v_mov_b32_e32 v59, v70
	v_pk_mul_f32 v[60:61], v[152:153], v[78:79]
	v_mov_b32_e32 v70, v69
	v_mul_f32_e32 v62, v152, v83
	v_pk_mul_f32 v[64:65], v[64:65], v[74:75]
	v_mov_b32_e32 v58, v68
	v_pk_mul_f32 v[60:61], v[60:61], v[70:71]
	v_mul_f32_e32 v52, v52, v72
	v_mul_f32_e32 v62, v62, v73
	v_mov_b32_e32 v53, v64
	v_mov_b32_e32 v63, v65
	v_pk_fma_f32 v[50:51], v[50:51], v[58:59], v[60:61]
	v_pk_add_f32 v[52:53], v[52:53], v[62:63]
.LBB0_674:
	s_and_b64 vcc, exec, s[16:17]
	s_mov_b64 s[70:71], -1
	s_cbranch_vccnz .LBB0_678
	v_mov_b32_e32 v60, v56
	v_mov_b32_e32 v61, v57
	v_mov_b32_e32 v64, v52
	v_mov_b32_e32 v65, v53
	s_cmpk_gt_i32 s1, 0x3ff
	v_mov_b32_e32 v58, v54
	v_mov_b32_e32 v59, v55
	v_mov_b32_e32 v62, v50
	v_mov_b32_e32 v63, v51
	s_cbranch_scc1 .LBB0_677
	v_pk_mul_f32 v[60:61], v[56:57], s[94:95] op_sel_hi:[1,0]
	v_pk_mul_f32 v[58:59], v[54:55], s[94:95] op_sel_hi:[1,0]
	v_pk_mul_f32 v[64:65], v[52:53], s[94:95] op_sel_hi:[1,0]
	v_pk_mul_f32 v[62:63], v[50:51], s[94:95] op_sel_hi:[1,0]

; DI float silu_f(float x) { return x * __builtin_amdgcn_rcpf(1.f + __expf(-x)); }
;   DI void operator()(const f32x4 (&acc)[2][2][4][2], const pg8::Unit& un, int wr, int wc, int fr, int fq) const {
;     ...
;             if (c128 >= vend) {
; #pragma unroll
;               for (int e = 0; e < 4; ++e) { v0[e] = silu_f(v0[e]); v1[e] = silu_f(v1[e]); }
;             } else if (c128 < 1024) {
;               v0 = v0 * (0.125f * 1.4426950408889634f); v1 = v1 * (0.125f * 1.4426950408889634f);
;             }
.LBB0_682:
	s_and_b64 vcc, exec, s[14:15]
	s_mov_b64 s[70:71], -1
	s_cbranch_vccnz .LBB0_686
	v_mov_b32_e32 v52, v48
	v_mov_b32_e32 v53, v49
	v_mov_b32_e32 v56, v44
	v_mov_b32_e32 v57, v45
	s_cmp_gt_i32 s86, 3
	v_mov_b32_e32 v50, v46
	v_mov_b32_e32 v51, v47
	v_mov_b32_e32 v54, v42
	v_mov_b32_e32 v55, v43
	s_cbranch_scc1 .LBB0_685
	v_pk_mul_f32 v[52:53], v[48:49], s[94:95] op_sel_hi:[1,0]
	v_pk_mul_f32 v[50:51], v[46:47], s[94:95] op_sel_hi:[1,0]
	v_pk_mul_f32 v[56:57], v[44:45], s[94:95] op_sel_hi:[1,0]
	v_pk_mul_f32 v[54:55], v[42:43], s[94:95] op_sel_hi:[1,0]

; #define LAS3 __attribute__((address_space(3)))
; DI unsigned pk2(float lo, float hi) { f32x2 v = {lo, hi}; return __builtin_bit_cast(unsigned, __builtin_convertvector(v, bf16x2v)); }
; DI float silu_f(float x) { return x * __builtin_amdgcn_rcpf(1.f + __expf(-x)); }
;   DI void operator()(const f32x4 (&acc)[2][2][4][2], const pg8::Unit& un, int wr, int wc, int fr, int fq) const {
;     ...
;         const int row = upm * 256 + ai * 128 + wr * 64 + m * 16 + fr;
; #pragma unroll
;         for (int bj = 0; bj < 2; ++bj) {
;           const int c128 = upn * 256 + bj * 128;
;           const int col0 = c128 + wc * 32 + fq * 8;
;           f32x4 v0 = acc[ai][bj][m][0], v1 = acc[ai][bj][m][1];
;           if (MODE == 2) {
;             u32x4 w; w[0] = pk2(v0[0], v0[1]); w[1] = pk2(v0[2], v0[3]); w[2] = pk2(v1[0], v1[1]); w[3] = pk2(v1[2], v1[3]);
;             *(u32x4*)(u + (size_t)row * 1024 + col0) = w;
;           } else {
;             if (isA && !isctx && c128 < kend) {
;               f32x4 p0, p1;
; #pragma unroll
;               for (int e = 0; e < 4; ++e) { p0[e] = __shfl_xor(v0[e], 32); p1[e] = __shfl_xor(v1[e], 32); }
;               const int sp = row & 2047;
;               const int pos = (wc & 1) ? (sp & 63) : (sp >> 6);
;               LAS3 const float* tb = rope + (pos * 16 + 8 * (fq & 1)) * 2;
;               const f32x4 t0 = *(LAS3 const f32x4*)(tb), t1 = *(LAS3 const f32x4*)(tb + 4), t2 = *(LAS3 const f32x4*)(tb + 8), t3 = *(LAS3 const f32x4*)(tb + 12);
;               const float sg = (fq < 2) ? -1.f : 1.f;
;               v0[0] = v0[0] * t0[0] + sg * p0[0] * t0[1]; v0[1] = v0[1] * t0[2] + sg * p0[1] * t0[3];
;               v0[2] = v0[2] * t1[0] + sg * p0[2] * t1[1]; v0[3] = v0[3] * t1[2] + sg * p0[3] * t1[3];
;               v1[0] = v1[0] * t2[0] + sg * p1[0] * t2[1]; v1[1] = v1[1] * t2[2] + sg * p1[1] * t2[3];
;               v1[2] = v1[2] * t3[0] + sg * p1[2] * t3[1]; v1[3] = v1[3] * t3[2] + sg * p1[3] * t3[3];
;             }
;             if (c128 >= vend) {
; #pragma unroll
;               for (int e = 0; e < 4; ++e) { v0[e] = silu_f(v0[e]); v1[e] = silu_f(v1[e]); }
;             } else if (c128 < 1024) {
;               v0 = v0 * (0.125f * 1.4426950408889634f); v1 = v1 * (0.125f * 1.4426950408889634f);
;             }
.LBB0_688:
	v_or_b32_e32 v48, s97, v161
	v_mov_b32_e32 v46, s38
	v_mov_b32_e32 v47, s39
	v_cvt_pk_bf16_f32 v42, v50, v51
	v_mad_i64_i32 v[50:51], s[20:21], v48, s92, v[46:47]
	v_cvt_pk_bf16_f32 v43, v52, v53
	v_cvt_pk_bf16_f32 v44, v54, v55
	v_cvt_pk_bf16_f32 v45, v56, v57
	v_lshl_add_u64 v[46:47], v[158:159], 1, v[50:51]
	s_and_b64 vcc, exec, s[12:13]
	global_store_dwordx4 v[46:47], v[42:45], off
	s_cbranch_vccnz .LBB0_690
	s_nop 0
	v_and_b32_e32 v43, 64, v214
	v_xor_b32_e32 v42, 32, v214
	v_add_u32_e32 v43, 64, v43
	v_cmp_lt_i32_e32 vcc, v42, v43
	s_nop 1
	v_cndmask_b32_e32 v42, v214, v42, vcc
	v_lshlrev_b32_e32 v46, 2, v42
	ds_bpermute_b32 v60, v46, v38
	ds_bpermute_b32 v61, v46, v39
	ds_read_b128 v[42:45], v58
	ds_bpermute_b32 v66, v46, v40
	ds_bpermute_b32 v68, v46, v41
	ds_bpermute_b32 v62, v46, v34
	ds_bpermute_b32 v63, v46, v35
	ds_bpermute_b32 v67, v46, v36
	ds_bpermute_b32 v69, v46, v37
	ds_read_b128 v[46:49], v58 offset:16
	ds_read_b128 v[52:55], v58 offset:32
	ds_read_b128 v[56:59], v58 offset:48
	s_waitcnt lgkmcnt(0)
	v_mov_b32_e32 v65, v44
	v_pk_mul_f32 v[60:61], v[152:153], v[60:61]
	v_mov_b32_e32 v44, v43
	v_mov_b32_e32 v64, v42
	v_pk_mul_f32 v[42:43], v[60:61], v[44:45]
	v_mul_f32_e32 v44, v152, v66
	v_mul_f32_e32 v40, v40, v46
	v_mul_f32_e32 v44, v44, v47
	v_mul_f32_e32 v47, v152, v68
	v_mov_b32_e32 v46, v41
	v_pk_mul_f32 v[46:47], v[46:47], v[48:49]
	v_mul_f32_e32 v49, v152, v69
	v_mov_b32_e32 v41, v46
	v_mov_b32_e32 v45, v47
	v_mov_b32_e32 v48, v37
	v_pk_fma_f32 v[38:39], v[38:39], v[64:65], v[42:43]
	v_pk_add_f32 v[40:41], v[40:41], v[44:45]
	v_mov_b32_e32 v43, v54
	v_pk_mul_f32 v[44:45], v[152:153], v[62:63]
	v_mov_b32_e32 v54, v53
	v_mul_f32_e32 v46, v152, v67
	v_pk_mul_f32 v[48:49], v[48:49], v[58:59]
	v_mov_b32_e32 v42, v52
	v_pk_mul_f32 v[44:45], v[44:45], v[54:55]
	v_mul_f32_e32 v36, v36, v56
	v_mul_f32_e32 v46, v46, v57
	v_mov_b32_e32 v37, v48
	v_mov_b32_e32 v47, v49
	v_pk_fma_f32 v[34:35], v[34:35], v[42:43], v[44:45]
	v_pk_add_f32 v[36:37], v[36:37], v[46:47]
.LBB0_690:
	s_and_b64 vcc, exec, s[16:17]
	s_mov_b64 s[70:71], -1
	s_cbranch_vccnz .LBB0_694
	v_mov_b32_e32 v44, v40
	v_mov_b32_e32 v45, v41
	v_mov_b32_e32 v48, v36
	v_mov_b32_e32 v49, v37
	s_cmpk_gt_i32 s1, 0x3ff
	v_mov_b32_e32 v42, v38
	v_mov_b32_e32 v43, v39
	v_mov_b32_e32 v46, v34
	v_mov_b32_e32 v47, v35
	s_cbranch_scc1 .LBB0_693
	v_pk_mul_f32 v[44:45], v[40:41], s[94:95] op_sel_hi:[1,0]
	v_pk_mul_f32 v[42:43], v[38:39], s[94:95] op_sel_hi:[1,0]
	v_pk_mul_f32 v[48:49], v[36:37], s[94:95] op_sel_hi:[1,0]
	v_pk_mul_f32 v[46:47], v[34:35], s[94:95] op_sel_hi:[1,0]

; DI float silu_f(float x) { return x * __builtin_amdgcn_rcpf(1.f + __expf(-x)); }
;   DI void operator()(const f32x4 (&acc)[2][2][4][2], const pg8::Unit& un, int wr, int wc, int fr, int fq) const {
;     ...
;             if (c128 >= vend) {
; #pragma unroll
;               for (int e = 0; e < 4; ++e) { v0[e] = silu_f(v0[e]); v1[e] = silu_f(v1[e]); }
;             } else if (c128 < 1024) {
;               v0 = v0 * (0.125f * 1.4426950408889634f); v1 = v1 * (0.125f * 1.4426950408889634f);
;             }
.LBB0_698:
	s_and_b64 vcc, exec, s[14:15]
	s_mov_b64 s[70:71], -1
	s_cbranch_vccnz .LBB0_702
	v_mov_b32_e32 v36, v32
	v_mov_b32_e32 v37, v33
	v_mov_b32_e32 v40, v28
	v_mov_b32_e32 v41, v29
	s_cmp_gt_i32 s86, 3
	v_mov_b32_e32 v34, v30
	v_mov_b32_e32 v35, v31
	v_mov_b32_e32 v38, v26
	v_mov_b32_e32 v39, v27
	s_cbranch_scc1 .LBB0_701
	v_pk_mul_f32 v[36:37], v[32:33], s[94:95] op_sel_hi:[1,0]
	v_pk_mul_f32 v[34:35], v[30:31], s[94:95] op_sel_hi:[1,0]
	v_pk_mul_f32 v[40:41], v[28:29], s[94:95] op_sel_hi:[1,0]
	v_pk_mul_f32 v[38:39], v[26:27], s[94:95] op_sel_hi:[1,0]

; #define LAS3 __attribute__((address_space(3)))
; DI unsigned pk2(float lo, float hi) { f32x2 v = {lo, hi}; return __builtin_bit_cast(unsigned, __builtin_convertvector(v, bf16x2v)); }
; DI float silu_f(float x) { return x * __builtin_amdgcn_rcpf(1.f + __expf(-x)); }
;   DI void operator()(const f32x4 (&acc)[2][2][4][2], const pg8::Unit& un, int wr, int wc, int fr, int fq) const {
;     ...
;         const int row = upm * 256 + ai * 128 + wr * 64 + m * 16 + fr;
; #pragma unroll
;         for (int bj = 0; bj < 2; ++bj) {
;           const int c128 = upn * 256 + bj * 128;
;           const int col0 = c128 + wc * 32 + fq * 8;
;           f32x4 v0 = acc[ai][bj][m][0], v1 = acc[ai][bj][m][1];
;           if (MODE == 2) {
;             u32x4 w; w[0] = pk2(v0[0], v0[1]); w[1] = pk2(v0[2], v0[3]); w[2] = pk2(v1[0], v1[1]); w[3] = pk2(v1[2], v1[3]);
;             *(u32x4*)(u + (size_t)row * 1024 + col0) = w;
;           } else {
;             if (isA && !isctx && c128 < kend) {
;               f32x4 p0, p1;
; #pragma unroll
;               for (int e = 0; e < 4; ++e) { p0[e] = __shfl_xor(v0[e], 32); p1[e] = __shfl_xor(v1[e], 32); }
;               const int sp = row & 2047;
;               const int pos = (wc & 1) ? (sp & 63) : (sp >> 6);
;               LAS3 const float* tb = rope + (pos * 16 + 8 * (fq & 1)) * 2;
;               const f32x4 t0 = *(LAS3 const f32x4*)(tb), t1 = *(LAS3 const f32x4*)(tb + 4), t2 = *(LAS3 const f32x4*)(tb + 8), t3 = *(LAS3 const f32x4*)(tb + 12);
;               const float sg = (fq < 2) ? -1.f : 1.f;
;               v0[0] = v0[0] * t0[0] + sg * p0[0] * t0[1]; v0[1] = v0[1] * t0[2] + sg * p0[1] * t0[3];
;               v0[2] = v0[2] * t1[0] + sg * p0[2] * t1[1]; v0[3] = v0[3] * t1[2] + sg * p0[3] * t1[3];
;               v1[0] = v1[0] * t2[0] + sg * p1[0] * t2[1]; v1[1] = v1[1] * t2[2] + sg * p1[1] * t2[3];
;               v1[2] = v1[2] * t3[0] + sg * p1[2] * t3[1]; v1[3] = v1[3] * t3[2] + sg * p1[3] * t3[3];
;             }
;             if (c128 >= vend) {
; #pragma unroll
;               for (int e = 0; e < 4; ++e) { v0[e] = silu_f(v0[e]); v1[e] = silu_f(v1[e]); }
;             } else if (c128 < 1024) {
;               v0 = v0 * (0.125f * 1.4426950408889634f); v1 = v1 * (0.125f * 1.4426950408889634f);
;             }
.LBB0_704:
	v_or_b32_e32 v32, s97, v162
	v_mov_b32_e32 v30, s38
	v_mov_b32_e32 v31, s39
	v_cvt_pk_bf16_f32 v26, v34, v35
	v_mad_i64_i32 v[34:35], s[20:21], v32, s92, v[30:31]
	v_cvt_pk_bf16_f32 v27, v36, v37
	v_cvt_pk_bf16_f32 v28, v38, v39
	v_cvt_pk_bf16_f32 v29, v40, v41
	v_lshl_add_u64 v[30:31], v[158:159], 1, v[34:35]
	s_and_b64 vcc, exec, s[12:13]
	global_store_dwordx4 v[30:31], v[26:29], off
	s_cbranch_vccnz .LBB0_706
	s_nop 0
	v_and_b32_e32 v27, 64, v214
	v_xor_b32_e32 v26, 32, v214
	v_add_u32_e32 v27, 64, v27
	v_cmp_lt_i32_e32 vcc, v26, v27
	s_nop 1
	v_cndmask_b32_e32 v26, v214, v26, vcc
	v_lshlrev_b32_e32 v30, 2, v26
	ds_bpermute_b32 v44, v30, v22
	ds_bpermute_b32 v45, v30, v23
	ds_read_b128 v[26:29], v42
	ds_bpermute_b32 v50, v30, v24
	ds_bpermute_b32 v52, v30, v25
	ds_bpermute_b32 v46, v30, v18
	ds_bpermute_b32 v47, v30, v19
	ds_bpermute_b32 v51, v30, v20
	ds_bpermute_b32 v53, v30, v21
	ds_read_b128 v[30:33], v42 offset:16
	ds_read_b128 v[36:39], v42 offset:32
	ds_read_b128 v[40:43], v42 offset:48
	s_waitcnt lgkmcnt(0)
	v_mov_b32_e32 v49, v28
	v_pk_mul_f32 v[44:45], v[152:153], v[44:45]
	v_mov_b32_e32 v28, v27
	v_mov_b32_e32 v48, v26
	v_pk_mul_f32 v[26:27], v[44:45], v[28:29]
	v_mul_f32_e32 v28, v152, v50
	v_mul_f32_e32 v24, v24, v30
	v_mul_f32_e32 v28, v28, v31
	v_mul_f32_e32 v31, v152, v52
	v_mov_b32_e32 v30, v25
	v_pk_mul_f32 v[30:31], v[30:31], v[32:33]
	v_mul_f32_e32 v33, v152, v53
	v_mov_b32_e32 v25, v30
	v_mov_b32_e32 v29, v31
	v_mov_b32_e32 v32, v21
	v_pk_fma_f32 v[22:23], v[22:23], v[48:49], v[26:27]
	v_pk_add_f32 v[24:25], v[24:25], v[28:29]
	v_mov_b32_e32 v27, v38
	v_pk_mul_f32 v[28:29], v[152:153], v[46:47]
	v_mov_b32_e32 v38, v37
	v_mul_f32_e32 v30, v152, v51
	v_pk_mul_f32 v[32:33], v[32:33], v[42:43]
	v_mov_b32_e32 v26, v36
	v_pk_mul_f32 v[28:29], v[28:29], v[38:39]
	v_mul_f32_e32 v20, v20, v40
	v_mul_f32_e32 v30, v30, v41
	v_mov_b32_e32 v21, v32
	v_mov_b32_e32 v31, v33
	v_pk_fma_f32 v[18:19], v[18:19], v[26:27], v[28:29]
	v_pk_add_f32 v[20:21], v[20:21], v[30:31]
.LBB0_706:
	s_and_b64 vcc, exec, s[16:17]
	s_mov_b64 s[70:71], -1
	s_cbranch_vccnz .LBB0_710
	v_mov_b32_e32 v28, v24
	v_mov_b32_e32 v29, v25
	v_mov_b32_e32 v32, v20
	v_mov_b32_e32 v33, v21
	s_cmpk_gt_i32 s1, 0x3ff
	v_mov_b32_e32 v26, v22
	v_mov_b32_e32 v27, v23
	v_mov_b32_e32 v30, v18
	v_mov_b32_e32 v31, v19
	s_cbranch_scc1 .LBB0_709
	v_pk_mul_f32 v[28:29], v[24:25], s[94:95] op_sel_hi:[1,0]
	v_pk_mul_f32 v[26:27], v[22:23], s[94:95] op_sel_hi:[1,0]
	v_pk_mul_f32 v[32:33], v[20:21], s[94:95] op_sel_hi:[1,0]
	v_pk_mul_f32 v[30:31], v[18:19], s[94:95] op_sel_hi:[1,0]

; DI float silu_f(float x) { return x * __builtin_amdgcn_rcpf(1.f + __expf(-x)); }
;   DI void operator()(const f32x4 (&acc)[2][2][4][2], const pg8::Unit& un, int wr, int wc, int fr, int fq) const {
;     ...
;             if (c128 >= vend) {
; #pragma unroll
;               for (int e = 0; e < 4; ++e) { v0[e] = silu_f(v0[e]); v1[e] = silu_f(v1[e]); }
;             } else if (c128 < 1024) {
;               v0 = v0 * (0.125f * 1.4426950408889634f); v1 = v1 * (0.125f * 1.4426950408889634f);
;             }
.LBB0_714:
	s_and_b64 vcc, exec, s[14:15]
	s_mov_b64 s[10:11], -1
	s_cbranch_vccnz .LBB0_718
	v_mov_b32_e32 v20, v16
	v_mov_b32_e32 v21, v17
	v_mov_b32_e32 v24, v12
	v_mov_b32_e32 v25, v13
	s_cmp_gt_i32 s86, 3
	v_mov_b32_e32 v18, v14
	v_mov_b32_e32 v19, v15
	v_mov_b32_e32 v22, v10
	v_mov_b32_e32 v23, v11
	s_cbranch_scc1 .LBB0_717
	v_pk_mul_f32 v[20:21], v[16:17], s[94:95] op_sel_hi:[1,0]
	v_pk_mul_f32 v[18:19], v[14:15], s[94:95] op_sel_hi:[1,0]
	v_pk_mul_f32 v[24:25], v[12:13], s[94:95] op_sel_hi:[1,0]
	v_pk_mul_f32 v[22:23], v[10:11], s[94:95] op_sel_hi:[1,0]

; #define LAS3 __attribute__((address_space(3)))
; DI unsigned pk2(float lo, float hi) { f32x2 v = {lo, hi}; return __builtin_bit_cast(unsigned, __builtin_convertvector(v, bf16x2v)); }
; DI float silu_f(float x) { return x * __builtin_amdgcn_rcpf(1.f + __expf(-x)); }
;   DI void operator()(const f32x4 (&acc)[2][2][4][2], const pg8::Unit& un, int wr, int wc, int fr, int fq) const {
;     ...
;         const int row = upm * 256 + ai * 128 + wr * 64 + m * 16 + fr;
; #pragma unroll
;         for (int bj = 0; bj < 2; ++bj) {
;           const int c128 = upn * 256 + bj * 128;
;           const int col0 = c128 + wc * 32 + fq * 8;
;           f32x4 v0 = acc[ai][bj][m][0], v1 = acc[ai][bj][m][1];
;           if (MODE == 2) {
;             u32x4 w; w[0] = pk2(v0[0], v0[1]); w[1] = pk2(v0[2], v0[3]); w[2] = pk2(v1[0], v1[1]); w[3] = pk2(v1[2], v1[3]);
;             *(u32x4*)(u + (size_t)row * 1024 + col0) = w;
;           } else {
;             if (isA && !isctx && c128 < kend) {
;               f32x4 p0, p1;
; #pragma unroll
;               for (int e = 0; e < 4; ++e) { p0[e] = __shfl_xor(v0[e], 32); p1[e] = __shfl_xor(v1[e], 32); }
;               const int sp = row & 2047;
;               const int pos = (wc & 1) ? (sp & 63) : (sp >> 6);
;               LAS3 const float* tb = rope + (pos * 16 + 8 * (fq & 1)) * 2;
;               const f32x4 t0 = *(LAS3 const f32x4*)(tb), t1 = *(LAS3 const f32x4*)(tb + 4), t2 = *(LAS3 const f32x4*)(tb + 8), t3 = *(LAS3 const f32x4*)(tb + 12);
;               const float sg = (fq < 2) ? -1.f : 1.f;
;               v0[0] = v0[0] * t0[0] + sg * p0[0] * t0[1]; v0[1] = v0[1] * t0[2] + sg * p0[1] * t0[3];
;               v0[2] = v0[2] * t1[0] + sg * p0[2] * t1[1]; v0[3] = v0[3] * t1[2] + sg * p0[3] * t1[3];
;               v1[0] = v1[0] * t2[0] + sg * p1[0] * t2[1]; v1[1] = v1[1] * t2[2] + sg * p1[1] * t2[3];
;               v1[2] = v1[2] * t3[0] + sg * p1[2] * t3[1]; v1[3] = v1[3] * t3[2] + sg * p1[3] * t3[3];
;             }
;             if (c128 >= vend) {
; #pragma unroll
;               for (int e = 0; e < 4; ++e) { v0[e] = silu_f(v0[e]); v1[e] = silu_f(v1[e]); }
;             } else if (c128 < 1024) {
;               v0 = v0 * (0.125f * 1.4426950408889634f); v1 = v1 * (0.125f * 1.4426950408889634f);
;             }
.LBB0_720:
	v_or_b32_e32 v16, s97, v163
	v_mov_b32_e32 v14, s38
	v_mov_b32_e32 v15, s39
	v_cvt_pk_bf16_f32 v10, v18, v19
	v_mad_i64_i32 v[18:19], s[10:11], v16, s92, v[14:15]
	v_cvt_pk_bf16_f32 v11, v20, v21
	v_cvt_pk_bf16_f32 v12, v22, v23
	v_cvt_pk_bf16_f32 v13, v24, v25
	v_lshl_add_u64 v[14:15], v[158:159], 1, v[18:19]
	s_and_b64 vcc, exec, s[12:13]
	global_store_dwordx4 v[14:15], v[10:13], off
	s_cbranch_vccnz .LBB0_722
	s_nop 0
	v_and_b32_e32 v11, 64, v214
	v_xor_b32_e32 v10, 32, v214
	v_add_u32_e32 v11, 64, v11
	v_cmp_lt_i32_e32 vcc, v10, v11
	s_nop 1
	v_cndmask_b32_e32 v10, v214, v10, vcc
	v_lshlrev_b32_e32 v14, 2, v10
	ds_bpermute_b32 v28, v14, v6
	ds_bpermute_b32 v29, v14, v7
	ds_read_b128 v[10:13], v26
	ds_bpermute_b32 v34, v14, v8
	ds_bpermute_b32 v36, v14, v9
	ds_bpermute_b32 v30, v14, v2
	ds_bpermute_b32 v31, v14, v3
	ds_bpermute_b32 v35, v14, v4
	ds_bpermute_b32 v37, v14, v5
	ds_read_b128 v[14:17], v26 offset:16
	ds_read_b128 v[20:23], v26 offset:32
	ds_read_b128 v[24:27], v26 offset:48
	s_waitcnt lgkmcnt(0)
	v_mov_b32_e32 v33, v12
	v_pk_mul_f32 v[28:29], v[152:153], v[28:29]
	v_mov_b32_e32 v12, v11
	v_mov_b32_e32 v32, v10
	v_pk_mul_f32 v[10:11], v[28:29], v[12:13]
	v_mul_f32_e32 v12, v152, v34
	v_mul_f32_e32 v8, v8, v14
	v_mul_f32_e32 v12, v12, v15
	v_mul_f32_e32 v15, v152, v36
	v_mov_b32_e32 v14, v9
	v_pk_mul_f32 v[14:15], v[14:15], v[16:17]
	v_mul_f32_e32 v17, v152, v37
	v_mov_b32_e32 v9, v14
	v_mov_b32_e32 v13, v15
	v_mov_b32_e32 v16, v5
	v_pk_fma_f32 v[6:7], v[6:7], v[32:33], v[10:11]
	v_pk_add_f32 v[8:9], v[8:9], v[12:13]
	v_mov_b32_e32 v11, v22
	v_pk_mul_f32 v[12:13], v[152:153], v[30:31]
	v_mov_b32_e32 v22, v21
	v_mul_f32_e32 v14, v152, v35
	v_pk_mul_f32 v[16:17], v[16:17], v[26:27]
	v_mov_b32_e32 v10, v20
	v_pk_mul_f32 v[12:13], v[12:13], v[22:23]
	v_mul_f32_e32 v4, v4, v24
	v_mul_f32_e32 v14, v14, v25
	v_mov_b32_e32 v5, v16
	v_mov_b32_e32 v15, v17
	v_pk_fma_f32 v[2:3], v[2:3], v[10:11], v[12:13]
	v_pk_add_f32 v[4:5], v[4:5], v[14:15]
.LBB0_722:
	s_movk_i32 s97, 0x104
	s_and_b64 vcc, exec, s[16:17]
	s_mov_b64 s[10:11], -1
	s_cbranch_vccnz .LBB0_726
	v_mov_b32_e32 v12, v8
	v_mov_b32_e32 v13, v9
	v_mov_b32_e32 v16, v4
	v_mov_b32_e32 v17, v5
	s_cmpk_gt_i32 s1, 0x3ff
	v_mov_b32_e32 v10, v6
	v_mov_b32_e32 v11, v7
	v_mov_b32_e32 v14, v2
	v_mov_b32_e32 v15, v3
	s_cbranch_scc1 .LBB0_725
	v_pk_mul_f32 v[12:13], v[8:9], s[94:95] op_sel_hi:[1,0]
	v_pk_mul_f32 v[10:11], v[6:7], s[94:95] op_sel_hi:[1,0]
	v_pk_mul_f32 v[16:17], v[4:5], s[94:95] op_sel_hi:[1,0]
	v_pk_mul_f32 v[14:15], v[2:3], s[94:95] op_sel_hi:[1,0]
